# all eight GEMM K-loops re-phased from 8 to 4 barrier-delimited phases (two 16-MFMA blocks per phase, B1 fragment reads hoisted, vmcnt(8) per phase)
# speedup vs baseline: 1.0202x; 1.0090x over previous
; #define PG8_STAGE(bufoff, gbase) do { _Pragma("unroll") for (int _i = 0; _i < 2; ++_i) \
;         __builtin_amdgcn_global_load_lds((const unsigned*)((const char*)(gbase) + voffA[_i]), (LAS unsigned*)(lds + (bufoff) + ldsw + _i * 8192), 16, 0, 0); } while (0)
; #define PG8_LDA(dst, b, h) do { _Pragma("unroll") for (int m = 0; m < 4; ++m) _Pragma("unroll") for (int k = 0; k < 2; ++k) dst[m][k] = *(const LAS bf16x8*)(lds + PG8_SA(b, h) + aoff + m * 2048 + k * 1024); } while (0)
; #define PG8_LDB(dst, b, h) do { _Pragma("unroll") for (int n = 0; n < 2; ++n) _Pragma("unroll") for (int k = 0; k < 2; ++k) dst[n][k] = *(const LAS bf16x8*)(lds + PG8_SB(b, h) + boff + n * 2048 + k * 1024); } while (0)
; #define PG8_MMA(ai, bj, At, Bt) do { __builtin_amdgcn_s_setprio(1); _Pragma("unroll") for (int m = 0; m < 4; ++m) _Pragma("unroll") for (int n = 0; n < 2; ++n) _Pragma("unroll") for (int k = 0; k < 2; ++k) \
;         acc[ai][bj][m][n] = __builtin_amdgcn_mfma_f32_16x16x32_bf16(Bt[n][k], At[m][k], acc[ai][bj][m][n], 0, 0, 0); __builtin_amdgcn_s_setprio(0); } while (0)
; #define PG8_WAIT_V(n) asm volatile("s_waitcnt vmcnt(" #n ")" ::: "memory")
; #define PG8_WAIT_L(n) asm volatile("s_waitcnt lgkmcnt(" #n ")" ::: "memory")
; #define PG8_BAR __builtin_amdgcn_s_barrier()
; #define PG8_SCHED __builtin_amdgcn_sched_barrier(0)
; template <class Epi>
; DI void gemm_phase(const int TID, const int BID, LAS unsigned char* lds, const Gemm g, const Epi& E) {
;     ...
;             PG8_LDB(B0, 0, 0); PG8_SCHED; PG8_LDA(At, 0, 0); PG8_STAGE(PG8_SA(1, 1), a1 + hstep);
;             PG8_WAIT_L(8); PG8_BAR; PG8_WAIT_L(0); PG8_MMA(0, 0, At, B0); PG8_BAR; PG8_SCHED;
;             PG8_LDB(B1, 0, 1); PG8_STAGE(PG8_SB(0, 0), b2);
;             PG8_BAR; PG8_WAIT_L(0); PG8_MMA(0, 1, At, B1); PG8_BAR;
;             PG8_LDA(At, 0, 1); PG8_STAGE(PG8_SA(0, 0), a2);
;             PG8_BAR; PG8_WAIT_L(0); PG8_MMA(1, 0, At, B0); PG8_BAR; PG8_SCHED;
;             PG8_STAGE(PG8_SB(0, 1), b2 + hstep);
;             PG8_WAIT_V(6); PG8_BAR; PG8_MMA(1, 1, At, B1); PG8_BAR;
.LBB0_137:
	v_add_u32_e32 v140, s19, v246
	ds_read_b128 v[128:131], v140
	ds_read_b128 v[132:135], v140 offset:1024
	ds_read_b128 v[136:139], v140 offset:2048
	ds_read_b128 v[140:143], v140 offset:3072
	s_add_i32 s29, s58, 2
	s_add_u32 s60, s56, 0x80
	s_addc_u32 s59, s57, 0
	s_cmp_eq_u32 vcc_lo, s58
	s_cselect_b32 s58, s54, s60
	s_cselect_b32 s59, s55, s59
	s_cselect_b32 s61, s1, s18
	s_cselect_b32 s60, s0, vcc_hi
	v_lshl_add_u64 v[186:187], s[56:57], 0, v[178:179]
	s_add_i32 m0, s22, 0xc000
	ds_read_b128 v[144:147], v248
	ds_read_b128 v[148:151], v248 offset:1024
	ds_read_b128 v[152:155], v248 offset:2048
	ds_read_b128 v[156:159], v248 offset:3072
	ds_read_b128 v[160:163], v248 offset:4096
	ds_read_b128 v[164:167], v248 offset:5120
	ds_read_b128 v[170:173], v248 offset:6144
	ds_read_b128 v[182:185], v248 offset:7168
	global_load_lds_dwordx4 v[186:187], off
	v_lshl_add_u64 v[186:187], s[56:57], 0, v[180:181]
	s_add_i32 m0, s22, 0xe000
	s_nop 0
	global_load_lds_dwordx4 v[186:187], off
	v_add_u32_e32 v198, s24, v246
	ds_read_b128 v[186:189], v198
	ds_read_b128 v[190:193], v198 offset:1024
	ds_read_b128 v[194:197], v198 offset:2048
	ds_read_b128 v[198:201], v198 offset:3072
	s_waitcnt vmcnt(8)
	s_waitcnt lgkmcnt(0)
	s_barrier
	s_setprio 1
	v_mfma_f32_16x16x32_bf16 v[124:127], v[128:131], v[144:147], v[124:127]
	v_mfma_f32_16x16x32_bf16 v[120:123], v[136:139], v[144:147], v[120:123]
	v_mfma_f32_16x16x32_bf16 v[108:111], v[128:131], v[152:155], v[108:111]
	v_mfma_f32_16x16x32_bf16 v[104:107], v[136:139], v[152:155], v[104:107]
	v_mfma_f32_16x16x32_bf16 v[92:95], v[128:131], v[160:163], v[92:95]
	v_mfma_f32_16x16x32_bf16 v[88:91], v[136:139], v[160:163], v[88:91]
	v_mfma_f32_16x16x32_bf16 v[76:79], v[128:131], v[170:173], v[76:79]
	v_mfma_f32_16x16x32_bf16 v[72:75], v[136:139], v[170:173], v[72:75]
	v_mfma_f32_16x16x32_bf16 v[124:127], v[132:135], v[148:151], v[124:127]
	v_mfma_f32_16x16x32_bf16 v[120:123], v[140:143], v[148:151], v[120:123]
	v_mfma_f32_16x16x32_bf16 v[108:111], v[132:135], v[156:159], v[108:111]
	v_mfma_f32_16x16x32_bf16 v[104:107], v[140:143], v[156:159], v[104:107]
	v_mfma_f32_16x16x32_bf16 v[92:95], v[132:135], v[164:167], v[92:95]
	v_mfma_f32_16x16x32_bf16 v[88:91], v[140:143], v[164:167], v[88:91]
	v_mfma_f32_16x16x32_bf16 v[76:79], v[132:135], v[182:185], v[76:79]
	v_mfma_f32_16x16x32_bf16 v[72:75], v[140:143], v[182:185], v[72:75]
	v_mfma_f32_16x16x32_bf16 v[116:119], v[186:189], v[144:147], v[116:119]
	v_mfma_f32_16x16x32_bf16 v[112:115], v[194:197], v[144:147], v[112:115]
	v_mfma_f32_16x16x32_bf16 v[100:103], v[186:189], v[152:155], v[100:103]
	v_mfma_f32_16x16x32_bf16 v[96:99], v[194:197], v[152:155], v[96:99]
	v_mfma_f32_16x16x32_bf16 v[84:87], v[186:189], v[160:163], v[84:87]
	v_mfma_f32_16x16x32_bf16 v[80:83], v[194:197], v[160:163], v[80:83]
	v_mfma_f32_16x16x32_bf16 v[68:71], v[186:189], v[170:173], v[68:71]
	v_mfma_f32_16x16x32_bf16 v[64:67], v[194:197], v[170:173], v[64:67]
	v_mfma_f32_16x16x32_bf16 v[116:119], v[190:193], v[148:151], v[116:119]
	v_mfma_f32_16x16x32_bf16 v[112:115], v[198:201], v[148:151], v[112:115]
	v_mfma_f32_16x16x32_bf16 v[100:103], v[190:193], v[156:159], v[100:103]
	v_mfma_f32_16x16x32_bf16 v[96:99], v[198:201], v[156:159], v[96:99]
	v_mfma_f32_16x16x32_bf16 v[84:87], v[190:193], v[164:167], v[84:87]
	v_mfma_f32_16x16x32_bf16 v[80:83], v[198:201], v[164:167], v[80:83]
	v_mfma_f32_16x16x32_bf16 v[68:71], v[190:193], v[182:185], v[68:71]
	v_mfma_f32_16x16x32_bf16 v[64:67], v[198:201], v[182:185], v[64:67]
	s_setprio 0
	s_barrier
	s_mov_b32 m0, s20
	v_lshl_add_u64 v[202:203], s[60:61], 0, v[168:169]
	global_load_lds_dwordx4 v[202:203], off
	v_lshl_add_u64 v[204:205], s[60:61], 0, v[176:177]
	s_mov_b32 m0, s21
	s_nop 0
	global_load_lds_dwordx4 v[204:205], off
	s_mov_b32 m0, s22
	v_lshl_add_u64 v[206:207], s[58:59], 0, v[168:169]
	ds_read_b128 v[144:147], v248 offset:16384
	ds_read_b128 v[148:151], v248 offset:17408
	ds_read_b128 v[152:155], v248 offset:18432
	ds_read_b128 v[156:159], v248 offset:19456
	ds_read_b128 v[160:163], v248 offset:20480
	ds_read_b128 v[164:167], v248 offset:21504
	ds_read_b128 v[170:173], v248 offset:22528
	ds_read_b128 v[182:185], v248 offset:23552
	global_load_lds_dwordx4 v[206:207], off
	v_lshl_add_u64 v[208:209], s[58:59], 0, v[176:177]
	s_mov_b32 m0, s23
	s_nop 0
	global_load_lds_dwordx4 v[208:209], off
	s_add_u32 s60, s60, s6
	s_addc_u32 s61, s61, s7
	s_mov_b32 m0, s25
	v_lshl_add_u64 v[210:211], s[60:61], 0, v[168:169]
	global_load_lds_dwordx4 v[210:211], off
	v_lshl_add_u64 v[212:213], s[60:61], 0, v[176:177]
	s_mov_b32 m0, s26
	s_nop 0
	global_load_lds_dwordx4 v[212:213], off
	s_waitcnt vmcnt(8)
	s_waitcnt lgkmcnt(0)
	s_barrier
; #define PG8_STAGE(bufoff, gbase) do { _Pragma("unroll") for (int _i = 0; _i < 2; ++_i) \
;         __builtin_amdgcn_global_load_lds((const unsigned*)((const char*)(gbase) + voffA[_i]), (LAS unsigned*)(lds + (bufoff) + ldsw + _i * 8192), 16, 0, 0); } while (0)
; #define PG8_LDA(dst, b, h) do { _Pragma("unroll") for (int m = 0; m < 4; ++m) _Pragma("unroll") for (int k = 0; k < 2; ++k) dst[m][k] = *(const LAS bf16x8*)(lds + PG8_SA(b, h) + aoff + m * 2048 + k * 1024); } while (0)
; #define PG8_LDB(dst, b, h) do { _Pragma("unroll") for (int n = 0; n < 2; ++n) _Pragma("unroll") for (int k = 0; k < 2; ++k) dst[n][k] = *(const LAS bf16x8*)(lds + PG8_SB(b, h) + boff + n * 2048 + k * 1024); } while (0)
; #define PG8_MMA(ai, bj, At, Bt) do { __builtin_amdgcn_s_setprio(1); _Pragma("unroll") for (int m = 0; m < 4; ++m) _Pragma("unroll") for (int n = 0; n < 2; ++n) _Pragma("unroll") for (int k = 0; k < 2; ++k) \
;         acc[ai][bj][m][n] = __builtin_amdgcn_mfma_f32_16x16x32_bf16(Bt[n][k], At[m][k], acc[ai][bj][m][n], 0, 0, 0); __builtin_amdgcn_s_setprio(0); } while (0)
; #define PG8_WAIT_V(n) asm volatile("s_waitcnt vmcnt(" #n ")" ::: "memory")
; #define PG8_WAIT_L(n) asm volatile("s_waitcnt lgkmcnt(" #n ")" ::: "memory")
; #define PG8_BAR __builtin_amdgcn_s_barrier()
; #define PG8_SCHED __builtin_amdgcn_sched_barrier(0)
; template <class Epi>
; DI void gemm_phase(const int TID, const int BID, LAS unsigned char* lds, const Gemm g, const Epi& E) {
;     ...
;             PG8_BAR; PG8_WAIT_L(0); PG8_MMA(1, 0, At, B0); PG8_BAR; PG8_SCHED;
;             PG8_STAGE(PG8_SB(0, 1), b2 + hstep);
;             PG8_WAIT_V(6); PG8_BAR; PG8_MMA(1, 1, At, B1); PG8_BAR;
;             PG8_LDB(B0, 1, 0); PG8_SCHED; PG8_LDA(At, 1, 0); PG8_STAGE(PG8_SA(0, 1), a2 + hstep);
;             PG8_WAIT_L(8); PG8_BAR; PG8_WAIT_L(0); PG8_MMA(0, 0, At, B0); PG8_BAR; PG8_SCHED;
;             PG8_LDB(B1, 1, 1); PG8_STAGE(PG8_SB(1, 0), b3);
;             PG8_BAR; PG8_WAIT_L(0); PG8_MMA(0, 1, At, B1); PG8_BAR;
	s_setprio 1
	v_mfma_f32_16x16x32_bf16 v[60:63], v[128:131], v[144:147], v[60:63]
	v_mfma_f32_16x16x32_bf16 v[56:59], v[136:139], v[144:147], v[56:59]
	v_mfma_f32_16x16x32_bf16 v[44:47], v[128:131], v[152:155], v[44:47]
	v_mfma_f32_16x16x32_bf16 v[40:43], v[136:139], v[152:155], v[40:43]
	v_mfma_f32_16x16x32_bf16 v[28:31], v[128:131], v[160:163], v[28:31]
	v_mfma_f32_16x16x32_bf16 v[24:27], v[136:139], v[160:163], v[24:27]
	v_mfma_f32_16x16x32_bf16 v[12:15], v[128:131], v[170:173], v[12:15]
	v_mfma_f32_16x16x32_bf16 v[8:11], v[136:139], v[170:173], v[8:11]
	v_mfma_f32_16x16x32_bf16 v[60:63], v[132:135], v[148:151], v[60:63]
	v_mfma_f32_16x16x32_bf16 v[56:59], v[140:143], v[148:151], v[56:59]
	v_mfma_f32_16x16x32_bf16 v[44:47], v[132:135], v[156:159], v[44:47]
	v_mfma_f32_16x16x32_bf16 v[40:43], v[140:143], v[156:159], v[40:43]
	v_mfma_f32_16x16x32_bf16 v[28:31], v[132:135], v[164:167], v[28:31]
	v_mfma_f32_16x16x32_bf16 v[24:27], v[140:143], v[164:167], v[24:27]
	v_mfma_f32_16x16x32_bf16 v[12:15], v[132:135], v[182:185], v[12:15]
	v_mfma_f32_16x16x32_bf16 v[8:11], v[140:143], v[182:185], v[8:11]
	v_mfma_f32_16x16x32_bf16 v[52:55], v[186:189], v[144:147], v[52:55]
	v_mfma_f32_16x16x32_bf16 v[48:51], v[194:197], v[144:147], v[48:51]
	v_mfma_f32_16x16x32_bf16 v[36:39], v[186:189], v[152:155], v[36:39]
	v_mfma_f32_16x16x32_bf16 v[32:35], v[194:197], v[152:155], v[32:35]
	v_mfma_f32_16x16x32_bf16 v[20:23], v[186:189], v[160:163], v[20:23]
	v_mfma_f32_16x16x32_bf16 v[16:19], v[194:197], v[160:163], v[16:19]
	v_mfma_f32_16x16x32_bf16 v[4:7], v[186:189], v[170:173], v[4:7]
	v_mfma_f32_16x16x32_bf16 v[0:3], v[194:197], v[170:173], v[0:3]
	v_mfma_f32_16x16x32_bf16 v[52:55], v[190:193], v[148:151], v[52:55]
	v_mfma_f32_16x16x32_bf16 v[48:51], v[198:201], v[148:151], v[48:51]
	v_mfma_f32_16x16x32_bf16 v[36:39], v[190:193], v[156:159], v[36:39]
	v_mfma_f32_16x16x32_bf16 v[32:35], v[198:201], v[156:159], v[32:35]
	v_mfma_f32_16x16x32_bf16 v[20:23], v[190:193], v[164:167], v[20:23]
	v_mfma_f32_16x16x32_bf16 v[16:19], v[198:201], v[164:167], v[16:19]
	v_mfma_f32_16x16x32_bf16 v[4:7], v[190:193], v[182:185], v[4:7]
	v_mfma_f32_16x16x32_bf16 v[0:3], v[198:201], v[182:185], v[0:3]
	s_setprio 0
	s_barrier
	v_add_u32_e32 v140, s33, v246
	ds_read_b128 v[128:131], v140
	ds_read_b128 v[132:135], v140 offset:1024
	ds_read_b128 v[136:139], v140 offset:2048
	ds_read_b128 v[140:143], v140 offset:3072
	s_add_u32 s58, s58, s6
	s_addc_u32 s59, s59, s7
	s_mov_b32 m0, s27
	v_lshl_add_u64 v[186:187], s[58:59], 0, v[168:169]
	ds_read_b128 v[144:147], v248 offset:32768
	ds_read_b128 v[148:151], v248 offset:33792
	ds_read_b128 v[152:155], v248 offset:34816
	ds_read_b128 v[156:159], v248 offset:35840
	ds_read_b128 v[160:163], v248 offset:36864
	ds_read_b128 v[164:167], v248 offset:37888
	ds_read_b128 v[170:173], v248 offset:38912
	ds_read_b128 v[182:185], v248 offset:39936
	global_load_lds_dwordx4 v[186:187], off
	v_lshl_add_u64 v[186:187], s[58:59], 0, v[176:177]
	s_mov_b32 m0, s28
	s_nop 0
	global_load_lds_dwordx4 v[186:187], off
	v_add_u32_e32 v198, s76, v246
	ds_read_b128 v[186:189], v198
	ds_read_b128 v[190:193], v198 offset:1024
	ds_read_b128 v[194:197], v198 offset:2048
	ds_read_b128 v[198:201], v198 offset:3072
	s_waitcnt vmcnt(8)
	s_waitcnt lgkmcnt(0)
	s_barrier
	s_setprio 1
	v_mfma_f32_16x16x32_bf16 v[124:127], v[128:131], v[144:147], v[124:127]
	v_mfma_f32_16x16x32_bf16 v[120:123], v[136:139], v[144:147], v[120:123]
	v_mfma_f32_16x16x32_bf16 v[108:111], v[128:131], v[152:155], v[108:111]
	v_mfma_f32_16x16x32_bf16 v[104:107], v[136:139], v[152:155], v[104:107]
	v_mfma_f32_16x16x32_bf16 v[92:95], v[128:131], v[160:163], v[92:95]
	v_mfma_f32_16x16x32_bf16 v[88:91], v[136:139], v[160:163], v[88:91]
	v_mfma_f32_16x16x32_bf16 v[76:79], v[128:131], v[170:173], v[76:79]
	v_mfma_f32_16x16x32_bf16 v[72:75], v[136:139], v[170:173], v[72:75]
	v_mfma_f32_16x16x32_bf16 v[124:127], v[132:135], v[148:151], v[124:127]
	v_mfma_f32_16x16x32_bf16 v[120:123], v[140:143], v[148:151], v[120:123]
	v_mfma_f32_16x16x32_bf16 v[108:111], v[132:135], v[156:159], v[108:111]
	v_mfma_f32_16x16x32_bf16 v[104:107], v[140:143], v[156:159], v[104:107]
	v_mfma_f32_16x16x32_bf16 v[92:95], v[132:135], v[164:167], v[92:95]
	v_mfma_f32_16x16x32_bf16 v[88:91], v[140:143], v[164:167], v[88:91]
	v_mfma_f32_16x16x32_bf16 v[76:79], v[132:135], v[182:185], v[76:79]
	v_mfma_f32_16x16x32_bf16 v[72:75], v[140:143], v[182:185], v[72:75]
	v_mfma_f32_16x16x32_bf16 v[116:119], v[186:189], v[144:147], v[116:119]
	v_mfma_f32_16x16x32_bf16 v[112:115], v[194:197], v[144:147], v[112:115]
	v_mfma_f32_16x16x32_bf16 v[100:103], v[186:189], v[152:155], v[100:103]
	v_mfma_f32_16x16x32_bf16 v[96:99], v[194:197], v[152:155], v[96:99]
	v_mfma_f32_16x16x32_bf16 v[84:87], v[186:189], v[160:163], v[84:87]
	v_mfma_f32_16x16x32_bf16 v[80:83], v[194:197], v[160:163], v[80:83]
	v_mfma_f32_16x16x32_bf16 v[68:71], v[186:189], v[170:173], v[68:71]
	v_mfma_f32_16x16x32_bf16 v[64:67], v[194:197], v[170:173], v[64:67]
	v_mfma_f32_16x16x32_bf16 v[116:119], v[190:193], v[148:151], v[116:119]
	v_mfma_f32_16x16x32_bf16 v[112:115], v[198:201], v[148:151], v[112:115]
	v_mfma_f32_16x16x32_bf16 v[100:103], v[190:193], v[156:159], v[100:103]
	v_mfma_f32_16x16x32_bf16 v[96:99], v[198:201], v[156:159], v[96:99]
	v_mfma_f32_16x16x32_bf16 v[84:87], v[190:193], v[164:167], v[84:87]
	v_mfma_f32_16x16x32_bf16 v[80:83], v[198:201], v[164:167], v[80:83]
	v_mfma_f32_16x16x32_bf16 v[68:71], v[190:193], v[182:185], v[68:71]
	v_mfma_f32_16x16x32_bf16 v[64:67], v[198:201], v[182:185], v[64:67]
	s_setprio 0
	s_barrier
; #define PG8_STAGE(bufoff, gbase) do { _Pragma("unroll") for (int _i = 0; _i < 2; ++_i) \
;         __builtin_amdgcn_global_load_lds((const unsigned*)((const char*)(gbase) + voffA[_i]), (LAS unsigned*)(lds + (bufoff) + ldsw + _i * 8192), 16, 0, 0); } while (0)
; #define PG8_LDA(dst, b, h) do { _Pragma("unroll") for (int m = 0; m < 4; ++m) _Pragma("unroll") for (int k = 0; k < 2; ++k) dst[m][k] = *(const LAS bf16x8*)(lds + PG8_SA(b, h) + aoff + m * 2048 + k * 1024); } while (0)
; #define PG8_MMA(ai, bj, At, Bt) do { __builtin_amdgcn_s_setprio(1); _Pragma("unroll") for (int m = 0; m < 4; ++m) _Pragma("unroll") for (int n = 0; n < 2; ++n) _Pragma("unroll") for (int k = 0; k < 2; ++k) \
;         acc[ai][bj][m][n] = __builtin_amdgcn_mfma_f32_16x16x32_bf16(Bt[n][k], At[m][k], acc[ai][bj][m][n], 0, 0, 0); __builtin_amdgcn_s_setprio(0); } while (0)
; #define PG8_WAIT_V(n) asm volatile("s_waitcnt vmcnt(" #n ")" ::: "memory")
; #define PG8_WAIT_L(n) asm volatile("s_waitcnt lgkmcnt(" #n ")" ::: "memory")
; #define PG8_BAR __builtin_amdgcn_s_barrier()
; #define PG8_SCHED __builtin_amdgcn_sched_barrier(0)
; template <class Epi>
; DI void gemm_phase(const int TID, const int BID, LAS unsigned char* lds, const Gemm g, const Epi& E) {
;     ...
;             PG8_LDA(At, 1, 1); PG8_STAGE(PG8_SA(1, 0), a3);
;             PG8_BAR; PG8_WAIT_L(0); PG8_MMA(1, 0, At, B0); PG8_BAR; PG8_SCHED;
;             PG8_STAGE(PG8_SB(1, 1), b3 + hstep);
;             PG8_WAIT_V(6); PG8_BAR; PG8_MMA(1, 1, At, B1); PG8_BAR;
;         }
	s_mov_b32 m0, s64
	v_lshl_add_u64 v[202:203], v[202:203], 0, s[92:93]
	global_load_lds_dwordx4 v[202:203], off
	v_lshl_add_u64 v[202:203], v[204:205], 0, s[92:93]
	s_mov_b32 m0, s65
	s_nop 0
	global_load_lds_dwordx4 v[202:203], off
	s_mov_b32 m0, s66
	v_lshl_add_u64 v[202:203], v[206:207], 0, s[92:93]
	ds_read_b128 v[144:147], v248 offset:49152
	ds_read_b128 v[148:151], v248 offset:50176
	ds_read_b128 v[152:155], v248 offset:51200
	ds_read_b128 v[156:159], v248 offset:52224
	ds_read_b128 v[160:163], v248 offset:53248
	ds_read_b128 v[164:167], v248 offset:54272
	ds_read_b128 v[170:173], v248 offset:55296
	ds_read_b128 v[182:185], v248 offset:56320
	global_load_lds_dwordx4 v[202:203], off
	v_lshl_add_u64 v[202:203], v[208:209], 0, s[92:93]
	s_mov_b32 m0, s67
	s_nop 0
	global_load_lds_dwordx4 v[202:203], off
	s_mov_b32 m0, s77
	v_lshl_add_u64 v[202:203], v[210:211], 0, s[92:93]
	global_load_lds_dwordx4 v[202:203], off
	v_lshl_add_u64 v[202:203], v[212:213], 0, s[92:93]
	s_mov_b32 m0, s80
	s_nop 0
	global_load_lds_dwordx4 v[202:203], off
	s_waitcnt vmcnt(8)
	s_waitcnt lgkmcnt(0)
	s_barrier
	s_setprio 1
	v_mfma_f32_16x16x32_bf16 v[60:63], v[128:131], v[144:147], v[60:63]
	v_mfma_f32_16x16x32_bf16 v[56:59], v[136:139], v[144:147], v[56:59]
	v_mfma_f32_16x16x32_bf16 v[44:47], v[128:131], v[152:155], v[44:47]
	v_mfma_f32_16x16x32_bf16 v[40:43], v[136:139], v[152:155], v[40:43]
	v_mfma_f32_16x16x32_bf16 v[28:31], v[128:131], v[160:163], v[28:31]
	v_mfma_f32_16x16x32_bf16 v[24:27], v[136:139], v[160:163], v[24:27]
	v_mfma_f32_16x16x32_bf16 v[12:15], v[128:131], v[170:173], v[12:15]
	v_mfma_f32_16x16x32_bf16 v[8:11], v[136:139], v[170:173], v[8:11]
	v_mfma_f32_16x16x32_bf16 v[60:63], v[132:135], v[148:151], v[60:63]
	v_mfma_f32_16x16x32_bf16 v[56:59], v[140:143], v[148:151], v[56:59]
	v_mfma_f32_16x16x32_bf16 v[44:47], v[132:135], v[156:159], v[44:47]
	v_mfma_f32_16x16x32_bf16 v[40:43], v[140:143], v[156:159], v[40:43]
	v_mfma_f32_16x16x32_bf16 v[28:31], v[132:135], v[164:167], v[28:31]
	v_mfma_f32_16x16x32_bf16 v[24:27], v[140:143], v[164:167], v[24:27]
	v_mfma_f32_16x16x32_bf16 v[12:15], v[132:135], v[182:185], v[12:15]
	v_mfma_f32_16x16x32_bf16 v[8:11], v[140:143], v[182:185], v[8:11]
	v_mfma_f32_16x16x32_bf16 v[52:55], v[186:189], v[144:147], v[52:55]
	v_mfma_f32_16x16x32_bf16 v[48:51], v[194:197], v[144:147], v[48:51]
	v_mfma_f32_16x16x32_bf16 v[36:39], v[186:189], v[152:155], v[36:39]
	v_mfma_f32_16x16x32_bf16 v[32:35], v[194:197], v[152:155], v[32:35]
	v_mfma_f32_16x16x32_bf16 v[20:23], v[186:189], v[160:163], v[20:23]
	v_mfma_f32_16x16x32_bf16 v[16:19], v[194:197], v[160:163], v[16:19]
	v_mfma_f32_16x16x32_bf16 v[4:7], v[186:189], v[170:173], v[4:7]
	v_mfma_f32_16x16x32_bf16 v[0:3], v[194:197], v[170:173], v[0:3]
	v_mfma_f32_16x16x32_bf16 v[52:55], v[190:193], v[148:151], v[52:55]
	v_mfma_f32_16x16x32_bf16 v[48:51], v[198:201], v[148:151], v[48:51]
	v_mfma_f32_16x16x32_bf16 v[36:39], v[190:193], v[156:159], v[36:39]
	v_mfma_f32_16x16x32_bf16 v[32:35], v[198:201], v[156:159], v[32:35]
	v_mfma_f32_16x16x32_bf16 v[20:23], v[190:193], v[164:167], v[20:23]
	v_mfma_f32_16x16x32_bf16 v[16:19], v[198:201], v[164:167], v[16:19]
	v_mfma_f32_16x16x32_bf16 v[4:7], v[190:193], v[182:185], v[4:7]
	v_mfma_f32_16x16x32_bf16 v[0:3], v[198:201], v[182:185], v[0:3]
	s_setprio 0
	s_add_u32 s56, s56, 0x100
	s_addc_u32 s57, s57, 0
	s_add_u32 vcc_hi, vcc_hi, 0x100
	s_addc_u32 s18, s18, 0
	s_cmp_ge_i32 s29, s5
	s_mov_b32 s58, s29
	s_barrier
	s_cbranch_scc0 .LBB0_137
	s_branch .LBB0_141

; #define PG8_STAGE(bufoff, gbase) do { _Pragma("unroll") for (int _i = 0; _i < 2; ++_i) \
;         __builtin_amdgcn_global_load_lds((const unsigned*)((const char*)(gbase) + voffA[_i]), (LAS unsigned*)(lds + (bufoff) + ldsw + _i * 8192), 16, 0, 0); } while (0)
; #define PG8_LDA(dst, b, h) do { _Pragma("unroll") for (int m = 0; m < 4; ++m) _Pragma("unroll") for (int k = 0; k < 2; ++k) dst[m][k] = *(const LAS bf16x8*)(lds + PG8_SA(b, h) + aoff + m * 2048 + k * 1024); } while (0)
; #define PG8_LDB(dst, b, h) do { _Pragma("unroll") for (int n = 0; n < 2; ++n) _Pragma("unroll") for (int k = 0; k < 2; ++k) dst[n][k] = *(const LAS bf16x8*)(lds + PG8_SB(b, h) + boff + n * 2048 + k * 1024); } while (0)
; #define PG8_MMA(ai, bj, At, Bt) do { __builtin_amdgcn_s_setprio(1); _Pragma("unroll") for (int m = 0; m < 4; ++m) _Pragma("unroll") for (int n = 0; n < 2; ++n) _Pragma("unroll") for (int k = 0; k < 2; ++k) \
;         acc[ai][bj][m][n] = __builtin_amdgcn_mfma_f32_16x16x32_bf16(Bt[n][k], At[m][k], acc[ai][bj][m][n], 0, 0, 0); __builtin_amdgcn_s_setprio(0); } while (0)
; #define PG8_WAIT_V(n) asm volatile("s_waitcnt vmcnt(" #n ")" ::: "memory")
; #define PG8_WAIT_L(n) asm volatile("s_waitcnt lgkmcnt(" #n ")" ::: "memory")
; #define PG8_BAR __builtin_amdgcn_s_barrier()
; #define PG8_SCHED __builtin_amdgcn_sched_barrier(0)
; template <class Epi>
; DI void gemm_phase(const int TID, const int BID, LAS unsigned char* lds, const Gemm g, const Epi& E) {
;     ...
;             PG8_LDB(B0, 0, 0); PG8_SCHED; PG8_LDA(At, 0, 0); PG8_STAGE(PG8_SA(1, 1), a1 + hstep);
;             PG8_WAIT_L(8); PG8_BAR; PG8_WAIT_L(0); PG8_MMA(0, 0, At, B0); PG8_BAR; PG8_SCHED;
;             PG8_LDB(B1, 0, 1); PG8_STAGE(PG8_SB(0, 0), b2);
;             PG8_BAR; PG8_WAIT_L(0); PG8_MMA(0, 1, At, B1); PG8_BAR;
;             PG8_LDA(At, 0, 1); PG8_STAGE(PG8_SA(0, 0), a2);
;             PG8_BAR; PG8_WAIT_L(0); PG8_MMA(1, 0, At, B0); PG8_BAR; PG8_SCHED;
;             PG8_STAGE(PG8_SB(0, 1), b2 + hstep);
;             PG8_WAIT_V(6); PG8_BAR; PG8_MMA(1, 1, At, B1); PG8_BAR;
.LBB0_164:
	v_add_u32_e32 v138, s16, v141
	ds_read_b128 v[134:137], v138
	ds_read_b128 v[144:147], v138 offset:1024
	ds_read_b128 v[148:151], v138 offset:2048
	ds_read_b128 v[152:155], v138 offset:3072
	s_add_i32 s80, s56, 2
	s_add_u32 s58, s54, 0x80
	s_addc_u32 s57, s55, 0
	s_cmp_eq_u32 s62, s56
	s_cselect_b32 s56, s12, s58
	s_cselect_b32 s57, s13, s57
	s_cselect_b32 s59, s53, s77
	s_cselect_b32 s58, s52, s76
	v_lshl_add_u64 v[138:139], s[54:55], 0, v[130:131]
	s_add_i32 m0, s19, 0xc000
	ds_read_b128 v[156:159], v143
	ds_read_b128 v[160:163], v143 offset:1024
	ds_read_b128 v[164:167], v143 offset:2048
	ds_read_b128 v[170:173], v143 offset:3072
	ds_read_b128 v[176:179], v143 offset:4096
	ds_read_b128 v[180:183], v143 offset:5120
	ds_read_b128 v[184:187], v143 offset:6144
	ds_read_b128 v[188:191], v143 offset:7168
	global_load_lds_dwordx4 v[138:139], off
	v_lshl_add_u64 v[138:139], s[54:55], 0, v[132:133]
	s_add_i32 m0, s19, 0xe000
	s_nop 0
	global_load_lds_dwordx4 v[138:139], off
	v_add_u32_e32 v138, s21, v141
	ds_read_b128 v[192:195], v138
	ds_read_b128 v[196:199], v138 offset:1024
	ds_read_b128 v[200:203], v138 offset:2048
	ds_read_b128 v[204:207], v138 offset:3072
	s_waitcnt vmcnt(8)
	s_waitcnt lgkmcnt(0)
	s_barrier
	s_setprio 1
	v_mfma_f32_16x16x32_bf16 v[124:127], v[134:137], v[156:159], v[124:127]
	v_mfma_f32_16x16x32_bf16 v[120:123], v[148:151], v[156:159], v[120:123]
	v_mfma_f32_16x16x32_bf16 v[108:111], v[134:137], v[164:167], v[108:111]
	v_mfma_f32_16x16x32_bf16 v[104:107], v[148:151], v[164:167], v[104:107]
	v_mfma_f32_16x16x32_bf16 v[92:95], v[134:137], v[176:179], v[92:95]
	v_mfma_f32_16x16x32_bf16 v[88:91], v[148:151], v[176:179], v[88:91]
	v_mfma_f32_16x16x32_bf16 v[76:79], v[134:137], v[184:187], v[76:79]
	v_mfma_f32_16x16x32_bf16 v[72:75], v[148:151], v[184:187], v[72:75]
	v_mfma_f32_16x16x32_bf16 v[124:127], v[144:147], v[160:163], v[124:127]
	v_mfma_f32_16x16x32_bf16 v[120:123], v[152:155], v[160:163], v[120:123]
	v_mfma_f32_16x16x32_bf16 v[108:111], v[144:147], v[170:173], v[108:111]
	v_mfma_f32_16x16x32_bf16 v[104:107], v[152:155], v[170:173], v[104:107]
	v_mfma_f32_16x16x32_bf16 v[92:95], v[144:147], v[180:183], v[92:95]
	v_mfma_f32_16x16x32_bf16 v[88:91], v[152:155], v[180:183], v[88:91]
	v_mfma_f32_16x16x32_bf16 v[76:79], v[144:147], v[188:191], v[76:79]
	v_mfma_f32_16x16x32_bf16 v[72:75], v[152:155], v[188:191], v[72:75]
	v_mfma_f32_16x16x32_bf16 v[116:119], v[192:195], v[156:159], v[116:119]
	v_mfma_f32_16x16x32_bf16 v[112:115], v[200:203], v[156:159], v[112:115]
	v_mfma_f32_16x16x32_bf16 v[100:103], v[192:195], v[164:167], v[100:103]
	v_mfma_f32_16x16x32_bf16 v[96:99], v[200:203], v[164:167], v[96:99]
	v_mfma_f32_16x16x32_bf16 v[84:87], v[192:195], v[176:179], v[84:87]
	v_mfma_f32_16x16x32_bf16 v[80:83], v[200:203], v[176:179], v[80:83]
	v_mfma_f32_16x16x32_bf16 v[68:71], v[192:195], v[184:187], v[68:71]
	v_mfma_f32_16x16x32_bf16 v[64:67], v[200:203], v[184:187], v[64:67]
	v_mfma_f32_16x16x32_bf16 v[116:119], v[196:199], v[160:163], v[116:119]
	v_mfma_f32_16x16x32_bf16 v[112:115], v[204:207], v[160:163], v[112:115]
	v_mfma_f32_16x16x32_bf16 v[100:103], v[196:199], v[170:173], v[100:103]
	v_mfma_f32_16x16x32_bf16 v[96:99], v[204:207], v[170:173], v[96:99]
	v_mfma_f32_16x16x32_bf16 v[84:87], v[196:199], v[180:183], v[84:87]
	v_mfma_f32_16x16x32_bf16 v[80:83], v[204:207], v[180:183], v[80:83]
	v_mfma_f32_16x16x32_bf16 v[68:71], v[196:199], v[188:191], v[68:71]
	v_mfma_f32_16x16x32_bf16 v[64:67], v[204:207], v[188:191], v[64:67]
	s_setprio 0
	s_barrier
	s_mov_b32 m0, s17
	v_lshl_add_u64 v[138:139], s[58:59], 0, v[168:169]
	global_load_lds_dwordx4 v[138:139], off
	v_lshl_add_u64 v[208:209], s[58:59], 0, v[128:129]
	s_mov_b32 m0, s18
	s_nop 0
	global_load_lds_dwordx4 v[208:209], off
	s_mov_b32 m0, s19
	v_lshl_add_u64 v[210:211], s[56:57], 0, v[168:169]
	ds_read_b128 v[156:159], v143 offset:16384
	ds_read_b128 v[160:163], v143 offset:17408
	ds_read_b128 v[164:167], v143 offset:18432
	ds_read_b128 v[170:173], v143 offset:19456
	ds_read_b128 v[176:179], v143 offset:20480
	ds_read_b128 v[180:183], v143 offset:21504
	ds_read_b128 v[184:187], v143 offset:22528
	ds_read_b128 v[188:191], v143 offset:23552
	global_load_lds_dwordx4 v[210:211], off
	v_lshl_add_u64 v[212:213], s[56:57], 0, v[128:129]
	s_mov_b32 m0, s20
	s_nop 0
	global_load_lds_dwordx4 v[212:213], off
	s_add_u32 s58, s58, s0
	s_addc_u32 s59, s59, s1
	s_mov_b32 m0, s22
	v_lshl_add_u64 v[214:215], s[58:59], 0, v[168:169]
	global_load_lds_dwordx4 v[214:215], off
	v_lshl_add_u64 v[216:217], s[58:59], 0, v[128:129]
	s_mov_b32 m0, s23
	s_nop 0
	global_load_lds_dwordx4 v[216:217], off
	s_waitcnt vmcnt(8)
	s_waitcnt lgkmcnt(0)
	s_barrier
; #define PG8_STAGE(bufoff, gbase) do { _Pragma("unroll") for (int _i = 0; _i < 2; ++_i) \
;         __builtin_amdgcn_global_load_lds((const unsigned*)((const char*)(gbase) + voffA[_i]), (LAS unsigned*)(lds + (bufoff) + ldsw + _i * 8192), 16, 0, 0); } while (0)
; #define PG8_LDA(dst, b, h) do { _Pragma("unroll") for (int m = 0; m < 4; ++m) _Pragma("unroll") for (int k = 0; k < 2; ++k) dst[m][k] = *(const LAS bf16x8*)(lds + PG8_SA(b, h) + aoff + m * 2048 + k * 1024); } while (0)
; #define PG8_LDB(dst, b, h) do { _Pragma("unroll") for (int n = 0; n < 2; ++n) _Pragma("unroll") for (int k = 0; k < 2; ++k) dst[n][k] = *(const LAS bf16x8*)(lds + PG8_SB(b, h) + boff + n * 2048 + k * 1024); } while (0)
; #define PG8_MMA(ai, bj, At, Bt) do { __builtin_amdgcn_s_setprio(1); _Pragma("unroll") for (int m = 0; m < 4; ++m) _Pragma("unroll") for (int n = 0; n < 2; ++n) _Pragma("unroll") for (int k = 0; k < 2; ++k) \
;         acc[ai][bj][m][n] = __builtin_amdgcn_mfma_f32_16x16x32_bf16(Bt[n][k], At[m][k], acc[ai][bj][m][n], 0, 0, 0); __builtin_amdgcn_s_setprio(0); } while (0)
; #define PG8_WAIT_V(n) asm volatile("s_waitcnt vmcnt(" #n ")" ::: "memory")
; #define PG8_WAIT_L(n) asm volatile("s_waitcnt lgkmcnt(" #n ")" ::: "memory")
; #define PG8_BAR __builtin_amdgcn_s_barrier()
; #define PG8_SCHED __builtin_amdgcn_sched_barrier(0)
; template <class Epi>
; DI void gemm_phase(const int TID, const int BID, LAS unsigned char* lds, const Gemm g, const Epi& E) {
;     ...
;             PG8_BAR; PG8_WAIT_L(0); PG8_MMA(1, 0, At, B0); PG8_BAR; PG8_SCHED;
;             PG8_STAGE(PG8_SB(0, 1), b2 + hstep);
;             PG8_WAIT_V(6); PG8_BAR; PG8_MMA(1, 1, At, B1); PG8_BAR;
;             PG8_LDB(B0, 1, 0); PG8_SCHED; PG8_LDA(At, 1, 0); PG8_STAGE(PG8_SA(0, 1), a2 + hstep);
;             PG8_WAIT_L(8); PG8_BAR; PG8_WAIT_L(0); PG8_MMA(0, 0, At, B0); PG8_BAR; PG8_SCHED;
;             PG8_LDB(B1, 1, 1); PG8_STAGE(PG8_SB(1, 0), b3);
;             PG8_BAR; PG8_WAIT_L(0); PG8_MMA(0, 1, At, B1); PG8_BAR;
	s_setprio 1
	v_mfma_f32_16x16x32_bf16 v[60:63], v[134:137], v[156:159], v[60:63]
	v_mfma_f32_16x16x32_bf16 v[56:59], v[148:151], v[156:159], v[56:59]
	v_mfma_f32_16x16x32_bf16 v[44:47], v[134:137], v[164:167], v[44:47]
	v_mfma_f32_16x16x32_bf16 v[40:43], v[148:151], v[164:167], v[40:43]
	v_mfma_f32_16x16x32_bf16 v[28:31], v[134:137], v[176:179], v[28:31]
	v_mfma_f32_16x16x32_bf16 v[24:27], v[148:151], v[176:179], v[24:27]
	v_mfma_f32_16x16x32_bf16 v[12:15], v[134:137], v[184:187], v[12:15]
	v_mfma_f32_16x16x32_bf16 v[8:11], v[148:151], v[184:187], v[8:11]
	v_mfma_f32_16x16x32_bf16 v[60:63], v[144:147], v[160:163], v[60:63]
	v_mfma_f32_16x16x32_bf16 v[56:59], v[152:155], v[160:163], v[56:59]
	v_mfma_f32_16x16x32_bf16 v[44:47], v[144:147], v[170:173], v[44:47]
	v_mfma_f32_16x16x32_bf16 v[40:43], v[152:155], v[170:173], v[40:43]
	v_mfma_f32_16x16x32_bf16 v[28:31], v[144:147], v[180:183], v[28:31]
	v_mfma_f32_16x16x32_bf16 v[24:27], v[152:155], v[180:183], v[24:27]
	v_mfma_f32_16x16x32_bf16 v[12:15], v[144:147], v[188:191], v[12:15]
	v_mfma_f32_16x16x32_bf16 v[8:11], v[152:155], v[188:191], v[8:11]
	v_mfma_f32_16x16x32_bf16 v[52:55], v[192:195], v[156:159], v[52:55]
	v_mfma_f32_16x16x32_bf16 v[48:51], v[200:203], v[156:159], v[48:51]
	v_mfma_f32_16x16x32_bf16 v[36:39], v[192:195], v[164:167], v[36:39]
	v_mfma_f32_16x16x32_bf16 v[32:35], v[200:203], v[164:167], v[32:35]
	v_mfma_f32_16x16x32_bf16 v[20:23], v[192:195], v[176:179], v[20:23]
	v_mfma_f32_16x16x32_bf16 v[16:19], v[200:203], v[176:179], v[16:19]
	v_mfma_f32_16x16x32_bf16 v[4:7], v[192:195], v[184:187], v[4:7]
	v_mfma_f32_16x16x32_bf16 v[0:3], v[200:203], v[184:187], v[0:3]
	v_mfma_f32_16x16x32_bf16 v[52:55], v[196:199], v[160:163], v[52:55]
	v_mfma_f32_16x16x32_bf16 v[48:51], v[204:207], v[160:163], v[48:51]
	v_mfma_f32_16x16x32_bf16 v[36:39], v[196:199], v[170:173], v[36:39]
	v_mfma_f32_16x16x32_bf16 v[32:35], v[204:207], v[170:173], v[32:35]
	v_mfma_f32_16x16x32_bf16 v[20:23], v[196:199], v[180:183], v[20:23]
	v_mfma_f32_16x16x32_bf16 v[16:19], v[204:207], v[180:183], v[16:19]
	v_mfma_f32_16x16x32_bf16 v[4:7], v[196:199], v[188:191], v[4:7]
	v_mfma_f32_16x16x32_bf16 v[0:3], v[204:207], v[188:191], v[0:3]
	s_setprio 0
	s_barrier
	v_add_u32_e32 v152, s27, v141
	ds_read_b128 v[134:137], v152
	ds_read_b128 v[144:147], v152 offset:1024
	ds_read_b128 v[148:151], v152 offset:2048
	ds_read_b128 v[152:155], v152 offset:3072
	s_add_u32 s56, s56, s0
	s_addc_u32 s57, s57, s1
	s_mov_b32 m0, s24
	v_lshl_add_u64 v[192:193], s[56:57], 0, v[168:169]
	ds_read_b128 v[156:159], v143 offset:32768
	ds_read_b128 v[160:163], v143 offset:33792
	ds_read_b128 v[164:167], v143 offset:34816
	ds_read_b128 v[170:173], v143 offset:35840
	ds_read_b128 v[176:179], v143 offset:36864
	ds_read_b128 v[180:183], v143 offset:37888
	ds_read_b128 v[184:187], v143 offset:38912
	ds_read_b128 v[188:191], v143 offset:39936
	global_load_lds_dwordx4 v[192:193], off
	v_lshl_add_u64 v[192:193], s[56:57], 0, v[128:129]
	s_mov_b32 m0, s25
	s_nop 0
	global_load_lds_dwordx4 v[192:193], off
	v_add_u32_e32 v175, s33, v141
	ds_read_b128 v[192:195], v175
	ds_read_b128 v[196:199], v175 offset:1024
	ds_read_b128 v[200:203], v175 offset:2048
	ds_read_b128 v[204:207], v175 offset:3072
	s_waitcnt vmcnt(8)
	s_waitcnt lgkmcnt(0)
	s_barrier
	s_setprio 1
	v_mfma_f32_16x16x32_bf16 v[124:127], v[134:137], v[156:159], v[124:127]
	v_mfma_f32_16x16x32_bf16 v[120:123], v[148:151], v[156:159], v[120:123]
	v_mfma_f32_16x16x32_bf16 v[108:111], v[134:137], v[164:167], v[108:111]
	v_mfma_f32_16x16x32_bf16 v[104:107], v[148:151], v[164:167], v[104:107]
	v_mfma_f32_16x16x32_bf16 v[92:95], v[134:137], v[176:179], v[92:95]
	v_mfma_f32_16x16x32_bf16 v[88:91], v[148:151], v[176:179], v[88:91]
	v_mfma_f32_16x16x32_bf16 v[76:79], v[134:137], v[184:187], v[76:79]
	v_mfma_f32_16x16x32_bf16 v[72:75], v[148:151], v[184:187], v[72:75]
	v_mfma_f32_16x16x32_bf16 v[124:127], v[144:147], v[160:163], v[124:127]
	v_mfma_f32_16x16x32_bf16 v[120:123], v[152:155], v[160:163], v[120:123]
	v_mfma_f32_16x16x32_bf16 v[108:111], v[144:147], v[170:173], v[108:111]
	v_mfma_f32_16x16x32_bf16 v[104:107], v[152:155], v[170:173], v[104:107]
	v_mfma_f32_16x16x32_bf16 v[92:95], v[144:147], v[180:183], v[92:95]
	v_mfma_f32_16x16x32_bf16 v[88:91], v[152:155], v[180:183], v[88:91]
	v_mfma_f32_16x16x32_bf16 v[76:79], v[144:147], v[188:191], v[76:79]
	v_mfma_f32_16x16x32_bf16 v[72:75], v[152:155], v[188:191], v[72:75]
	v_mfma_f32_16x16x32_bf16 v[116:119], v[192:195], v[156:159], v[116:119]
	v_mfma_f32_16x16x32_bf16 v[112:115], v[200:203], v[156:159], v[112:115]
	v_mfma_f32_16x16x32_bf16 v[100:103], v[192:195], v[164:167], v[100:103]
	v_mfma_f32_16x16x32_bf16 v[96:99], v[200:203], v[164:167], v[96:99]
	v_mfma_f32_16x16x32_bf16 v[84:87], v[192:195], v[176:179], v[84:87]
	v_mfma_f32_16x16x32_bf16 v[80:83], v[200:203], v[176:179], v[80:83]
	v_mfma_f32_16x16x32_bf16 v[68:71], v[192:195], v[184:187], v[68:71]
	v_mfma_f32_16x16x32_bf16 v[64:67], v[200:203], v[184:187], v[64:67]
	v_mfma_f32_16x16x32_bf16 v[116:119], v[196:199], v[160:163], v[116:119]
	v_mfma_f32_16x16x32_bf16 v[112:115], v[204:207], v[160:163], v[112:115]
	v_mfma_f32_16x16x32_bf16 v[100:103], v[196:199], v[170:173], v[100:103]
	v_mfma_f32_16x16x32_bf16 v[96:99], v[204:207], v[170:173], v[96:99]
	v_mfma_f32_16x16x32_bf16 v[84:87], v[196:199], v[180:183], v[84:87]
	v_mfma_f32_16x16x32_bf16 v[80:83], v[204:207], v[180:183], v[80:83]
	v_mfma_f32_16x16x32_bf16 v[68:71], v[196:199], v[188:191], v[68:71]
	v_mfma_f32_16x16x32_bf16 v[64:67], v[204:207], v[188:191], v[64:67]
	s_setprio 0
	s_barrier
; #define PG8_STAGE(bufoff, gbase) do { _Pragma("unroll") for (int _i = 0; _i < 2; ++_i) \
;         __builtin_amdgcn_global_load_lds((const unsigned*)((const char*)(gbase) + voffA[_i]), (LAS unsigned*)(lds + (bufoff) + ldsw + _i * 8192), 16, 0, 0); } while (0)
; #define PG8_LDA(dst, b, h) do { _Pragma("unroll") for (int m = 0; m < 4; ++m) _Pragma("unroll") for (int k = 0; k < 2; ++k) dst[m][k] = *(const LAS bf16x8*)(lds + PG8_SA(b, h) + aoff + m * 2048 + k * 1024); } while (0)
; #define PG8_MMA(ai, bj, At, Bt) do { __builtin_amdgcn_s_setprio(1); _Pragma("unroll") for (int m = 0; m < 4; ++m) _Pragma("unroll") for (int n = 0; n < 2; ++n) _Pragma("unroll") for (int k = 0; k < 2; ++k) \
;         acc[ai][bj][m][n] = __builtin_amdgcn_mfma_f32_16x16x32_bf16(Bt[n][k], At[m][k], acc[ai][bj][m][n], 0, 0, 0); __builtin_amdgcn_s_setprio(0); } while (0)
; #define PG8_WAIT_V(n) asm volatile("s_waitcnt vmcnt(" #n ")" ::: "memory")
; #define PG8_WAIT_L(n) asm volatile("s_waitcnt lgkmcnt(" #n ")" ::: "memory")
; #define PG8_BAR __builtin_amdgcn_s_barrier()
; #define PG8_SCHED __builtin_amdgcn_sched_barrier(0)
; template <class Epi>
; DI void gemm_phase(const int TID, const int BID, LAS unsigned char* lds, const Gemm g, const Epi& E) {
;     ...
;             PG8_LDA(At, 1, 1); PG8_STAGE(PG8_SA(1, 0), a3);
;             PG8_BAR; PG8_WAIT_L(0); PG8_MMA(1, 0, At, B0); PG8_BAR; PG8_SCHED;
;             PG8_STAGE(PG8_SB(1, 1), b3 + hstep);
;             PG8_WAIT_V(6); PG8_BAR; PG8_MMA(1, 1, At, B1); PG8_BAR;
;         }
	s_mov_b32 m0, s28
	v_lshl_add_u64 v[138:139], v[138:139], 0, s[92:93]
	global_load_lds_dwordx4 v[138:139], off
	v_lshl_add_u64 v[138:139], v[208:209], 0, s[92:93]
	s_mov_b32 m0, s29
	s_nop 0
	global_load_lds_dwordx4 v[138:139], off
	s_mov_b32 m0, s30
	v_lshl_add_u64 v[138:139], v[210:211], 0, s[92:93]
	ds_read_b128 v[156:159], v143 offset:49152
	ds_read_b128 v[160:163], v143 offset:50176
	ds_read_b128 v[164:167], v143 offset:51200
	ds_read_b128 v[170:173], v143 offset:52224
	ds_read_b128 v[176:179], v143 offset:53248
	ds_read_b128 v[180:183], v143 offset:54272
	ds_read_b128 v[184:187], v143 offset:55296
	ds_read_b128 v[188:191], v143 offset:56320
	global_load_lds_dwordx4 v[138:139], off
	v_lshl_add_u64 v[138:139], v[212:213], 0, s[92:93]
	s_mov_b32 m0, s31
	s_nop 0
	global_load_lds_dwordx4 v[138:139], off
	s_mov_b32 m0, s60
	v_lshl_add_u64 v[138:139], v[214:215], 0, s[92:93]
	global_load_lds_dwordx4 v[138:139], off
	v_lshl_add_u64 v[138:139], v[216:217], 0, s[92:93]
	s_mov_b32 m0, s61
	s_nop 0
	global_load_lds_dwordx4 v[138:139], off
	s_waitcnt vmcnt(8)
	s_waitcnt lgkmcnt(0)
	s_barrier
	s_setprio 1
	v_mfma_f32_16x16x32_bf16 v[60:63], v[134:137], v[156:159], v[60:63]
	v_mfma_f32_16x16x32_bf16 v[56:59], v[148:151], v[156:159], v[56:59]
	v_mfma_f32_16x16x32_bf16 v[44:47], v[134:137], v[164:167], v[44:47]
	v_mfma_f32_16x16x32_bf16 v[40:43], v[148:151], v[164:167], v[40:43]
	v_mfma_f32_16x16x32_bf16 v[28:31], v[134:137], v[176:179], v[28:31]
	v_mfma_f32_16x16x32_bf16 v[24:27], v[148:151], v[176:179], v[24:27]
	v_mfma_f32_16x16x32_bf16 v[12:15], v[134:137], v[184:187], v[12:15]
	v_mfma_f32_16x16x32_bf16 v[8:11], v[148:151], v[184:187], v[8:11]
	v_mfma_f32_16x16x32_bf16 v[60:63], v[144:147], v[160:163], v[60:63]
	v_mfma_f32_16x16x32_bf16 v[56:59], v[152:155], v[160:163], v[56:59]
	v_mfma_f32_16x16x32_bf16 v[44:47], v[144:147], v[170:173], v[44:47]
	v_mfma_f32_16x16x32_bf16 v[40:43], v[152:155], v[170:173], v[40:43]
	v_mfma_f32_16x16x32_bf16 v[28:31], v[144:147], v[180:183], v[28:31]
	v_mfma_f32_16x16x32_bf16 v[24:27], v[152:155], v[180:183], v[24:27]
	v_mfma_f32_16x16x32_bf16 v[12:15], v[144:147], v[188:191], v[12:15]
	v_mfma_f32_16x16x32_bf16 v[8:11], v[152:155], v[188:191], v[8:11]
	v_mfma_f32_16x16x32_bf16 v[52:55], v[192:195], v[156:159], v[52:55]
	v_mfma_f32_16x16x32_bf16 v[48:51], v[200:203], v[156:159], v[48:51]
	v_mfma_f32_16x16x32_bf16 v[36:39], v[192:195], v[164:167], v[36:39]
	v_mfma_f32_16x16x32_bf16 v[32:35], v[200:203], v[164:167], v[32:35]
	v_mfma_f32_16x16x32_bf16 v[20:23], v[192:195], v[176:179], v[20:23]
	v_mfma_f32_16x16x32_bf16 v[16:19], v[200:203], v[176:179], v[16:19]
	v_mfma_f32_16x16x32_bf16 v[4:7], v[192:195], v[184:187], v[4:7]
	v_mfma_f32_16x16x32_bf16 v[0:3], v[200:203], v[184:187], v[0:3]
	v_mfma_f32_16x16x32_bf16 v[52:55], v[196:199], v[160:163], v[52:55]
	v_mfma_f32_16x16x32_bf16 v[48:51], v[204:207], v[160:163], v[48:51]
	v_mfma_f32_16x16x32_bf16 v[36:39], v[196:199], v[170:173], v[36:39]
	v_mfma_f32_16x16x32_bf16 v[32:35], v[204:207], v[170:173], v[32:35]
	v_mfma_f32_16x16x32_bf16 v[20:23], v[196:199], v[180:183], v[20:23]
	v_mfma_f32_16x16x32_bf16 v[16:19], v[204:207], v[180:183], v[16:19]
	v_mfma_f32_16x16x32_bf16 v[4:7], v[196:199], v[188:191], v[4:7]
	v_mfma_f32_16x16x32_bf16 v[0:3], v[204:207], v[188:191], v[0:3]
	s_setprio 0
	s_add_u32 s54, s54, 0x100
	s_addc_u32 s55, s55, 0
	s_add_u32 s76, s76, 0x100
	s_addc_u32 s77, s77, 0
	s_cmp_ge_i32 s80, s26
	s_mov_b32 s56, s80
	s_barrier
	s_cbranch_scc0 .LBB0_164
	v_readlane_b32 s76, v255, 9
	v_readlane_b32 s77, v255, 10
	s_branch .LBB0_155

; #define PG8_STAGE(bufoff, gbase) do { _Pragma("unroll") for (int _i = 0; _i < 2; ++_i) \
;         __builtin_amdgcn_global_load_lds((const unsigned*)((const char*)(gbase) + voffA[_i]), (LAS unsigned*)(lds + (bufoff) + ldsw + _i * 8192), 16, 0, 0); } while (0)
; #define PG8_LDA(dst, b, h) do { _Pragma("unroll") for (int m = 0; m < 4; ++m) _Pragma("unroll") for (int k = 0; k < 2; ++k) dst[m][k] = *(const LAS bf16x8*)(lds + PG8_SA(b, h) + aoff + m * 2048 + k * 1024); } while (0)
; #define PG8_LDB(dst, b, h) do { _Pragma("unroll") for (int n = 0; n < 2; ++n) _Pragma("unroll") for (int k = 0; k < 2; ++k) dst[n][k] = *(const LAS bf16x8*)(lds + PG8_SB(b, h) + boff + n * 2048 + k * 1024); } while (0)
; #define PG8_MMA(ai, bj, At, Bt) do { __builtin_amdgcn_s_setprio(1); _Pragma("unroll") for (int m = 0; m < 4; ++m) _Pragma("unroll") for (int n = 0; n < 2; ++n) _Pragma("unroll") for (int k = 0; k < 2; ++k) \
;         acc[ai][bj][m][n] = __builtin_amdgcn_mfma_f32_16x16x32_bf16(Bt[n][k], At[m][k], acc[ai][bj][m][n], 0, 0, 0); __builtin_amdgcn_s_setprio(0); } while (0)
; #define PG8_WAIT_V(n) asm volatile("s_waitcnt vmcnt(" #n ")" ::: "memory")
; #define PG8_WAIT_L(n) asm volatile("s_waitcnt lgkmcnt(" #n ")" ::: "memory")
; #define PG8_BAR __builtin_amdgcn_s_barrier()
; #define PG8_SCHED __builtin_amdgcn_sched_barrier(0)
; template <class Epi>
; DI void gemm_phase(const int TID, const int BID, LAS unsigned char* lds, const Gemm g, const Epi& E) {
;     ...
;             PG8_LDB(B0, 0, 0); PG8_SCHED; PG8_LDA(At, 0, 0); PG8_STAGE(PG8_SA(1, 1), a1 + hstep);
;             PG8_WAIT_L(8); PG8_BAR; PG8_WAIT_L(0); PG8_MMA(0, 0, At, B0); PG8_BAR; PG8_SCHED;
;             PG8_LDB(B1, 0, 1); PG8_STAGE(PG8_SB(0, 0), b2);
;             PG8_BAR; PG8_WAIT_L(0); PG8_MMA(0, 1, At, B1); PG8_BAR;
;             PG8_LDA(At, 0, 1); PG8_STAGE(PG8_SA(0, 0), a2);
;             PG8_BAR; PG8_WAIT_L(0); PG8_MMA(1, 0, At, B0); PG8_BAR; PG8_SCHED;
;             PG8_STAGE(PG8_SB(0, 1), b2 + hstep);
;             PG8_WAIT_V(6); PG8_BAR; PG8_MMA(1, 1, At, B1); PG8_BAR;
.LBB0_230:
	v_add_u32_e32 v140, s18, v246
	ds_read_b128 v[128:131], v140
	ds_read_b128 v[132:135], v140 offset:1024
	ds_read_b128 v[136:139], v140 offset:2048
	ds_read_b128 v[140:143], v140 offset:3072
	s_add_i32 s58, s54, 2
	s_add_u32 s56, s52, 0x80
	s_addc_u32 s55, s53, 0
	s_cmp_eq_u32 vcc_lo, s54
	s_cselect_b32 s54, s12, s56
	s_cselect_b32 s55, s13, s55
	s_cselect_b32 s57, s1, s29
	s_cselect_b32 s56, s0, vcc_hi
	v_lshl_add_u64 v[186:187], s[52:53], 0, v[178:179]
	s_add_i32 m0, s21, 0xc000
	ds_read_b128 v[144:147], v248
	ds_read_b128 v[148:151], v248 offset:1024
	ds_read_b128 v[152:155], v248 offset:2048
	ds_read_b128 v[156:159], v248 offset:3072
	ds_read_b128 v[160:163], v248 offset:4096
	ds_read_b128 v[164:167], v248 offset:5120
	ds_read_b128 v[170:173], v248 offset:6144
	ds_read_b128 v[182:185], v248 offset:7168
	global_load_lds_dwordx4 v[186:187], off
	v_lshl_add_u64 v[186:187], s[52:53], 0, v[180:181]
	s_add_i32 m0, s21, 0xe000
	s_nop 0
	global_load_lds_dwordx4 v[186:187], off
	v_add_u32_e32 v198, s23, v246
	ds_read_b128 v[186:189], v198
	ds_read_b128 v[190:193], v198 offset:1024
	ds_read_b128 v[194:197], v198 offset:2048
	ds_read_b128 v[198:201], v198 offset:3072
	s_waitcnt vmcnt(8)
	s_waitcnt lgkmcnt(0)
	s_barrier
	s_setprio 1
	v_mfma_f32_16x16x32_bf16 v[124:127], v[128:131], v[144:147], v[124:127]
	v_mfma_f32_16x16x32_bf16 v[120:123], v[136:139], v[144:147], v[120:123]
	v_mfma_f32_16x16x32_bf16 v[108:111], v[128:131], v[152:155], v[108:111]
	v_mfma_f32_16x16x32_bf16 v[104:107], v[136:139], v[152:155], v[104:107]
	v_mfma_f32_16x16x32_bf16 v[92:95], v[128:131], v[160:163], v[92:95]
	v_mfma_f32_16x16x32_bf16 v[88:91], v[136:139], v[160:163], v[88:91]
	v_mfma_f32_16x16x32_bf16 v[76:79], v[128:131], v[170:173], v[76:79]
	v_mfma_f32_16x16x32_bf16 v[72:75], v[136:139], v[170:173], v[72:75]
	v_mfma_f32_16x16x32_bf16 v[124:127], v[132:135], v[148:151], v[124:127]
	v_mfma_f32_16x16x32_bf16 v[120:123], v[140:143], v[148:151], v[120:123]
	v_mfma_f32_16x16x32_bf16 v[108:111], v[132:135], v[156:159], v[108:111]
	v_mfma_f32_16x16x32_bf16 v[104:107], v[140:143], v[156:159], v[104:107]
	v_mfma_f32_16x16x32_bf16 v[92:95], v[132:135], v[164:167], v[92:95]
	v_mfma_f32_16x16x32_bf16 v[88:91], v[140:143], v[164:167], v[88:91]
	v_mfma_f32_16x16x32_bf16 v[76:79], v[132:135], v[182:185], v[76:79]
	v_mfma_f32_16x16x32_bf16 v[72:75], v[140:143], v[182:185], v[72:75]
	v_mfma_f32_16x16x32_bf16 v[116:119], v[186:189], v[144:147], v[116:119]
	v_mfma_f32_16x16x32_bf16 v[112:115], v[194:197], v[144:147], v[112:115]
	v_mfma_f32_16x16x32_bf16 v[100:103], v[186:189], v[152:155], v[100:103]
	v_mfma_f32_16x16x32_bf16 v[96:99], v[194:197], v[152:155], v[96:99]
	v_mfma_f32_16x16x32_bf16 v[84:87], v[186:189], v[160:163], v[84:87]
	v_mfma_f32_16x16x32_bf16 v[80:83], v[194:197], v[160:163], v[80:83]
	v_mfma_f32_16x16x32_bf16 v[68:71], v[186:189], v[170:173], v[68:71]
	v_mfma_f32_16x16x32_bf16 v[64:67], v[194:197], v[170:173], v[64:67]
	v_mfma_f32_16x16x32_bf16 v[116:119], v[190:193], v[148:151], v[116:119]
	v_mfma_f32_16x16x32_bf16 v[112:115], v[198:201], v[148:151], v[112:115]
	v_mfma_f32_16x16x32_bf16 v[100:103], v[190:193], v[156:159], v[100:103]
	v_mfma_f32_16x16x32_bf16 v[96:99], v[198:201], v[156:159], v[96:99]
	v_mfma_f32_16x16x32_bf16 v[84:87], v[190:193], v[164:167], v[84:87]
	v_mfma_f32_16x16x32_bf16 v[80:83], v[198:201], v[164:167], v[80:83]
	v_mfma_f32_16x16x32_bf16 v[68:71], v[190:193], v[182:185], v[68:71]
	v_mfma_f32_16x16x32_bf16 v[64:67], v[198:201], v[182:185], v[64:67]
	s_setprio 0
	s_barrier
	s_mov_b32 m0, s19
	v_lshl_add_u64 v[202:203], s[56:57], 0, v[168:169]
	global_load_lds_dwordx4 v[202:203], off
	v_lshl_add_u64 v[204:205], s[56:57], 0, v[176:177]
	s_mov_b32 m0, s20
	s_nop 0
	global_load_lds_dwordx4 v[204:205], off
	s_mov_b32 m0, s21
	v_lshl_add_u64 v[206:207], s[54:55], 0, v[168:169]
	ds_read_b128 v[144:147], v248 offset:16384
	ds_read_b128 v[148:151], v248 offset:17408
	ds_read_b128 v[152:155], v248 offset:18432
	ds_read_b128 v[156:159], v248 offset:19456
	ds_read_b128 v[160:163], v248 offset:20480
	ds_read_b128 v[164:167], v248 offset:21504
	ds_read_b128 v[170:173], v248 offset:22528
	ds_read_b128 v[182:185], v248 offset:23552
	global_load_lds_dwordx4 v[206:207], off
	v_lshl_add_u64 v[208:209], s[54:55], 0, v[176:177]
	s_mov_b32 m0, s22
	s_nop 0
	global_load_lds_dwordx4 v[208:209], off
	s_add_u32 s56, s56, s2
	s_addc_u32 s57, s57, s3
	s_mov_b32 m0, s24
	v_lshl_add_u64 v[210:211], s[56:57], 0, v[168:169]
	global_load_lds_dwordx4 v[210:211], off
	v_lshl_add_u64 v[212:213], s[56:57], 0, v[176:177]
	s_mov_b32 m0, s25
	s_nop 0
	global_load_lds_dwordx4 v[212:213], off
	s_waitcnt vmcnt(8)
	s_waitcnt lgkmcnt(0)
	s_barrier
; #define PG8_STAGE(bufoff, gbase) do { _Pragma("unroll") for (int _i = 0; _i < 2; ++_i) \
;         __builtin_amdgcn_global_load_lds((const unsigned*)((const char*)(gbase) + voffA[_i]), (LAS unsigned*)(lds + (bufoff) + ldsw + _i * 8192), 16, 0, 0); } while (0)
; #define PG8_LDA(dst, b, h) do { _Pragma("unroll") for (int m = 0; m < 4; ++m) _Pragma("unroll") for (int k = 0; k < 2; ++k) dst[m][k] = *(const LAS bf16x8*)(lds + PG8_SA(b, h) + aoff + m * 2048 + k * 1024); } while (0)
; #define PG8_LDB(dst, b, h) do { _Pragma("unroll") for (int n = 0; n < 2; ++n) _Pragma("unroll") for (int k = 0; k < 2; ++k) dst[n][k] = *(const LAS bf16x8*)(lds + PG8_SB(b, h) + boff + n * 2048 + k * 1024); } while (0)
; #define PG8_MMA(ai, bj, At, Bt) do { __builtin_amdgcn_s_setprio(1); _Pragma("unroll") for (int m = 0; m < 4; ++m) _Pragma("unroll") for (int n = 0; n < 2; ++n) _Pragma("unroll") for (int k = 0; k < 2; ++k) \
;         acc[ai][bj][m][n] = __builtin_amdgcn_mfma_f32_16x16x32_bf16(Bt[n][k], At[m][k], acc[ai][bj][m][n], 0, 0, 0); __builtin_amdgcn_s_setprio(0); } while (0)
; #define PG8_WAIT_V(n) asm volatile("s_waitcnt vmcnt(" #n ")" ::: "memory")
; #define PG8_WAIT_L(n) asm volatile("s_waitcnt lgkmcnt(" #n ")" ::: "memory")
; #define PG8_BAR __builtin_amdgcn_s_barrier()
; #define PG8_SCHED __builtin_amdgcn_sched_barrier(0)
; template <class Epi>
; DI void gemm_phase(const int TID, const int BID, LAS unsigned char* lds, const Gemm g, const Epi& E) {
;     ...
;             PG8_BAR; PG8_WAIT_L(0); PG8_MMA(1, 0, At, B0); PG8_BAR; PG8_SCHED;
;             PG8_STAGE(PG8_SB(0, 1), b2 + hstep);
;             PG8_WAIT_V(6); PG8_BAR; PG8_MMA(1, 1, At, B1); PG8_BAR;
;             PG8_LDB(B0, 1, 0); PG8_SCHED; PG8_LDA(At, 1, 0); PG8_STAGE(PG8_SA(0, 1), a2 + hstep);
;             PG8_WAIT_L(8); PG8_BAR; PG8_WAIT_L(0); PG8_MMA(0, 0, At, B0); PG8_BAR; PG8_SCHED;
;             PG8_LDB(B1, 1, 1); PG8_STAGE(PG8_SB(1, 0), b3);
;             PG8_BAR; PG8_WAIT_L(0); PG8_MMA(0, 1, At, B1); PG8_BAR;
	s_setprio 1
	v_mfma_f32_16x16x32_bf16 v[60:63], v[128:131], v[144:147], v[60:63]
	v_mfma_f32_16x16x32_bf16 v[56:59], v[136:139], v[144:147], v[56:59]
	v_mfma_f32_16x16x32_bf16 v[44:47], v[128:131], v[152:155], v[44:47]
	v_mfma_f32_16x16x32_bf16 v[40:43], v[136:139], v[152:155], v[40:43]
	v_mfma_f32_16x16x32_bf16 v[28:31], v[128:131], v[160:163], v[28:31]
	v_mfma_f32_16x16x32_bf16 v[24:27], v[136:139], v[160:163], v[24:27]
	v_mfma_f32_16x16x32_bf16 v[12:15], v[128:131], v[170:173], v[12:15]
	v_mfma_f32_16x16x32_bf16 v[8:11], v[136:139], v[170:173], v[8:11]
	v_mfma_f32_16x16x32_bf16 v[60:63], v[132:135], v[148:151], v[60:63]
	v_mfma_f32_16x16x32_bf16 v[56:59], v[140:143], v[148:151], v[56:59]
	v_mfma_f32_16x16x32_bf16 v[44:47], v[132:135], v[156:159], v[44:47]
	v_mfma_f32_16x16x32_bf16 v[40:43], v[140:143], v[156:159], v[40:43]
	v_mfma_f32_16x16x32_bf16 v[28:31], v[132:135], v[164:167], v[28:31]
	v_mfma_f32_16x16x32_bf16 v[24:27], v[140:143], v[164:167], v[24:27]
	v_mfma_f32_16x16x32_bf16 v[12:15], v[132:135], v[182:185], v[12:15]
	v_mfma_f32_16x16x32_bf16 v[8:11], v[140:143], v[182:185], v[8:11]
	v_mfma_f32_16x16x32_bf16 v[52:55], v[186:189], v[144:147], v[52:55]
	v_mfma_f32_16x16x32_bf16 v[48:51], v[194:197], v[144:147], v[48:51]
	v_mfma_f32_16x16x32_bf16 v[36:39], v[186:189], v[152:155], v[36:39]
	v_mfma_f32_16x16x32_bf16 v[32:35], v[194:197], v[152:155], v[32:35]
	v_mfma_f32_16x16x32_bf16 v[20:23], v[186:189], v[160:163], v[20:23]
	v_mfma_f32_16x16x32_bf16 v[16:19], v[194:197], v[160:163], v[16:19]
	v_mfma_f32_16x16x32_bf16 v[4:7], v[186:189], v[170:173], v[4:7]
	v_mfma_f32_16x16x32_bf16 v[0:3], v[194:197], v[170:173], v[0:3]
	v_mfma_f32_16x16x32_bf16 v[52:55], v[190:193], v[148:151], v[52:55]
	v_mfma_f32_16x16x32_bf16 v[48:51], v[198:201], v[148:151], v[48:51]
	v_mfma_f32_16x16x32_bf16 v[36:39], v[190:193], v[156:159], v[36:39]
	v_mfma_f32_16x16x32_bf16 v[32:35], v[198:201], v[156:159], v[32:35]
	v_mfma_f32_16x16x32_bf16 v[20:23], v[190:193], v[164:167], v[20:23]
	v_mfma_f32_16x16x32_bf16 v[16:19], v[198:201], v[164:167], v[16:19]
	v_mfma_f32_16x16x32_bf16 v[4:7], v[190:193], v[182:185], v[4:7]
	v_mfma_f32_16x16x32_bf16 v[0:3], v[198:201], v[182:185], v[0:3]
	s_setprio 0
	s_barrier
	v_add_u32_e32 v140, s31, v246
	ds_read_b128 v[128:131], v140
	ds_read_b128 v[132:135], v140 offset:1024
	ds_read_b128 v[136:139], v140 offset:2048
	ds_read_b128 v[140:143], v140 offset:3072
	s_add_u32 s54, s54, s2
	s_addc_u32 s55, s55, s3
	s_mov_b32 m0, s26
	v_lshl_add_u64 v[186:187], s[54:55], 0, v[168:169]
	ds_read_b128 v[144:147], v248 offset:32768
	ds_read_b128 v[148:151], v248 offset:33792
	ds_read_b128 v[152:155], v248 offset:34816
	ds_read_b128 v[156:159], v248 offset:35840
	ds_read_b128 v[160:163], v248 offset:36864
	ds_read_b128 v[164:167], v248 offset:37888
	ds_read_b128 v[170:173], v248 offset:38912
	ds_read_b128 v[182:185], v248 offset:39936
	global_load_lds_dwordx4 v[186:187], off
	v_lshl_add_u64 v[186:187], s[54:55], 0, v[176:177]
	s_mov_b32 m0, s27
	s_nop 0
	global_load_lds_dwordx4 v[186:187], off
	v_add_u32_e32 v198, s65, v246
	ds_read_b128 v[186:189], v198
	ds_read_b128 v[190:193], v198 offset:1024
	ds_read_b128 v[194:197], v198 offset:2048
	ds_read_b128 v[198:201], v198 offset:3072
	s_waitcnt vmcnt(8)
	s_waitcnt lgkmcnt(0)
	s_barrier
	s_setprio 1
	v_mfma_f32_16x16x32_bf16 v[124:127], v[128:131], v[144:147], v[124:127]
	v_mfma_f32_16x16x32_bf16 v[120:123], v[136:139], v[144:147], v[120:123]
	v_mfma_f32_16x16x32_bf16 v[108:111], v[128:131], v[152:155], v[108:111]
	v_mfma_f32_16x16x32_bf16 v[104:107], v[136:139], v[152:155], v[104:107]
	v_mfma_f32_16x16x32_bf16 v[92:95], v[128:131], v[160:163], v[92:95]
	v_mfma_f32_16x16x32_bf16 v[88:91], v[136:139], v[160:163], v[88:91]
	v_mfma_f32_16x16x32_bf16 v[76:79], v[128:131], v[170:173], v[76:79]
	v_mfma_f32_16x16x32_bf16 v[72:75], v[136:139], v[170:173], v[72:75]
	v_mfma_f32_16x16x32_bf16 v[124:127], v[132:135], v[148:151], v[124:127]
	v_mfma_f32_16x16x32_bf16 v[120:123], v[140:143], v[148:151], v[120:123]
	v_mfma_f32_16x16x32_bf16 v[108:111], v[132:135], v[156:159], v[108:111]
	v_mfma_f32_16x16x32_bf16 v[104:107], v[140:143], v[156:159], v[104:107]
	v_mfma_f32_16x16x32_bf16 v[92:95], v[132:135], v[164:167], v[92:95]
	v_mfma_f32_16x16x32_bf16 v[88:91], v[140:143], v[164:167], v[88:91]
	v_mfma_f32_16x16x32_bf16 v[76:79], v[132:135], v[182:185], v[76:79]
	v_mfma_f32_16x16x32_bf16 v[72:75], v[140:143], v[182:185], v[72:75]
	v_mfma_f32_16x16x32_bf16 v[116:119], v[186:189], v[144:147], v[116:119]
	v_mfma_f32_16x16x32_bf16 v[112:115], v[194:197], v[144:147], v[112:115]
	v_mfma_f32_16x16x32_bf16 v[100:103], v[186:189], v[152:155], v[100:103]
	v_mfma_f32_16x16x32_bf16 v[96:99], v[194:197], v[152:155], v[96:99]
	v_mfma_f32_16x16x32_bf16 v[84:87], v[186:189], v[160:163], v[84:87]
	v_mfma_f32_16x16x32_bf16 v[80:83], v[194:197], v[160:163], v[80:83]
	v_mfma_f32_16x16x32_bf16 v[68:71], v[186:189], v[170:173], v[68:71]
	v_mfma_f32_16x16x32_bf16 v[64:67], v[194:197], v[170:173], v[64:67]
	v_mfma_f32_16x16x32_bf16 v[116:119], v[190:193], v[148:151], v[116:119]
	v_mfma_f32_16x16x32_bf16 v[112:115], v[198:201], v[148:151], v[112:115]
	v_mfma_f32_16x16x32_bf16 v[100:103], v[190:193], v[156:159], v[100:103]
	v_mfma_f32_16x16x32_bf16 v[96:99], v[198:201], v[156:159], v[96:99]
	v_mfma_f32_16x16x32_bf16 v[84:87], v[190:193], v[164:167], v[84:87]
	v_mfma_f32_16x16x32_bf16 v[80:83], v[198:201], v[164:167], v[80:83]
	v_mfma_f32_16x16x32_bf16 v[68:71], v[190:193], v[182:185], v[68:71]
	v_mfma_f32_16x16x32_bf16 v[64:67], v[198:201], v[182:185], v[64:67]
	s_setprio 0
	s_barrier
; #define PG8_STAGE(bufoff, gbase) do { _Pragma("unroll") for (int _i = 0; _i < 2; ++_i) \
;         __builtin_amdgcn_global_load_lds((const unsigned*)((const char*)(gbase) + voffA[_i]), (LAS unsigned*)(lds + (bufoff) + ldsw + _i * 8192), 16, 0, 0); } while (0)
; #define PG8_LDA(dst, b, h) do { _Pragma("unroll") for (int m = 0; m < 4; ++m) _Pragma("unroll") for (int k = 0; k < 2; ++k) dst[m][k] = *(const LAS bf16x8*)(lds + PG8_SA(b, h) + aoff + m * 2048 + k * 1024); } while (0)
; #define PG8_MMA(ai, bj, At, Bt) do { __builtin_amdgcn_s_setprio(1); _Pragma("unroll") for (int m = 0; m < 4; ++m) _Pragma("unroll") for (int n = 0; n < 2; ++n) _Pragma("unroll") for (int k = 0; k < 2; ++k) \
;         acc[ai][bj][m][n] = __builtin_amdgcn_mfma_f32_16x16x32_bf16(Bt[n][k], At[m][k], acc[ai][bj][m][n], 0, 0, 0); __builtin_amdgcn_s_setprio(0); } while (0)
; #define PG8_WAIT_V(n) asm volatile("s_waitcnt vmcnt(" #n ")" ::: "memory")
; #define PG8_WAIT_L(n) asm volatile("s_waitcnt lgkmcnt(" #n ")" ::: "memory")
; #define PG8_BAR __builtin_amdgcn_s_barrier()
; #define PG8_SCHED __builtin_amdgcn_sched_barrier(0)
; template <class Epi>
; DI void gemm_phase(const int TID, const int BID, LAS unsigned char* lds, const Gemm g, const Epi& E) {
;     ...
;             PG8_LDA(At, 1, 1); PG8_STAGE(PG8_SA(1, 0), a3);
;             PG8_BAR; PG8_WAIT_L(0); PG8_MMA(1, 0, At, B0); PG8_BAR; PG8_SCHED;
;             PG8_STAGE(PG8_SB(1, 1), b3 + hstep);
;             PG8_WAIT_V(6); PG8_BAR; PG8_MMA(1, 1, At, B1); PG8_BAR;
;         }
	s_mov_b32 m0, s33
	v_lshl_add_u64 v[202:203], v[202:203], 0, s[92:93]
	global_load_lds_dwordx4 v[202:203], off
	v_lshl_add_u64 v[202:203], v[204:205], 0, s[92:93]
	s_mov_b32 m0, s60
	s_nop 0
	global_load_lds_dwordx4 v[202:203], off
	s_mov_b32 m0, s61
	v_lshl_add_u64 v[202:203], v[206:207], 0, s[92:93]
	ds_read_b128 v[144:147], v248 offset:49152
	ds_read_b128 v[148:151], v248 offset:50176
	ds_read_b128 v[152:155], v248 offset:51200
	ds_read_b128 v[156:159], v248 offset:52224
	ds_read_b128 v[160:163], v248 offset:53248
	ds_read_b128 v[164:167], v248 offset:54272
	ds_read_b128 v[170:173], v248 offset:55296
	ds_read_b128 v[182:185], v248 offset:56320
	global_load_lds_dwordx4 v[202:203], off
	v_lshl_add_u64 v[202:203], v[208:209], 0, s[92:93]
	s_mov_b32 m0, s64
	s_nop 0
	global_load_lds_dwordx4 v[202:203], off
	s_mov_b32 m0, s66
	v_lshl_add_u64 v[202:203], v[210:211], 0, s[92:93]
	global_load_lds_dwordx4 v[202:203], off
	v_lshl_add_u64 v[202:203], v[212:213], 0, s[92:93]
	s_mov_b32 m0, s67
	s_nop 0
	global_load_lds_dwordx4 v[202:203], off
	s_waitcnt vmcnt(8)
	s_waitcnt lgkmcnt(0)
	s_barrier
	s_setprio 1
	v_mfma_f32_16x16x32_bf16 v[60:63], v[128:131], v[144:147], v[60:63]
	v_mfma_f32_16x16x32_bf16 v[56:59], v[136:139], v[144:147], v[56:59]
	v_mfma_f32_16x16x32_bf16 v[44:47], v[128:131], v[152:155], v[44:47]
	v_mfma_f32_16x16x32_bf16 v[40:43], v[136:139], v[152:155], v[40:43]
	v_mfma_f32_16x16x32_bf16 v[28:31], v[128:131], v[160:163], v[28:31]
	v_mfma_f32_16x16x32_bf16 v[24:27], v[136:139], v[160:163], v[24:27]
	v_mfma_f32_16x16x32_bf16 v[12:15], v[128:131], v[170:173], v[12:15]
	v_mfma_f32_16x16x32_bf16 v[8:11], v[136:139], v[170:173], v[8:11]
	v_mfma_f32_16x16x32_bf16 v[60:63], v[132:135], v[148:151], v[60:63]
	v_mfma_f32_16x16x32_bf16 v[56:59], v[140:143], v[148:151], v[56:59]
	v_mfma_f32_16x16x32_bf16 v[44:47], v[132:135], v[156:159], v[44:47]
	v_mfma_f32_16x16x32_bf16 v[40:43], v[140:143], v[156:159], v[40:43]
	v_mfma_f32_16x16x32_bf16 v[28:31], v[132:135], v[164:167], v[28:31]
	v_mfma_f32_16x16x32_bf16 v[24:27], v[140:143], v[164:167], v[24:27]
	v_mfma_f32_16x16x32_bf16 v[12:15], v[132:135], v[182:185], v[12:15]
	v_mfma_f32_16x16x32_bf16 v[8:11], v[140:143], v[182:185], v[8:11]
	v_mfma_f32_16x16x32_bf16 v[52:55], v[186:189], v[144:147], v[52:55]
	v_mfma_f32_16x16x32_bf16 v[48:51], v[194:197], v[144:147], v[48:51]
	v_mfma_f32_16x16x32_bf16 v[36:39], v[186:189], v[152:155], v[36:39]
	v_mfma_f32_16x16x32_bf16 v[32:35], v[194:197], v[152:155], v[32:35]
	v_mfma_f32_16x16x32_bf16 v[20:23], v[186:189], v[160:163], v[20:23]
	v_mfma_f32_16x16x32_bf16 v[16:19], v[194:197], v[160:163], v[16:19]
	v_mfma_f32_16x16x32_bf16 v[4:7], v[186:189], v[170:173], v[4:7]
	v_mfma_f32_16x16x32_bf16 v[0:3], v[194:197], v[170:173], v[0:3]
	v_mfma_f32_16x16x32_bf16 v[52:55], v[190:193], v[148:151], v[52:55]
	v_mfma_f32_16x16x32_bf16 v[48:51], v[198:201], v[148:151], v[48:51]
	v_mfma_f32_16x16x32_bf16 v[36:39], v[190:193], v[156:159], v[36:39]
	v_mfma_f32_16x16x32_bf16 v[32:35], v[198:201], v[156:159], v[32:35]
	v_mfma_f32_16x16x32_bf16 v[20:23], v[190:193], v[164:167], v[20:23]
	v_mfma_f32_16x16x32_bf16 v[16:19], v[198:201], v[164:167], v[16:19]
	v_mfma_f32_16x16x32_bf16 v[4:7], v[190:193], v[182:185], v[4:7]
	v_mfma_f32_16x16x32_bf16 v[0:3], v[198:201], v[182:185], v[0:3]
	s_setprio 0
	s_add_u32 s52, s52, 0x100
	s_addc_u32 s53, s53, 0
	s_add_u32 vcc_hi, vcc_hi, 0x100
	s_addc_u32 s29, s29, 0
	s_cmp_ge_i32 s58, s17
	s_mov_b32 s54, s58
	s_barrier
	s_cbranch_scc0 .LBB0_230
	s_branch .LBB0_234

; #define PG8_STAGE(bufoff, gbase) do { _Pragma("unroll") for (int _i = 0; _i < 2; ++_i) \
;         __builtin_amdgcn_global_load_lds((const unsigned*)((const char*)(gbase) + voffA[_i]), (LAS unsigned*)(lds + (bufoff) + ldsw + _i * 8192), 16, 0, 0); } while (0)
; #define PG8_LDA(dst, b, h) do { _Pragma("unroll") for (int m = 0; m < 4; ++m) _Pragma("unroll") for (int k = 0; k < 2; ++k) dst[m][k] = *(const LAS bf16x8*)(lds + PG8_SA(b, h) + aoff + m * 2048 + k * 1024); } while (0)
; #define PG8_LDB(dst, b, h) do { _Pragma("unroll") for (int n = 0; n < 2; ++n) _Pragma("unroll") for (int k = 0; k < 2; ++k) dst[n][k] = *(const LAS bf16x8*)(lds + PG8_SB(b, h) + boff + n * 2048 + k * 1024); } while (0)
; #define PG8_MMA(ai, bj, At, Bt) do { __builtin_amdgcn_s_setprio(1); _Pragma("unroll") for (int m = 0; m < 4; ++m) _Pragma("unroll") for (int n = 0; n < 2; ++n) _Pragma("unroll") for (int k = 0; k < 2; ++k) \
;         acc[ai][bj][m][n] = __builtin_amdgcn_mfma_f32_16x16x32_bf16(Bt[n][k], At[m][k], acc[ai][bj][m][n], 0, 0, 0); __builtin_amdgcn_s_setprio(0); } while (0)
; #define PG8_WAIT_V(n) asm volatile("s_waitcnt vmcnt(" #n ")" ::: "memory")
; #define PG8_WAIT_L(n) asm volatile("s_waitcnt lgkmcnt(" #n ")" ::: "memory")
; #define PG8_BAR __builtin_amdgcn_s_barrier()
; #define PG8_SCHED __builtin_amdgcn_sched_barrier(0)
; template <class Epi>
; DI void gemm_phase(const int TID, const int BID, LAS unsigned char* lds, const Gemm g, const Epi& E) {
;     ...
;             PG8_LDB(B0, 0, 0); PG8_SCHED; PG8_LDA(At, 0, 0); PG8_STAGE(PG8_SA(1, 1), a1 + hstep);
;             PG8_WAIT_L(8); PG8_BAR; PG8_WAIT_L(0); PG8_MMA(0, 0, At, B0); PG8_BAR; PG8_SCHED;
;             PG8_LDB(B1, 0, 1); PG8_STAGE(PG8_SB(0, 0), b2);
;             PG8_BAR; PG8_WAIT_L(0); PG8_MMA(0, 1, At, B1); PG8_BAR;
;             PG8_LDA(At, 0, 1); PG8_STAGE(PG8_SA(0, 0), a2);
;             PG8_BAR; PG8_WAIT_L(0); PG8_MMA(1, 0, At, B0); PG8_BAR; PG8_SCHED;
;             PG8_STAGE(PG8_SB(0, 1), b2 + hstep);
;             PG8_WAIT_V(6); PG8_BAR; PG8_MMA(1, 1, At, B1); PG8_BAR;
.LBB0_271:
	v_add_u32_e32 v140, s18, v222
	ds_read_b128 v[128:131], v140
	ds_read_b128 v[132:135], v140 offset:1024
	ds_read_b128 v[136:139], v140 offset:2048
	ds_read_b128 v[140:143], v140 offset:3072
	s_add_i32 vcc_hi, s12, 2
	s_add_u32 s52, s0, 0x80
	s_addc_u32 s13, s1, 0
	s_cmp_eq_u32 s54, s12
	s_cselect_b32 s12, s8, s52
	s_cselect_b32 s13, s9, s13
	s_cselect_b32 s53, s11, vcc_lo
	s_cselect_b32 s52, s10, s55
	v_lshl_add_u64 v[170:171], s[0:1], 0, v[164:165]
	s_add_i32 m0, s21, 0xc000
	ds_read_b128 v[144:147], v224
	ds_read_b128 v[148:151], v224 offset:1024
	ds_read_b128 v[152:155], v224 offset:2048
	ds_read_b128 v[156:159], v224 offset:3072
	ds_read_b128 v[176:179], v224 offset:4096
	ds_read_b128 v[180:183], v224 offset:5120
	ds_read_b128 v[184:187], v224 offset:6144
	ds_read_b128 v[188:191], v224 offset:7168
	global_load_lds_dwordx4 v[170:171], off
	v_lshl_add_u64 v[170:171], s[0:1], 0, v[166:167]
	s_add_i32 m0, s21, 0xe000
	s_nop 0
	global_load_lds_dwordx4 v[170:171], off
	v_add_u32_e32 v168, s23, v222
	ds_read_b128 v[192:195], v168
	ds_read_b128 v[196:199], v168 offset:1024
	ds_read_b128 v[200:203], v168 offset:2048
	ds_read_b128 v[204:207], v168 offset:3072
	s_waitcnt vmcnt(8)
	s_waitcnt lgkmcnt(0)
	s_barrier
	s_setprio 1
	v_mfma_f32_16x16x32_bf16 v[124:127], v[128:131], v[144:147], v[124:127]
	v_mfma_f32_16x16x32_bf16 v[120:123], v[136:139], v[144:147], v[120:123]
	v_mfma_f32_16x16x32_bf16 v[108:111], v[128:131], v[152:155], v[108:111]
	v_mfma_f32_16x16x32_bf16 v[104:107], v[136:139], v[152:155], v[104:107]
	v_mfma_f32_16x16x32_bf16 v[92:95], v[128:131], v[176:179], v[92:95]
	v_mfma_f32_16x16x32_bf16 v[88:91], v[136:139], v[176:179], v[88:91]
	v_mfma_f32_16x16x32_bf16 v[76:79], v[128:131], v[184:187], v[76:79]
	v_mfma_f32_16x16x32_bf16 v[72:75], v[136:139], v[184:187], v[72:75]
	v_mfma_f32_16x16x32_bf16 v[124:127], v[132:135], v[148:151], v[124:127]
	v_mfma_f32_16x16x32_bf16 v[120:123], v[140:143], v[148:151], v[120:123]
	v_mfma_f32_16x16x32_bf16 v[108:111], v[132:135], v[156:159], v[108:111]
	v_mfma_f32_16x16x32_bf16 v[104:107], v[140:143], v[156:159], v[104:107]
	v_mfma_f32_16x16x32_bf16 v[92:95], v[132:135], v[180:183], v[92:95]
	v_mfma_f32_16x16x32_bf16 v[88:91], v[140:143], v[180:183], v[88:91]
	v_mfma_f32_16x16x32_bf16 v[76:79], v[132:135], v[188:191], v[76:79]
	v_mfma_f32_16x16x32_bf16 v[72:75], v[140:143], v[188:191], v[72:75]
	v_mfma_f32_16x16x32_bf16 v[116:119], v[192:195], v[144:147], v[116:119]
	v_mfma_f32_16x16x32_bf16 v[112:115], v[200:203], v[144:147], v[112:115]
	v_mfma_f32_16x16x32_bf16 v[100:103], v[192:195], v[152:155], v[100:103]
	v_mfma_f32_16x16x32_bf16 v[96:99], v[200:203], v[152:155], v[96:99]
	v_mfma_f32_16x16x32_bf16 v[84:87], v[192:195], v[176:179], v[84:87]
	v_mfma_f32_16x16x32_bf16 v[80:83], v[200:203], v[176:179], v[80:83]
	v_mfma_f32_16x16x32_bf16 v[68:71], v[192:195], v[184:187], v[68:71]
	v_mfma_f32_16x16x32_bf16 v[64:67], v[200:203], v[184:187], v[64:67]
	v_mfma_f32_16x16x32_bf16 v[116:119], v[196:199], v[148:151], v[116:119]
	v_mfma_f32_16x16x32_bf16 v[112:115], v[204:207], v[148:151], v[112:115]
	v_mfma_f32_16x16x32_bf16 v[100:103], v[196:199], v[156:159], v[100:103]
	v_mfma_f32_16x16x32_bf16 v[96:99], v[204:207], v[156:159], v[96:99]
	v_mfma_f32_16x16x32_bf16 v[84:87], v[196:199], v[180:183], v[84:87]
	v_mfma_f32_16x16x32_bf16 v[80:83], v[204:207], v[180:183], v[80:83]
	v_mfma_f32_16x16x32_bf16 v[68:71], v[196:199], v[188:191], v[68:71]
	v_mfma_f32_16x16x32_bf16 v[64:67], v[204:207], v[188:191], v[64:67]
	s_setprio 0
	s_barrier
	s_mov_b32 m0, s19
	v_lshl_add_u64 v[170:171], s[52:53], 0, v[160:161]
	global_load_lds_dwordx4 v[170:171], off
	v_lshl_add_u64 v[172:173], s[52:53], 0, v[162:163]
	s_mov_b32 m0, s20
	s_nop 0
	global_load_lds_dwordx4 v[172:173], off
	s_mov_b32 m0, s21
	v_lshl_add_u64 v[208:209], s[12:13], 0, v[160:161]
	ds_read_b128 v[144:147], v224 offset:16384
	ds_read_b128 v[148:151], v224 offset:17408
	ds_read_b128 v[152:155], v224 offset:18432
	ds_read_b128 v[156:159], v224 offset:19456
	ds_read_b128 v[176:179], v224 offset:20480
	ds_read_b128 v[180:183], v224 offset:21504
	ds_read_b128 v[184:187], v224 offset:22528
	ds_read_b128 v[188:191], v224 offset:23552
	global_load_lds_dwordx4 v[208:209], off
	v_lshl_add_u64 v[210:211], s[12:13], 0, v[162:163]
	s_mov_b32 m0, s22
	s_nop 0
	global_load_lds_dwordx4 v[210:211], off
	s_add_u32 s52, s52, s2
	s_addc_u32 s53, s53, s3
	s_mov_b32 m0, s24
	v_lshl_add_u64 v[212:213], s[52:53], 0, v[160:161]
	global_load_lds_dwordx4 v[212:213], off
	v_lshl_add_u64 v[214:215], s[52:53], 0, v[162:163]
	s_mov_b32 m0, s25
	s_nop 0
	global_load_lds_dwordx4 v[214:215], off
	s_waitcnt vmcnt(8)
	s_waitcnt lgkmcnt(0)
	s_barrier
; #define PG8_STAGE(bufoff, gbase) do { _Pragma("unroll") for (int _i = 0; _i < 2; ++_i) \
;         __builtin_amdgcn_global_load_lds((const unsigned*)((const char*)(gbase) + voffA[_i]), (LAS unsigned*)(lds + (bufoff) + ldsw + _i * 8192), 16, 0, 0); } while (0)
; #define PG8_LDA(dst, b, h) do { _Pragma("unroll") for (int m = 0; m < 4; ++m) _Pragma("unroll") for (int k = 0; k < 2; ++k) dst[m][k] = *(const LAS bf16x8*)(lds + PG8_SA(b, h) + aoff + m * 2048 + k * 1024); } while (0)
; #define PG8_LDB(dst, b, h) do { _Pragma("unroll") for (int n = 0; n < 2; ++n) _Pragma("unroll") for (int k = 0; k < 2; ++k) dst[n][k] = *(const LAS bf16x8*)(lds + PG8_SB(b, h) + boff + n * 2048 + k * 1024); } while (0)
; #define PG8_MMA(ai, bj, At, Bt) do { __builtin_amdgcn_s_setprio(1); _Pragma("unroll") for (int m = 0; m < 4; ++m) _Pragma("unroll") for (int n = 0; n < 2; ++n) _Pragma("unroll") for (int k = 0; k < 2; ++k) \
;         acc[ai][bj][m][n] = __builtin_amdgcn_mfma_f32_16x16x32_bf16(Bt[n][k], At[m][k], acc[ai][bj][m][n], 0, 0, 0); __builtin_amdgcn_s_setprio(0); } while (0)
; #define PG8_WAIT_V(n) asm volatile("s_waitcnt vmcnt(" #n ")" ::: "memory")
; #define PG8_WAIT_L(n) asm volatile("s_waitcnt lgkmcnt(" #n ")" ::: "memory")
; #define PG8_BAR __builtin_amdgcn_s_barrier()
; #define PG8_SCHED __builtin_amdgcn_sched_barrier(0)
; template <class Epi>
; DI void gemm_phase(const int TID, const int BID, LAS unsigned char* lds, const Gemm g, const Epi& E) {
;     ...
;             PG8_BAR; PG8_WAIT_L(0); PG8_MMA(1, 0, At, B0); PG8_BAR; PG8_SCHED;
;             PG8_STAGE(PG8_SB(0, 1), b2 + hstep);
;             PG8_WAIT_V(6); PG8_BAR; PG8_MMA(1, 1, At, B1); PG8_BAR;
;             PG8_LDB(B0, 1, 0); PG8_SCHED; PG8_LDA(At, 1, 0); PG8_STAGE(PG8_SA(0, 1), a2 + hstep);
;             PG8_WAIT_L(8); PG8_BAR; PG8_WAIT_L(0); PG8_MMA(0, 0, At, B0); PG8_BAR; PG8_SCHED;
;             PG8_LDB(B1, 1, 1); PG8_STAGE(PG8_SB(1, 0), b3);
;             PG8_BAR; PG8_WAIT_L(0); PG8_MMA(0, 1, At, B1); PG8_BAR;
	s_setprio 1
	v_mfma_f32_16x16x32_bf16 v[60:63], v[128:131], v[144:147], v[60:63]
	v_mfma_f32_16x16x32_bf16 v[56:59], v[136:139], v[144:147], v[56:59]
	v_mfma_f32_16x16x32_bf16 v[44:47], v[128:131], v[152:155], v[44:47]
	v_mfma_f32_16x16x32_bf16 v[40:43], v[136:139], v[152:155], v[40:43]
	v_mfma_f32_16x16x32_bf16 v[28:31], v[128:131], v[176:179], v[28:31]
	v_mfma_f32_16x16x32_bf16 v[24:27], v[136:139], v[176:179], v[24:27]
	v_mfma_f32_16x16x32_bf16 v[12:15], v[128:131], v[184:187], v[12:15]
	v_mfma_f32_16x16x32_bf16 v[8:11], v[136:139], v[184:187], v[8:11]
	v_mfma_f32_16x16x32_bf16 v[60:63], v[132:135], v[148:151], v[60:63]
	v_mfma_f32_16x16x32_bf16 v[56:59], v[140:143], v[148:151], v[56:59]
	v_mfma_f32_16x16x32_bf16 v[44:47], v[132:135], v[156:159], v[44:47]
	v_mfma_f32_16x16x32_bf16 v[40:43], v[140:143], v[156:159], v[40:43]
	v_mfma_f32_16x16x32_bf16 v[28:31], v[132:135], v[180:183], v[28:31]
	v_mfma_f32_16x16x32_bf16 v[24:27], v[140:143], v[180:183], v[24:27]
	v_mfma_f32_16x16x32_bf16 v[12:15], v[132:135], v[188:191], v[12:15]
	v_mfma_f32_16x16x32_bf16 v[8:11], v[140:143], v[188:191], v[8:11]
	v_mfma_f32_16x16x32_bf16 v[52:55], v[192:195], v[144:147], v[52:55]
	v_mfma_f32_16x16x32_bf16 v[48:51], v[200:203], v[144:147], v[48:51]
	v_mfma_f32_16x16x32_bf16 v[36:39], v[192:195], v[152:155], v[36:39]
	v_mfma_f32_16x16x32_bf16 v[32:35], v[200:203], v[152:155], v[32:35]
	v_mfma_f32_16x16x32_bf16 v[20:23], v[192:195], v[176:179], v[20:23]
	v_mfma_f32_16x16x32_bf16 v[16:19], v[200:203], v[176:179], v[16:19]
	v_mfma_f32_16x16x32_bf16 v[4:7], v[192:195], v[184:187], v[4:7]
	v_mfma_f32_16x16x32_bf16 v[0:3], v[200:203], v[184:187], v[0:3]
	v_mfma_f32_16x16x32_bf16 v[52:55], v[196:199], v[148:151], v[52:55]
	v_mfma_f32_16x16x32_bf16 v[48:51], v[204:207], v[148:151], v[48:51]
	v_mfma_f32_16x16x32_bf16 v[36:39], v[196:199], v[156:159], v[36:39]
	v_mfma_f32_16x16x32_bf16 v[32:35], v[204:207], v[156:159], v[32:35]
	v_mfma_f32_16x16x32_bf16 v[20:23], v[196:199], v[180:183], v[20:23]
	v_mfma_f32_16x16x32_bf16 v[16:19], v[204:207], v[180:183], v[16:19]
	v_mfma_f32_16x16x32_bf16 v[4:7], v[196:199], v[188:191], v[4:7]
	v_mfma_f32_16x16x32_bf16 v[0:3], v[204:207], v[188:191], v[0:3]
	s_setprio 0
	s_barrier
	v_add_u32_e32 v140, s31, v222
	ds_read_b128 v[128:131], v140
	ds_read_b128 v[132:135], v140 offset:1024
	ds_read_b128 v[136:139], v140 offset:2048
	ds_read_b128 v[140:143], v140 offset:3072
	s_add_u32 s12, s12, s2
	s_addc_u32 s13, s13, s3
	s_mov_b32 m0, s26
	v_lshl_add_u64 v[192:193], s[12:13], 0, v[160:161]
	ds_read_b128 v[144:147], v224 offset:32768
	ds_read_b128 v[148:151], v224 offset:33792
	ds_read_b128 v[152:155], v224 offset:34816
	ds_read_b128 v[156:159], v224 offset:35840
	ds_read_b128 v[176:179], v224 offset:36864
	ds_read_b128 v[180:183], v224 offset:37888
	ds_read_b128 v[184:187], v224 offset:38912
	ds_read_b128 v[188:191], v224 offset:39936
	global_load_lds_dwordx4 v[192:193], off
	v_lshl_add_u64 v[192:193], s[12:13], 0, v[162:163]
	s_mov_b32 m0, s27
	s_nop 0
	global_load_lds_dwordx4 v[192:193], off
	v_add_u32_e32 v168, s61, v222
	ds_read_b128 v[192:195], v168
	ds_read_b128 v[196:199], v168 offset:1024
	ds_read_b128 v[200:203], v168 offset:2048
	ds_read_b128 v[204:207], v168 offset:3072
	s_waitcnt vmcnt(8)
	s_waitcnt lgkmcnt(0)
	s_barrier
	s_setprio 1
	v_mfma_f32_16x16x32_bf16 v[124:127], v[128:131], v[144:147], v[124:127]
	v_mfma_f32_16x16x32_bf16 v[120:123], v[136:139], v[144:147], v[120:123]
	v_mfma_f32_16x16x32_bf16 v[108:111], v[128:131], v[152:155], v[108:111]
	v_mfma_f32_16x16x32_bf16 v[104:107], v[136:139], v[152:155], v[104:107]
	v_mfma_f32_16x16x32_bf16 v[92:95], v[128:131], v[176:179], v[92:95]
	v_mfma_f32_16x16x32_bf16 v[88:91], v[136:139], v[176:179], v[88:91]
	v_mfma_f32_16x16x32_bf16 v[76:79], v[128:131], v[184:187], v[76:79]
	v_mfma_f32_16x16x32_bf16 v[72:75], v[136:139], v[184:187], v[72:75]
	v_mfma_f32_16x16x32_bf16 v[124:127], v[132:135], v[148:151], v[124:127]
	v_mfma_f32_16x16x32_bf16 v[120:123], v[140:143], v[148:151], v[120:123]
	v_mfma_f32_16x16x32_bf16 v[108:111], v[132:135], v[156:159], v[108:111]
	v_mfma_f32_16x16x32_bf16 v[104:107], v[140:143], v[156:159], v[104:107]
	v_mfma_f32_16x16x32_bf16 v[92:95], v[132:135], v[180:183], v[92:95]
	v_mfma_f32_16x16x32_bf16 v[88:91], v[140:143], v[180:183], v[88:91]
	v_mfma_f32_16x16x32_bf16 v[76:79], v[132:135], v[188:191], v[76:79]
	v_mfma_f32_16x16x32_bf16 v[72:75], v[140:143], v[188:191], v[72:75]
	v_mfma_f32_16x16x32_bf16 v[116:119], v[192:195], v[144:147], v[116:119]
	v_mfma_f32_16x16x32_bf16 v[112:115], v[200:203], v[144:147], v[112:115]
	v_mfma_f32_16x16x32_bf16 v[100:103], v[192:195], v[152:155], v[100:103]
	v_mfma_f32_16x16x32_bf16 v[96:99], v[200:203], v[152:155], v[96:99]
	v_mfma_f32_16x16x32_bf16 v[84:87], v[192:195], v[176:179], v[84:87]
	v_mfma_f32_16x16x32_bf16 v[80:83], v[200:203], v[176:179], v[80:83]
	v_mfma_f32_16x16x32_bf16 v[68:71], v[192:195], v[184:187], v[68:71]
	v_mfma_f32_16x16x32_bf16 v[64:67], v[200:203], v[184:187], v[64:67]
	v_mfma_f32_16x16x32_bf16 v[116:119], v[196:199], v[148:151], v[116:119]
	v_mfma_f32_16x16x32_bf16 v[112:115], v[204:207], v[148:151], v[112:115]
	v_mfma_f32_16x16x32_bf16 v[100:103], v[196:199], v[156:159], v[100:103]
	v_mfma_f32_16x16x32_bf16 v[96:99], v[204:207], v[156:159], v[96:99]
	v_mfma_f32_16x16x32_bf16 v[84:87], v[196:199], v[180:183], v[84:87]
	v_mfma_f32_16x16x32_bf16 v[80:83], v[204:207], v[180:183], v[80:83]
	v_mfma_f32_16x16x32_bf16 v[68:71], v[196:199], v[188:191], v[68:71]
	v_mfma_f32_16x16x32_bf16 v[64:67], v[204:207], v[188:191], v[64:67]
	s_setprio 0
	s_barrier
; #define PG8_STAGE(bufoff, gbase) do { _Pragma("unroll") for (int _i = 0; _i < 2; ++_i) \
;         __builtin_amdgcn_global_load_lds((const unsigned*)((const char*)(gbase) + voffA[_i]), (LAS unsigned*)(lds + (bufoff) + ldsw + _i * 8192), 16, 0, 0); } while (0)
; #define PG8_LDA(dst, b, h) do { _Pragma("unroll") for (int m = 0; m < 4; ++m) _Pragma("unroll") for (int k = 0; k < 2; ++k) dst[m][k] = *(const LAS bf16x8*)(lds + PG8_SA(b, h) + aoff + m * 2048 + k * 1024); } while (0)
; #define PG8_MMA(ai, bj, At, Bt) do { __builtin_amdgcn_s_setprio(1); _Pragma("unroll") for (int m = 0; m < 4; ++m) _Pragma("unroll") for (int n = 0; n < 2; ++n) _Pragma("unroll") for (int k = 0; k < 2; ++k) \
;         acc[ai][bj][m][n] = __builtin_amdgcn_mfma_f32_16x16x32_bf16(Bt[n][k], At[m][k], acc[ai][bj][m][n], 0, 0, 0); __builtin_amdgcn_s_setprio(0); } while (0)
; #define PG8_WAIT_V(n) asm volatile("s_waitcnt vmcnt(" #n ")" ::: "memory")
; #define PG8_WAIT_L(n) asm volatile("s_waitcnt lgkmcnt(" #n ")" ::: "memory")
; #define PG8_BAR __builtin_amdgcn_s_barrier()
; #define PG8_SCHED __builtin_amdgcn_sched_barrier(0)
; template <class Epi>
; DI void gemm_phase(const int TID, const int BID, LAS unsigned char* lds, const Gemm g, const Epi& E) {
;     ...
;             PG8_LDA(At, 1, 1); PG8_STAGE(PG8_SA(1, 0), a3);
;             PG8_BAR; PG8_WAIT_L(0); PG8_MMA(1, 0, At, B0); PG8_BAR; PG8_SCHED;
;             PG8_STAGE(PG8_SB(1, 1), b3 + hstep);
;             PG8_WAIT_V(6); PG8_BAR; PG8_MMA(1, 1, At, B1); PG8_BAR;
;         }
	s_mov_b32 m0, s33
	v_lshl_add_u64 v[170:171], v[170:171], 0, s[92:93]
	global_load_lds_dwordx4 v[170:171], off
	v_lshl_add_u64 v[170:171], v[172:173], 0, s[92:93]
	s_mov_b32 m0, s56
	s_nop 0
	global_load_lds_dwordx4 v[170:171], off
	s_mov_b32 m0, s57
	v_lshl_add_u64 v[170:171], v[208:209], 0, s[92:93]
	ds_read_b128 v[144:147], v224 offset:49152
	ds_read_b128 v[148:151], v224 offset:50176
	ds_read_b128 v[152:155], v224 offset:51200
	ds_read_b128 v[156:159], v224 offset:52224
	ds_read_b128 v[176:179], v224 offset:53248
	ds_read_b128 v[180:183], v224 offset:54272
	ds_read_b128 v[184:187], v224 offset:55296
	ds_read_b128 v[188:191], v224 offset:56320
	global_load_lds_dwordx4 v[170:171], off
	v_lshl_add_u64 v[170:171], v[210:211], 0, s[92:93]
	s_mov_b32 m0, s60
	s_nop 0
	global_load_lds_dwordx4 v[170:171], off
	s_mov_b32 m0, s62
	v_lshl_add_u64 v[170:171], v[212:213], 0, s[92:93]
	global_load_lds_dwordx4 v[170:171], off
	v_lshl_add_u64 v[170:171], v[214:215], 0, s[92:93]
	s_mov_b32 m0, s63
	s_nop 0
	global_load_lds_dwordx4 v[170:171], off
	s_waitcnt vmcnt(8)
	s_waitcnt lgkmcnt(0)
	s_barrier
	s_setprio 1
	v_mfma_f32_16x16x32_bf16 v[60:63], v[128:131], v[144:147], v[60:63]
	v_mfma_f32_16x16x32_bf16 v[56:59], v[136:139], v[144:147], v[56:59]
	v_mfma_f32_16x16x32_bf16 v[44:47], v[128:131], v[152:155], v[44:47]
	v_mfma_f32_16x16x32_bf16 v[40:43], v[136:139], v[152:155], v[40:43]
	v_mfma_f32_16x16x32_bf16 v[28:31], v[128:131], v[176:179], v[28:31]
	v_mfma_f32_16x16x32_bf16 v[24:27], v[136:139], v[176:179], v[24:27]
	v_mfma_f32_16x16x32_bf16 v[12:15], v[128:131], v[184:187], v[12:15]
	v_mfma_f32_16x16x32_bf16 v[8:11], v[136:139], v[184:187], v[8:11]
	v_mfma_f32_16x16x32_bf16 v[60:63], v[132:135], v[148:151], v[60:63]
	v_mfma_f32_16x16x32_bf16 v[56:59], v[140:143], v[148:151], v[56:59]
	v_mfma_f32_16x16x32_bf16 v[44:47], v[132:135], v[156:159], v[44:47]
	v_mfma_f32_16x16x32_bf16 v[40:43], v[140:143], v[156:159], v[40:43]
	v_mfma_f32_16x16x32_bf16 v[28:31], v[132:135], v[180:183], v[28:31]
	v_mfma_f32_16x16x32_bf16 v[24:27], v[140:143], v[180:183], v[24:27]
	v_mfma_f32_16x16x32_bf16 v[12:15], v[132:135], v[188:191], v[12:15]
	v_mfma_f32_16x16x32_bf16 v[8:11], v[140:143], v[188:191], v[8:11]
	v_mfma_f32_16x16x32_bf16 v[52:55], v[192:195], v[144:147], v[52:55]
	v_mfma_f32_16x16x32_bf16 v[48:51], v[200:203], v[144:147], v[48:51]
	v_mfma_f32_16x16x32_bf16 v[36:39], v[192:195], v[152:155], v[36:39]
	v_mfma_f32_16x16x32_bf16 v[32:35], v[200:203], v[152:155], v[32:35]
	v_mfma_f32_16x16x32_bf16 v[20:23], v[192:195], v[176:179], v[20:23]
	v_mfma_f32_16x16x32_bf16 v[16:19], v[200:203], v[176:179], v[16:19]
	v_mfma_f32_16x16x32_bf16 v[4:7], v[192:195], v[184:187], v[4:7]
	v_mfma_f32_16x16x32_bf16 v[0:3], v[200:203], v[184:187], v[0:3]
	v_mfma_f32_16x16x32_bf16 v[52:55], v[196:199], v[148:151], v[52:55]
	v_mfma_f32_16x16x32_bf16 v[48:51], v[204:207], v[148:151], v[48:51]
	v_mfma_f32_16x16x32_bf16 v[36:39], v[196:199], v[156:159], v[36:39]
	v_mfma_f32_16x16x32_bf16 v[32:35], v[204:207], v[156:159], v[32:35]
	v_mfma_f32_16x16x32_bf16 v[20:23], v[196:199], v[180:183], v[20:23]
	v_mfma_f32_16x16x32_bf16 v[16:19], v[204:207], v[180:183], v[16:19]
	v_mfma_f32_16x16x32_bf16 v[4:7], v[196:199], v[188:191], v[4:7]
	v_mfma_f32_16x16x32_bf16 v[0:3], v[204:207], v[188:191], v[0:3]
	s_setprio 0
	s_add_u32 s0, s0, 0x100
	s_addc_u32 s1, s1, 0
	s_add_u32 s55, s55, 0x100
	s_addc_u32 vcc_lo, vcc_lo, 0
	s_cmp_ge_i32 vcc_hi, s80
	s_mov_b32 s12, vcc_hi
	s_barrier
	s_cbranch_scc0 .LBB0_271
	s_branch .LBB0_275

; #define PG8_STAGE(bufoff, gbase) do { _Pragma("unroll") for (int _i = 0; _i < 2; ++_i) \
;         __builtin_amdgcn_global_load_lds((const unsigned*)((const char*)(gbase) + voffA[_i]), (LAS unsigned*)(lds + (bufoff) + ldsw + _i * 8192), 16, 0, 0); } while (0)
; #define PG8_LDA(dst, b, h) do { _Pragma("unroll") for (int m = 0; m < 4; ++m) _Pragma("unroll") for (int k = 0; k < 2; ++k) dst[m][k] = *(const LAS bf16x8*)(lds + PG8_SA(b, h) + aoff + m * 2048 + k * 1024); } while (0)
; #define PG8_LDB(dst, b, h) do { _Pragma("unroll") for (int n = 0; n < 2; ++n) _Pragma("unroll") for (int k = 0; k < 2; ++k) dst[n][k] = *(const LAS bf16x8*)(lds + PG8_SB(b, h) + boff + n * 2048 + k * 1024); } while (0)
; #define PG8_MMA(ai, bj, At, Bt) do { __builtin_amdgcn_s_setprio(1); _Pragma("unroll") for (int m = 0; m < 4; ++m) _Pragma("unroll") for (int n = 0; n < 2; ++n) _Pragma("unroll") for (int k = 0; k < 2; ++k) \
;         acc[ai][bj][m][n] = __builtin_amdgcn_mfma_f32_16x16x32_bf16(Bt[n][k], At[m][k], acc[ai][bj][m][n], 0, 0, 0); __builtin_amdgcn_s_setprio(0); } while (0)
; #define PG8_WAIT_V(n) asm volatile("s_waitcnt vmcnt(" #n ")" ::: "memory")
; #define PG8_WAIT_L(n) asm volatile("s_waitcnt lgkmcnt(" #n ")" ::: "memory")
; #define PG8_BAR __builtin_amdgcn_s_barrier()
; #define PG8_SCHED __builtin_amdgcn_sched_barrier(0)
; template <class Epi>
; DI void gemm_phase(const int TID, const int BID, LAS unsigned char* lds, const Gemm g, const Epi& E) {
;     ...
;             PG8_LDB(B0, 0, 0); PG8_SCHED; PG8_LDA(At, 0, 0); PG8_STAGE(PG8_SA(1, 1), a1 + hstep);
;             PG8_WAIT_L(8); PG8_BAR; PG8_WAIT_L(0); PG8_MMA(0, 0, At, B0); PG8_BAR; PG8_SCHED;
;             PG8_LDB(B1, 0, 1); PG8_STAGE(PG8_SB(0, 0), b2);
;             PG8_BAR; PG8_WAIT_L(0); PG8_MMA(0, 1, At, B1); PG8_BAR;
;             PG8_LDA(At, 0, 1); PG8_STAGE(PG8_SA(0, 0), a2);
;             PG8_BAR; PG8_WAIT_L(0); PG8_MMA(1, 0, At, B0); PG8_BAR; PG8_SCHED;
;             PG8_STAGE(PG8_SB(0, 1), b2 + hstep);
;             PG8_WAIT_V(6); PG8_BAR; PG8_MMA(1, 1, At, B1); PG8_BAR;
.LBB0_359:
	v_add_u32_e32 v140, s19, v192
	ds_read_b128 v[128:131], v140
	ds_read_b128 v[132:135], v140 offset:1024
	ds_read_b128 v[136:139], v140 offset:2048
	ds_read_b128 v[140:143], v140 offset:3072
	s_add_i32 s17, s8, 2
	s_add_u32 s10, s6, 0x80
	s_addc_u32 s9, s7, 0
	s_cmp_eq_u32 s16, s8
	s_cselect_b32 s8, s60, s10
	s_cselect_b32 s9, s61, s9
	s_cselect_b32 s11, s63, s13
	s_cselect_b32 s10, s62, s12
	v_lshl_add_u64 v[170:171], s[6:7], 0, v[176:177]
	s_add_i32 m0, s22, 0xc000
	ds_read_b128 v[144:147], v203
	ds_read_b128 v[148:151], v203 offset:1024
	ds_read_b128 v[152:155], v203 offset:2048
	ds_read_b128 v[204:207], v203 offset:3072
	ds_read_b128 v[208:211], v203 offset:4096
	ds_read_b128 v[212:215], v203 offset:5120
	ds_read_b128 v[216:219], v203 offset:6144
	ds_read_b128 v[220:223], v203 offset:7168
	global_load_lds_dwordx4 v[170:171], off
	v_lshl_add_u64 v[170:171], s[6:7], 0, v[178:179]
	s_add_i32 m0, s22, 0xe000
	s_nop 0
	global_load_lds_dwordx4 v[170:171], off
	v_add_u32_e32 v168, s24, v192
	ds_read_b128 v[224:227], v168
	ds_read_b128 v[228:231], v168 offset:1024
	ds_read_b128 v[246:249], v168 offset:2048
	ds_read_b128 v[232:235], v168 offset:3072
	s_waitcnt vmcnt(8)
	s_waitcnt lgkmcnt(0)
	s_barrier
	s_setprio 1
	v_mfma_f32_16x16x32_bf16 v[124:127], v[128:131], v[144:147], v[124:127]
	v_mfma_f32_16x16x32_bf16 v[120:123], v[136:139], v[144:147], v[120:123]
	v_mfma_f32_16x16x32_bf16 v[108:111], v[128:131], v[152:155], v[108:111]
	v_mfma_f32_16x16x32_bf16 v[104:107], v[136:139], v[152:155], v[104:107]
	v_mfma_f32_16x16x32_bf16 v[92:95], v[128:131], v[208:211], v[92:95]
	v_mfma_f32_16x16x32_bf16 v[88:91], v[136:139], v[208:211], v[88:91]
	v_mfma_f32_16x16x32_bf16 v[76:79], v[128:131], v[216:219], v[76:79]
	v_mfma_f32_16x16x32_bf16 v[72:75], v[136:139], v[216:219], v[72:75]
	v_mfma_f32_16x16x32_bf16 v[124:127], v[132:135], v[148:151], v[124:127]
	v_mfma_f32_16x16x32_bf16 v[120:123], v[140:143], v[148:151], v[120:123]
	v_mfma_f32_16x16x32_bf16 v[108:111], v[132:135], v[204:207], v[108:111]
	v_mfma_f32_16x16x32_bf16 v[104:107], v[140:143], v[204:207], v[104:107]
	v_mfma_f32_16x16x32_bf16 v[92:95], v[132:135], v[212:215], v[92:95]
	v_mfma_f32_16x16x32_bf16 v[88:91], v[140:143], v[212:215], v[88:91]
	v_mfma_f32_16x16x32_bf16 v[76:79], v[132:135], v[220:223], v[76:79]
	v_mfma_f32_16x16x32_bf16 v[72:75], v[140:143], v[220:223], v[72:75]
	v_mfma_f32_16x16x32_bf16 v[116:119], v[224:227], v[144:147], v[116:119]
	v_mfma_f32_16x16x32_bf16 v[112:115], v[246:249], v[144:147], v[112:115]
	v_mfma_f32_16x16x32_bf16 v[100:103], v[224:227], v[152:155], v[100:103]
	v_mfma_f32_16x16x32_bf16 v[96:99], v[246:249], v[152:155], v[96:99]
	v_mfma_f32_16x16x32_bf16 v[84:87], v[224:227], v[208:211], v[84:87]
	v_mfma_f32_16x16x32_bf16 v[80:83], v[246:249], v[208:211], v[80:83]
	v_mfma_f32_16x16x32_bf16 v[68:71], v[224:227], v[216:219], v[68:71]
	v_mfma_f32_16x16x32_bf16 v[64:67], v[246:249], v[216:219], v[64:67]
	v_mfma_f32_16x16x32_bf16 v[116:119], v[228:231], v[148:151], v[116:119]
	v_mfma_f32_16x16x32_bf16 v[112:115], v[232:235], v[148:151], v[112:115]
	v_mfma_f32_16x16x32_bf16 v[100:103], v[228:231], v[204:207], v[100:103]
	v_mfma_f32_16x16x32_bf16 v[96:99], v[232:235], v[204:207], v[96:99]
	v_mfma_f32_16x16x32_bf16 v[84:87], v[228:231], v[212:215], v[84:87]
	v_mfma_f32_16x16x32_bf16 v[80:83], v[232:235], v[212:215], v[80:83]
	v_mfma_f32_16x16x32_bf16 v[68:71], v[228:231], v[220:223], v[68:71]
	v_mfma_f32_16x16x32_bf16 v[64:67], v[232:235], v[220:223], v[64:67]
	s_setprio 0
	s_barrier
	s_mov_b32 m0, s20
	v_lshl_add_u64 v[170:171], s[10:11], 0, v[158:159]
	global_load_lds_dwordx4 v[170:171], off
	v_lshl_add_u64 v[172:173], s[10:11], 0, v[160:161]
	s_mov_b32 m0, s21
	s_nop 0
	global_load_lds_dwordx4 v[172:173], off
	s_mov_b32 m0, s22
	v_lshl_add_u64 v[180:181], s[8:9], 0, v[158:159]
	ds_read_b128 v[144:147], v203 offset:16384
	ds_read_b128 v[148:151], v203 offset:17408
	ds_read_b128 v[152:155], v203 offset:18432
	ds_read_b128 v[204:207], v203 offset:19456
	ds_read_b128 v[208:211], v203 offset:20480
	ds_read_b128 v[212:215], v203 offset:21504
	ds_read_b128 v[216:219], v203 offset:22528
	ds_read_b128 v[220:223], v203 offset:23552
	global_load_lds_dwordx4 v[180:181], off
	v_lshl_add_u64 v[236:237], s[8:9], 0, v[160:161]
	s_mov_b32 m0, s23
	s_nop 0
	global_load_lds_dwordx4 v[236:237], off
	s_add_u32 s10, s10, s52
	s_addc_u32 s11, s11, s53
	s_mov_b32 m0, s25
	v_lshl_add_u64 v[238:239], s[10:11], 0, v[158:159]
	global_load_lds_dwordx4 v[238:239], off
	v_lshl_add_u64 v[184:185], s[10:11], 0, v[160:161]
	s_mov_b32 m0, s26
	s_nop 0
	global_load_lds_dwordx4 v[184:185], off
	s_waitcnt vmcnt(8)
	s_waitcnt lgkmcnt(0)
	s_barrier
; #define PG8_STAGE(bufoff, gbase) do { _Pragma("unroll") for (int _i = 0; _i < 2; ++_i) \
;         __builtin_amdgcn_global_load_lds((const unsigned*)((const char*)(gbase) + voffA[_i]), (LAS unsigned*)(lds + (bufoff) + ldsw + _i * 8192), 16, 0, 0); } while (0)
; #define PG8_LDA(dst, b, h) do { _Pragma("unroll") for (int m = 0; m < 4; ++m) _Pragma("unroll") for (int k = 0; k < 2; ++k) dst[m][k] = *(const LAS bf16x8*)(lds + PG8_SA(b, h) + aoff + m * 2048 + k * 1024); } while (0)
; #define PG8_LDB(dst, b, h) do { _Pragma("unroll") for (int n = 0; n < 2; ++n) _Pragma("unroll") for (int k = 0; k < 2; ++k) dst[n][k] = *(const LAS bf16x8*)(lds + PG8_SB(b, h) + boff + n * 2048 + k * 1024); } while (0)
; #define PG8_MMA(ai, bj, At, Bt) do { __builtin_amdgcn_s_setprio(1); _Pragma("unroll") for (int m = 0; m < 4; ++m) _Pragma("unroll") for (int n = 0; n < 2; ++n) _Pragma("unroll") for (int k = 0; k < 2; ++k) \
;         acc[ai][bj][m][n] = __builtin_amdgcn_mfma_f32_16x16x32_bf16(Bt[n][k], At[m][k], acc[ai][bj][m][n], 0, 0, 0); __builtin_amdgcn_s_setprio(0); } while (0)
; #define PG8_WAIT_V(n) asm volatile("s_waitcnt vmcnt(" #n ")" ::: "memory")
; #define PG8_WAIT_L(n) asm volatile("s_waitcnt lgkmcnt(" #n ")" ::: "memory")
; #define PG8_BAR __builtin_amdgcn_s_barrier()
; #define PG8_SCHED __builtin_amdgcn_sched_barrier(0)
; template <class Epi>
; DI void gemm_phase(const int TID, const int BID, LAS unsigned char* lds, const Gemm g, const Epi& E) {
;     ...
;             PG8_BAR; PG8_WAIT_L(0); PG8_MMA(1, 0, At, B0); PG8_BAR; PG8_SCHED;
;             PG8_STAGE(PG8_SB(0, 1), b2 + hstep);
;             PG8_WAIT_V(6); PG8_BAR; PG8_MMA(1, 1, At, B1); PG8_BAR;
;             PG8_LDB(B0, 1, 0); PG8_SCHED; PG8_LDA(At, 1, 0); PG8_STAGE(PG8_SA(0, 1), a2 + hstep);
;             PG8_WAIT_L(8); PG8_BAR; PG8_WAIT_L(0); PG8_MMA(0, 0, At, B0); PG8_BAR; PG8_SCHED;
;             PG8_LDB(B1, 1, 1); PG8_STAGE(PG8_SB(1, 0), b3);
;             PG8_BAR; PG8_WAIT_L(0); PG8_MMA(0, 1, At, B1); PG8_BAR;
	s_setprio 1
	v_mfma_f32_16x16x32_bf16 v[60:63], v[128:131], v[144:147], v[60:63]
	v_mfma_f32_16x16x32_bf16 v[56:59], v[136:139], v[144:147], v[56:59]
	v_mfma_f32_16x16x32_bf16 v[44:47], v[128:131], v[152:155], v[44:47]
	v_mfma_f32_16x16x32_bf16 v[40:43], v[136:139], v[152:155], v[40:43]
	v_mfma_f32_16x16x32_bf16 v[28:31], v[128:131], v[208:211], v[28:31]
	v_mfma_f32_16x16x32_bf16 v[24:27], v[136:139], v[208:211], v[24:27]
	v_mfma_f32_16x16x32_bf16 v[12:15], v[128:131], v[216:219], v[12:15]
	v_mfma_f32_16x16x32_bf16 v[8:11], v[136:139], v[216:219], v[8:11]
	v_mfma_f32_16x16x32_bf16 v[60:63], v[132:135], v[148:151], v[60:63]
	v_mfma_f32_16x16x32_bf16 v[56:59], v[140:143], v[148:151], v[56:59]
	v_mfma_f32_16x16x32_bf16 v[44:47], v[132:135], v[204:207], v[44:47]
	v_mfma_f32_16x16x32_bf16 v[40:43], v[140:143], v[204:207], v[40:43]
	v_mfma_f32_16x16x32_bf16 v[28:31], v[132:135], v[212:215], v[28:31]
	v_mfma_f32_16x16x32_bf16 v[24:27], v[140:143], v[212:215], v[24:27]
	v_mfma_f32_16x16x32_bf16 v[12:15], v[132:135], v[220:223], v[12:15]
	v_mfma_f32_16x16x32_bf16 v[8:11], v[140:143], v[220:223], v[8:11]
	v_mfma_f32_16x16x32_bf16 v[52:55], v[224:227], v[144:147], v[52:55]
	v_mfma_f32_16x16x32_bf16 v[48:51], v[246:249], v[144:147], v[48:51]
	v_mfma_f32_16x16x32_bf16 v[36:39], v[224:227], v[152:155], v[36:39]
	v_mfma_f32_16x16x32_bf16 v[32:35], v[246:249], v[152:155], v[32:35]
	v_mfma_f32_16x16x32_bf16 v[20:23], v[224:227], v[208:211], v[20:23]
	v_mfma_f32_16x16x32_bf16 v[16:19], v[246:249], v[208:211], v[16:19]
	v_mfma_f32_16x16x32_bf16 v[4:7], v[224:227], v[216:219], v[4:7]
	v_mfma_f32_16x16x32_bf16 v[0:3], v[246:249], v[216:219], v[0:3]
	v_mfma_f32_16x16x32_bf16 v[52:55], v[228:231], v[148:151], v[52:55]
	v_mfma_f32_16x16x32_bf16 v[48:51], v[232:235], v[148:151], v[48:51]
	v_mfma_f32_16x16x32_bf16 v[36:39], v[228:231], v[204:207], v[36:39]
	v_mfma_f32_16x16x32_bf16 v[32:35], v[232:235], v[204:207], v[32:35]
	v_mfma_f32_16x16x32_bf16 v[20:23], v[228:231], v[212:215], v[20:23]
	v_mfma_f32_16x16x32_bf16 v[16:19], v[232:235], v[212:215], v[16:19]
	v_mfma_f32_16x16x32_bf16 v[4:7], v[228:231], v[220:223], v[4:7]
	v_mfma_f32_16x16x32_bf16 v[0:3], v[232:235], v[220:223], v[0:3]
	s_setprio 0
	s_barrier
	v_add_u32_e32 v140, s29, v192
	ds_read_b128 v[128:131], v140
	ds_read_b128 v[132:135], v140 offset:1024
	ds_read_b128 v[136:139], v140 offset:2048
	ds_read_b128 v[140:143], v140 offset:3072
	s_add_u32 s8, s8, s52
	s_addc_u32 s9, s9, s53
	s_mov_b32 m0, s27
	v_lshl_add_u64 v[224:225], s[8:9], 0, v[158:159]
	ds_read_b128 v[144:147], v203 offset:32768
	ds_read_b128 v[148:151], v203 offset:33792
	ds_read_b128 v[152:155], v203 offset:34816
	ds_read_b128 v[204:207], v203 offset:35840
	ds_read_b128 v[208:211], v203 offset:36864
	ds_read_b128 v[212:215], v203 offset:37888
	ds_read_b128 v[216:219], v203 offset:38912
	ds_read_b128 v[220:223], v203 offset:39936
	global_load_lds_dwordx4 v[224:225], off
	v_lshl_add_u64 v[224:225], s[8:9], 0, v[160:161]
	s_mov_b32 m0, s28
	s_nop 0
	global_load_lds_dwordx4 v[224:225], off
	v_add_u32_e32 v168, s77, v192
	ds_read_b128 v[224:227], v168
	ds_read_b128 v[228:231], v168 offset:1024
	ds_read_b128 v[232:235], v168 offset:2048
	ds_read_b128 v[246:249], v168 offset:3072
	s_waitcnt vmcnt(8)
	s_waitcnt lgkmcnt(0)
	s_barrier
	s_setprio 1
	v_mfma_f32_16x16x32_bf16 v[124:127], v[128:131], v[144:147], v[124:127]
	v_mfma_f32_16x16x32_bf16 v[120:123], v[136:139], v[144:147], v[120:123]
	v_mfma_f32_16x16x32_bf16 v[108:111], v[128:131], v[152:155], v[108:111]
	v_mfma_f32_16x16x32_bf16 v[104:107], v[136:139], v[152:155], v[104:107]
	v_mfma_f32_16x16x32_bf16 v[92:95], v[128:131], v[208:211], v[92:95]
	v_mfma_f32_16x16x32_bf16 v[88:91], v[136:139], v[208:211], v[88:91]
	v_mfma_f32_16x16x32_bf16 v[76:79], v[128:131], v[216:219], v[76:79]
	v_mfma_f32_16x16x32_bf16 v[72:75], v[136:139], v[216:219], v[72:75]
	v_mfma_f32_16x16x32_bf16 v[124:127], v[132:135], v[148:151], v[124:127]
	v_mfma_f32_16x16x32_bf16 v[120:123], v[140:143], v[148:151], v[120:123]
	v_mfma_f32_16x16x32_bf16 v[108:111], v[132:135], v[204:207], v[108:111]
	v_mfma_f32_16x16x32_bf16 v[104:107], v[140:143], v[204:207], v[104:107]
	v_mfma_f32_16x16x32_bf16 v[92:95], v[132:135], v[212:215], v[92:95]
	v_mfma_f32_16x16x32_bf16 v[88:91], v[140:143], v[212:215], v[88:91]
	v_mfma_f32_16x16x32_bf16 v[76:79], v[132:135], v[220:223], v[76:79]
	v_mfma_f32_16x16x32_bf16 v[72:75], v[140:143], v[220:223], v[72:75]
	v_mfma_f32_16x16x32_bf16 v[116:119], v[224:227], v[144:147], v[116:119]
	v_mfma_f32_16x16x32_bf16 v[112:115], v[232:235], v[144:147], v[112:115]
	v_mfma_f32_16x16x32_bf16 v[100:103], v[224:227], v[152:155], v[100:103]
	v_mfma_f32_16x16x32_bf16 v[96:99], v[232:235], v[152:155], v[96:99]
	v_mfma_f32_16x16x32_bf16 v[84:87], v[224:227], v[208:211], v[84:87]
	v_mfma_f32_16x16x32_bf16 v[80:83], v[232:235], v[208:211], v[80:83]
	v_mfma_f32_16x16x32_bf16 v[68:71], v[224:227], v[216:219], v[68:71]
	v_mfma_f32_16x16x32_bf16 v[64:67], v[232:235], v[216:219], v[64:67]
	v_mfma_f32_16x16x32_bf16 v[116:119], v[228:231], v[148:151], v[116:119]
	v_mfma_f32_16x16x32_bf16 v[112:115], v[246:249], v[148:151], v[112:115]
	v_mfma_f32_16x16x32_bf16 v[100:103], v[228:231], v[204:207], v[100:103]
	v_mfma_f32_16x16x32_bf16 v[96:99], v[246:249], v[204:207], v[96:99]
	v_mfma_f32_16x16x32_bf16 v[84:87], v[228:231], v[212:215], v[84:87]
	v_mfma_f32_16x16x32_bf16 v[80:83], v[246:249], v[212:215], v[80:83]
	v_mfma_f32_16x16x32_bf16 v[68:71], v[228:231], v[220:223], v[68:71]
	v_mfma_f32_16x16x32_bf16 v[64:67], v[246:249], v[220:223], v[64:67]
	s_setprio 0
	s_barrier
; #define PG8_STAGE(bufoff, gbase) do { _Pragma("unroll") for (int _i = 0; _i < 2; ++_i) \
;         __builtin_amdgcn_global_load_lds((const unsigned*)((const char*)(gbase) + voffA[_i]), (LAS unsigned*)(lds + (bufoff) + ldsw + _i * 8192), 16, 0, 0); } while (0)
; #define PG8_LDA(dst, b, h) do { _Pragma("unroll") for (int m = 0; m < 4; ++m) _Pragma("unroll") for (int k = 0; k < 2; ++k) dst[m][k] = *(const LAS bf16x8*)(lds + PG8_SA(b, h) + aoff + m * 2048 + k * 1024); } while (0)
; #define PG8_MMA(ai, bj, At, Bt) do { __builtin_amdgcn_s_setprio(1); _Pragma("unroll") for (int m = 0; m < 4; ++m) _Pragma("unroll") for (int n = 0; n < 2; ++n) _Pragma("unroll") for (int k = 0; k < 2; ++k) \
;         acc[ai][bj][m][n] = __builtin_amdgcn_mfma_f32_16x16x32_bf16(Bt[n][k], At[m][k], acc[ai][bj][m][n], 0, 0, 0); __builtin_amdgcn_s_setprio(0); } while (0)
; #define PG8_WAIT_V(n) asm volatile("s_waitcnt vmcnt(" #n ")" ::: "memory")
; #define PG8_WAIT_L(n) asm volatile("s_waitcnt lgkmcnt(" #n ")" ::: "memory")
; #define PG8_BAR __builtin_amdgcn_s_barrier()
; #define PG8_SCHED __builtin_amdgcn_sched_barrier(0)
; template <class Epi>
; DI void gemm_phase(const int TID, const int BID, LAS unsigned char* lds, const Gemm g, const Epi& E) {
;     ...
;             PG8_LDA(At, 1, 1); PG8_STAGE(PG8_SA(1, 0), a3);
;             PG8_BAR; PG8_WAIT_L(0); PG8_MMA(1, 0, At, B0); PG8_BAR; PG8_SCHED;
;             PG8_STAGE(PG8_SB(1, 1), b3 + hstep);
;             PG8_WAIT_V(6); PG8_BAR; PG8_MMA(1, 1, At, B1); PG8_BAR;
;         }
	s_mov_b32 m0, s30
	v_lshl_add_u64 v[170:171], v[170:171], 0, s[92:93]
	global_load_lds_dwordx4 v[170:171], off
	v_lshl_add_u64 v[170:171], v[172:173], 0, s[92:93]
	s_mov_b32 m0, s31
	s_nop 0
	global_load_lds_dwordx4 v[170:171], off
	s_mov_b32 m0, s33
	v_lshl_add_u64 v[170:171], v[180:181], 0, s[92:93]
	ds_read_b128 v[144:147], v203 offset:49152
	ds_read_b128 v[148:151], v203 offset:50176
	ds_read_b128 v[152:155], v203 offset:51200
	ds_read_b128 v[204:207], v203 offset:52224
	ds_read_b128 v[208:211], v203 offset:53248
	ds_read_b128 v[212:215], v203 offset:54272
	ds_read_b128 v[216:219], v203 offset:55296
	ds_read_b128 v[220:223], v203 offset:56320
	global_load_lds_dwordx4 v[170:171], off
	v_lshl_add_u64 v[170:171], v[236:237], 0, s[92:93]
	s_mov_b32 m0, s76
	s_nop 0
	global_load_lds_dwordx4 v[170:171], off
	s_mov_b32 m0, s80
	v_lshl_add_u64 v[170:171], v[238:239], 0, s[92:93]
	global_load_lds_dwordx4 v[170:171], off
	v_lshl_add_u64 v[170:171], v[184:185], 0, s[92:93]
	s_mov_b32 m0, s81
	s_nop 0
	global_load_lds_dwordx4 v[170:171], off
	s_waitcnt vmcnt(8)
	s_waitcnt lgkmcnt(0)
	s_barrier
	s_setprio 1
	v_mfma_f32_16x16x32_bf16 v[60:63], v[128:131], v[144:147], v[60:63]
	v_mfma_f32_16x16x32_bf16 v[56:59], v[136:139], v[144:147], v[56:59]
	v_mfma_f32_16x16x32_bf16 v[44:47], v[128:131], v[152:155], v[44:47]
	v_mfma_f32_16x16x32_bf16 v[40:43], v[136:139], v[152:155], v[40:43]
	v_mfma_f32_16x16x32_bf16 v[28:31], v[128:131], v[208:211], v[28:31]
	v_mfma_f32_16x16x32_bf16 v[24:27], v[136:139], v[208:211], v[24:27]
	v_mfma_f32_16x16x32_bf16 v[12:15], v[128:131], v[216:219], v[12:15]
	v_mfma_f32_16x16x32_bf16 v[8:11], v[136:139], v[216:219], v[8:11]
	v_mfma_f32_16x16x32_bf16 v[60:63], v[132:135], v[148:151], v[60:63]
	v_mfma_f32_16x16x32_bf16 v[56:59], v[140:143], v[148:151], v[56:59]
	v_mfma_f32_16x16x32_bf16 v[44:47], v[132:135], v[204:207], v[44:47]
	v_mfma_f32_16x16x32_bf16 v[40:43], v[140:143], v[204:207], v[40:43]
	v_mfma_f32_16x16x32_bf16 v[28:31], v[132:135], v[212:215], v[28:31]
	v_mfma_f32_16x16x32_bf16 v[24:27], v[140:143], v[212:215], v[24:27]
	v_mfma_f32_16x16x32_bf16 v[12:15], v[132:135], v[220:223], v[12:15]
	v_mfma_f32_16x16x32_bf16 v[8:11], v[140:143], v[220:223], v[8:11]
	v_mfma_f32_16x16x32_bf16 v[52:55], v[224:227], v[144:147], v[52:55]
	v_mfma_f32_16x16x32_bf16 v[48:51], v[232:235], v[144:147], v[48:51]
	v_mfma_f32_16x16x32_bf16 v[36:39], v[224:227], v[152:155], v[36:39]
	v_mfma_f32_16x16x32_bf16 v[32:35], v[232:235], v[152:155], v[32:35]
	v_mfma_f32_16x16x32_bf16 v[20:23], v[224:227], v[208:211], v[20:23]
	v_mfma_f32_16x16x32_bf16 v[16:19], v[232:235], v[208:211], v[16:19]
	v_mfma_f32_16x16x32_bf16 v[4:7], v[224:227], v[216:219], v[4:7]
	v_mfma_f32_16x16x32_bf16 v[0:3], v[232:235], v[216:219], v[0:3]
	v_mfma_f32_16x16x32_bf16 v[52:55], v[228:231], v[148:151], v[52:55]
	v_mfma_f32_16x16x32_bf16 v[48:51], v[246:249], v[148:151], v[48:51]
	v_mfma_f32_16x16x32_bf16 v[36:39], v[228:231], v[204:207], v[36:39]
	v_mfma_f32_16x16x32_bf16 v[32:35], v[246:249], v[204:207], v[32:35]
	v_mfma_f32_16x16x32_bf16 v[20:23], v[228:231], v[212:215], v[20:23]
	v_mfma_f32_16x16x32_bf16 v[16:19], v[246:249], v[212:215], v[16:19]
	v_mfma_f32_16x16x32_bf16 v[4:7], v[228:231], v[220:223], v[4:7]
	v_mfma_f32_16x16x32_bf16 v[0:3], v[246:249], v[220:223], v[0:3]
	s_setprio 0
	s_add_u32 s6, s6, 0x100
	s_addc_u32 s7, s7, 0
	s_add_u32 s12, s12, 0x100
	s_addc_u32 s13, s13, 0
	s_cmp_ge_i32 s17, s18
	s_mov_b32 s8, s17
	s_barrier
	s_cbranch_scc0 .LBB0_359

; #define PG8_STAGE(bufoff, gbase) do { _Pragma("unroll") for (int _i = 0; _i < 2; ++_i) \
;         __builtin_amdgcn_global_load_lds((const unsigned*)((const char*)(gbase) + voffA[_i]), (LAS unsigned*)(lds + (bufoff) + ldsw + _i * 8192), 16, 0, 0); } while (0)
; #define PG8_LDA(dst, b, h) do { _Pragma("unroll") for (int m = 0; m < 4; ++m) _Pragma("unroll") for (int k = 0; k < 2; ++k) dst[m][k] = *(const LAS bf16x8*)(lds + PG8_SA(b, h) + aoff + m * 2048 + k * 1024); } while (0)
; #define PG8_LDB(dst, b, h) do { _Pragma("unroll") for (int n = 0; n < 2; ++n) _Pragma("unroll") for (int k = 0; k < 2; ++k) dst[n][k] = *(const LAS bf16x8*)(lds + PG8_SB(b, h) + boff + n * 2048 + k * 1024); } while (0)
; #define PG8_MMA(ai, bj, At, Bt) do { __builtin_amdgcn_s_setprio(1); _Pragma("unroll") for (int m = 0; m < 4; ++m) _Pragma("unroll") for (int n = 0; n < 2; ++n) _Pragma("unroll") for (int k = 0; k < 2; ++k) \
;         acc[ai][bj][m][n] = __builtin_amdgcn_mfma_f32_16x16x32_bf16(Bt[n][k], At[m][k], acc[ai][bj][m][n], 0, 0, 0); __builtin_amdgcn_s_setprio(0); } while (0)
; #define PG8_WAIT_L(n) asm volatile("s_waitcnt lgkmcnt(" #n ")" ::: "memory")
; #define PG8_BAR __builtin_amdgcn_s_barrier()
; #define PG8_SCHED __builtin_amdgcn_sched_barrier(0)
; template <class Epi>
; DI void gemm_phase(const int TID, const int BID, LAS unsigned char* lds, const Gemm g, const Epi& E) {
;     ...
;             const bool last = (t == nt - 2);
;             const char* a1 = cA + (size_t)(t + 1) * kstep;
;             const char* a2 = last ? nA : cA + (size_t)(t + 2) * kstep; const char* b2 = last ? nB : cB + (size_t)(t + 2) * kstep;
;             const char* a3 = a2 + kstep; const char* b3 = b2 + kstep;
;             PG8_LDB(B0, 0, 0); PG8_SCHED; PG8_LDA(At, 0, 0); PG8_STAGE(PG8_SA(1, 1), a1 + hstep);
;             PG8_WAIT_L(8); PG8_BAR; PG8_WAIT_L(0); PG8_MMA(0, 0, At, B0); PG8_BAR; PG8_SCHED;
;             PG8_LDB(B1, 0, 1); PG8_STAGE(PG8_SB(0, 0), b2);
;             PG8_BAR; PG8_WAIT_L(0); PG8_MMA(0, 1, At, B1); PG8_BAR;
;             PG8_LDA(At, 0, 1); PG8_STAGE(PG8_SA(0, 0), a2);
;             PG8_BAR; PG8_WAIT_L(0); PG8_MMA(1, 0, At, B0); PG8_BAR; PG8_SCHED;
;             PG8_STAGE(PG8_SB(0, 1), b2 + hstep);
.LBB0_491:
	v_add_u32_e32 v140, s18, v192
	ds_read_b128 v[128:131], v140
	ds_read_b128 v[132:135], v140 offset:1024
	ds_read_b128 v[136:139], v140 offset:2048
	ds_read_b128 v[140:143], v140 offset:3072
	s_add_i32 s16, s60, 2
	s_add_u32 s62, s4, 0x80
	s_addc_u32 s61, s5, 0
	s_cmp_eq_u32 s76, s60
	s_cselect_b32 s60, s56, s62
	s_cselect_b32 s61, s57, s61
	s_cselect_b32 s63, s59, vcc_hi
	s_cselect_b32 s62, s58, vcc_lo
	v_lshl_add_u64 v[156:157], s[4:5], 0, v[188:189]
	s_add_i32 m0, s21, 0xc000
	ds_read_b128 v[144:147], v175
	ds_read_b128 v[148:151], v175 offset:1024
	ds_read_b128 v[152:155], v175 offset:2048
	ds_read_b128 v[196:199], v175 offset:3072
	ds_read_b128 v[200:203], v175 offset:4096
	ds_read_b128 v[204:207], v175 offset:5120
	ds_read_b128 v[208:211], v175 offset:6144
	ds_read_b128 v[212:215], v175 offset:7168
	global_load_lds_dwordx4 v[156:157], off
	v_lshl_add_u64 v[156:157], s[4:5], 0, v[190:191]
	s_add_i32 m0, s21, 0xe000
	s_nop 0
	global_load_lds_dwordx4 v[156:157], off
	v_add_u32_e32 v156, s23, v192
	ds_read_b128 v[216:219], v156
	ds_read_b128 v[220:223], v156 offset:1024
	ds_read_b128 v[224:227], v156 offset:2048
	ds_read_b128 v[228:231], v156 offset:3072
	s_waitcnt vmcnt(8)
	s_waitcnt lgkmcnt(0)
	s_barrier
	s_setprio 1
	v_mfma_f32_16x16x32_bf16 v[124:127], v[128:131], v[144:147], v[124:127]
	v_mfma_f32_16x16x32_bf16 v[120:123], v[136:139], v[144:147], v[120:123]
	v_mfma_f32_16x16x32_bf16 v[108:111], v[128:131], v[152:155], v[108:111]
	v_mfma_f32_16x16x32_bf16 v[104:107], v[136:139], v[152:155], v[104:107]
	v_mfma_f32_16x16x32_bf16 v[92:95], v[128:131], v[200:203], v[92:95]
	v_mfma_f32_16x16x32_bf16 v[88:91], v[136:139], v[200:203], v[88:91]
	v_mfma_f32_16x16x32_bf16 v[76:79], v[128:131], v[208:211], v[76:79]
	v_mfma_f32_16x16x32_bf16 v[72:75], v[136:139], v[208:211], v[72:75]
	v_mfma_f32_16x16x32_bf16 v[124:127], v[132:135], v[148:151], v[124:127]
	v_mfma_f32_16x16x32_bf16 v[120:123], v[140:143], v[148:151], v[120:123]
	v_mfma_f32_16x16x32_bf16 v[108:111], v[132:135], v[196:199], v[108:111]
	v_mfma_f32_16x16x32_bf16 v[104:107], v[140:143], v[196:199], v[104:107]
	v_mfma_f32_16x16x32_bf16 v[92:95], v[132:135], v[204:207], v[92:95]
	v_mfma_f32_16x16x32_bf16 v[88:91], v[140:143], v[204:207], v[88:91]
	v_mfma_f32_16x16x32_bf16 v[76:79], v[132:135], v[212:215], v[76:79]
	v_mfma_f32_16x16x32_bf16 v[72:75], v[140:143], v[212:215], v[72:75]
	v_mfma_f32_16x16x32_bf16 v[116:119], v[216:219], v[144:147], v[116:119]
	v_mfma_f32_16x16x32_bf16 v[112:115], v[224:227], v[144:147], v[112:115]
	v_mfma_f32_16x16x32_bf16 v[100:103], v[216:219], v[152:155], v[100:103]
	v_mfma_f32_16x16x32_bf16 v[96:99], v[224:227], v[152:155], v[96:99]
	v_mfma_f32_16x16x32_bf16 v[84:87], v[216:219], v[200:203], v[84:87]
	v_mfma_f32_16x16x32_bf16 v[80:83], v[224:227], v[200:203], v[80:83]
	v_mfma_f32_16x16x32_bf16 v[68:71], v[216:219], v[208:211], v[68:71]
	v_mfma_f32_16x16x32_bf16 v[64:67], v[224:227], v[208:211], v[64:67]
	v_mfma_f32_16x16x32_bf16 v[116:119], v[220:223], v[148:151], v[116:119]
	v_mfma_f32_16x16x32_bf16 v[112:115], v[228:231], v[148:151], v[112:115]
	v_mfma_f32_16x16x32_bf16 v[100:103], v[220:223], v[196:199], v[100:103]
	v_mfma_f32_16x16x32_bf16 v[96:99], v[228:231], v[196:199], v[96:99]
	v_mfma_f32_16x16x32_bf16 v[84:87], v[220:223], v[204:207], v[84:87]
	v_mfma_f32_16x16x32_bf16 v[80:83], v[228:231], v[204:207], v[80:83]
	v_mfma_f32_16x16x32_bf16 v[68:71], v[220:223], v[212:215], v[68:71]
	v_mfma_f32_16x16x32_bf16 v[64:67], v[228:231], v[212:215], v[64:67]
	s_setprio 0
	s_barrier
	s_mov_b32 m0, s19
	v_lshl_add_u64 v[156:157], s[62:63], 0, v[160:161]
	global_load_lds_dwordx4 v[156:157], off
	v_lshl_add_u64 v[170:171], s[62:63], 0, v[158:159]
	s_mov_b32 m0, s20
	s_nop 0
	global_load_lds_dwordx4 v[170:171], off
	s_mov_b32 m0, s21
	v_lshl_add_u64 v[172:173], s[60:61], 0, v[160:161]
	ds_read_b128 v[144:147], v175 offset:16384
	ds_read_b128 v[148:151], v175 offset:17408
	ds_read_b128 v[152:155], v175 offset:18432
	ds_read_b128 v[196:199], v175 offset:19456
	ds_read_b128 v[200:203], v175 offset:20480
	ds_read_b128 v[204:207], v175 offset:21504
	ds_read_b128 v[208:211], v175 offset:22528
	ds_read_b128 v[212:215], v175 offset:23552
	global_load_lds_dwordx4 v[172:173], off
	v_lshl_add_u64 v[232:233], s[60:61], 0, v[158:159]
	s_mov_b32 m0, s22
	s_nop 0
	global_load_lds_dwordx4 v[232:233], off
	s_add_u32 s62, s62, s6
	s_addc_u32 s63, s63, s7
	s_mov_b32 m0, s24
	v_lshl_add_u64 v[234:235], s[62:63], 0, v[160:161]
	global_load_lds_dwordx4 v[234:235], off
	v_lshl_add_u64 v[236:237], s[62:63], 0, v[158:159]
	s_mov_b32 m0, s25
	s_nop 0
	global_load_lds_dwordx4 v[236:237], off
	s_waitcnt vmcnt(8)
	s_waitcnt lgkmcnt(0)
	s_barrier
; #define PG8_STAGE(bufoff, gbase) do { _Pragma("unroll") for (int _i = 0; _i < 2; ++_i) \
;         __builtin_amdgcn_global_load_lds((const unsigned*)((const char*)(gbase) + voffA[_i]), (LAS unsigned*)(lds + (bufoff) + ldsw + _i * 8192), 16, 0, 0); } while (0)
; #define PG8_LDA(dst, b, h) do { _Pragma("unroll") for (int m = 0; m < 4; ++m) _Pragma("unroll") for (int k = 0; k < 2; ++k) dst[m][k] = *(const LAS bf16x8*)(lds + PG8_SA(b, h) + aoff + m * 2048 + k * 1024); } while (0)
; #define PG8_LDB(dst, b, h) do { _Pragma("unroll") for (int n = 0; n < 2; ++n) _Pragma("unroll") for (int k = 0; k < 2; ++k) dst[n][k] = *(const LAS bf16x8*)(lds + PG8_SB(b, h) + boff + n * 2048 + k * 1024); } while (0)
; #define PG8_MMA(ai, bj, At, Bt) do { __builtin_amdgcn_s_setprio(1); _Pragma("unroll") for (int m = 0; m < 4; ++m) _Pragma("unroll") for (int n = 0; n < 2; ++n) _Pragma("unroll") for (int k = 0; k < 2; ++k) \
;         acc[ai][bj][m][n] = __builtin_amdgcn_mfma_f32_16x16x32_bf16(Bt[n][k], At[m][k], acc[ai][bj][m][n], 0, 0, 0); __builtin_amdgcn_s_setprio(0); } while (0)
; #define PG8_WAIT_V(n) asm volatile("s_waitcnt vmcnt(" #n ")" ::: "memory")
; #define PG8_WAIT_L(n) asm volatile("s_waitcnt lgkmcnt(" #n ")" ::: "memory")
; #define PG8_BAR __builtin_amdgcn_s_barrier()
; #define PG8_SCHED __builtin_amdgcn_sched_barrier(0)
; template <class Epi>
; DI void gemm_phase(const int TID, const int BID, LAS unsigned char* lds, const Gemm g, const Epi& E) {
;     ...
;             PG8_BAR; PG8_WAIT_L(0); PG8_MMA(0, 1, At, B1); PG8_BAR;
;             PG8_LDA(At, 0, 1); PG8_STAGE(PG8_SA(0, 0), a2);
;             PG8_BAR; PG8_WAIT_L(0); PG8_MMA(1, 0, At, B0); PG8_BAR; PG8_SCHED;
;             PG8_STAGE(PG8_SB(0, 1), b2 + hstep);
;             PG8_WAIT_V(6); PG8_BAR; PG8_MMA(1, 1, At, B1); PG8_BAR;
;             PG8_LDB(B0, 1, 0); PG8_SCHED; PG8_LDA(At, 1, 0); PG8_STAGE(PG8_SA(0, 1), a2 + hstep);
;             PG8_WAIT_L(8); PG8_BAR; PG8_WAIT_L(0); PG8_MMA(0, 0, At, B0); PG8_BAR; PG8_SCHED;
;             PG8_LDB(B1, 1, 1); PG8_STAGE(PG8_SB(1, 0), b3);
	s_setprio 1
	v_mfma_f32_16x16x32_bf16 v[60:63], v[128:131], v[144:147], v[60:63]
	v_mfma_f32_16x16x32_bf16 v[56:59], v[136:139], v[144:147], v[56:59]
	v_mfma_f32_16x16x32_bf16 v[44:47], v[128:131], v[152:155], v[44:47]
	v_mfma_f32_16x16x32_bf16 v[40:43], v[136:139], v[152:155], v[40:43]
	v_mfma_f32_16x16x32_bf16 v[28:31], v[128:131], v[200:203], v[28:31]
	v_mfma_f32_16x16x32_bf16 v[24:27], v[136:139], v[200:203], v[24:27]
	v_mfma_f32_16x16x32_bf16 v[12:15], v[128:131], v[208:211], v[12:15]
	v_mfma_f32_16x16x32_bf16 v[8:11], v[136:139], v[208:211], v[8:11]
	v_mfma_f32_16x16x32_bf16 v[60:63], v[132:135], v[148:151], v[60:63]
	v_mfma_f32_16x16x32_bf16 v[56:59], v[140:143], v[148:151], v[56:59]
	v_mfma_f32_16x16x32_bf16 v[44:47], v[132:135], v[196:199], v[44:47]
	v_mfma_f32_16x16x32_bf16 v[40:43], v[140:143], v[196:199], v[40:43]
	v_mfma_f32_16x16x32_bf16 v[28:31], v[132:135], v[204:207], v[28:31]
	v_mfma_f32_16x16x32_bf16 v[24:27], v[140:143], v[204:207], v[24:27]
	v_mfma_f32_16x16x32_bf16 v[12:15], v[132:135], v[212:215], v[12:15]
	v_mfma_f32_16x16x32_bf16 v[8:11], v[140:143], v[212:215], v[8:11]
	v_mfma_f32_16x16x32_bf16 v[52:55], v[216:219], v[144:147], v[52:55]
	v_mfma_f32_16x16x32_bf16 v[48:51], v[224:227], v[144:147], v[48:51]
	v_mfma_f32_16x16x32_bf16 v[36:39], v[216:219], v[152:155], v[36:39]
	v_mfma_f32_16x16x32_bf16 v[32:35], v[224:227], v[152:155], v[32:35]
	v_mfma_f32_16x16x32_bf16 v[20:23], v[216:219], v[200:203], v[20:23]
	v_mfma_f32_16x16x32_bf16 v[16:19], v[224:227], v[200:203], v[16:19]
	v_mfma_f32_16x16x32_bf16 v[4:7], v[216:219], v[208:211], v[4:7]
	v_mfma_f32_16x16x32_bf16 v[0:3], v[224:227], v[208:211], v[0:3]
	v_mfma_f32_16x16x32_bf16 v[52:55], v[220:223], v[148:151], v[52:55]
	v_mfma_f32_16x16x32_bf16 v[48:51], v[228:231], v[148:151], v[48:51]
	v_mfma_f32_16x16x32_bf16 v[36:39], v[220:223], v[196:199], v[36:39]
	v_mfma_f32_16x16x32_bf16 v[32:35], v[228:231], v[196:199], v[32:35]
	v_mfma_f32_16x16x32_bf16 v[20:23], v[220:223], v[204:207], v[20:23]
	v_mfma_f32_16x16x32_bf16 v[16:19], v[228:231], v[204:207], v[16:19]
	v_mfma_f32_16x16x32_bf16 v[4:7], v[220:223], v[212:215], v[4:7]
	v_mfma_f32_16x16x32_bf16 v[0:3], v[228:231], v[212:215], v[0:3]
	s_setprio 0
	s_barrier
	v_add_u32_e32 v140, s28, v192
	ds_read_b128 v[128:131], v140
	ds_read_b128 v[132:135], v140 offset:1024
	ds_read_b128 v[136:139], v140 offset:2048
	ds_read_b128 v[140:143], v140 offset:3072
	s_add_u32 s60, s60, s6
	s_addc_u32 s61, s61, s7
	s_mov_b32 m0, s26
	v_lshl_add_u64 v[216:217], s[60:61], 0, v[160:161]
	ds_read_b128 v[144:147], v175 offset:32768
	ds_read_b128 v[148:151], v175 offset:33792
	ds_read_b128 v[152:155], v175 offset:34816
	ds_read_b128 v[196:199], v175 offset:35840
	ds_read_b128 v[200:203], v175 offset:36864
	ds_read_b128 v[204:207], v175 offset:37888
	ds_read_b128 v[208:211], v175 offset:38912
	ds_read_b128 v[212:215], v175 offset:39936
	global_load_lds_dwordx4 v[216:217], off
	v_lshl_add_u64 v[216:217], s[60:61], 0, v[158:159]
	s_mov_b32 m0, s27
	s_nop 0
	global_load_lds_dwordx4 v[216:217], off
	v_add_u32_e32 v195, s64, v192
	ds_read_b128 v[216:219], v195
	ds_read_b128 v[220:223], v195 offset:1024
	ds_read_b128 v[224:227], v195 offset:2048
	ds_read_b128 v[228:231], v195 offset:3072
	s_waitcnt vmcnt(8)
	s_waitcnt lgkmcnt(0)
	s_barrier
	s_setprio 1
	v_mfma_f32_16x16x32_bf16 v[124:127], v[128:131], v[144:147], v[124:127]
	v_mfma_f32_16x16x32_bf16 v[120:123], v[136:139], v[144:147], v[120:123]
	v_mfma_f32_16x16x32_bf16 v[108:111], v[128:131], v[152:155], v[108:111]
	v_mfma_f32_16x16x32_bf16 v[104:107], v[136:139], v[152:155], v[104:107]
	v_mfma_f32_16x16x32_bf16 v[92:95], v[128:131], v[200:203], v[92:95]
	v_mfma_f32_16x16x32_bf16 v[88:91], v[136:139], v[200:203], v[88:91]
	v_mfma_f32_16x16x32_bf16 v[76:79], v[128:131], v[208:211], v[76:79]
	v_mfma_f32_16x16x32_bf16 v[72:75], v[136:139], v[208:211], v[72:75]
	v_mfma_f32_16x16x32_bf16 v[124:127], v[132:135], v[148:151], v[124:127]
	v_mfma_f32_16x16x32_bf16 v[120:123], v[140:143], v[148:151], v[120:123]
	v_mfma_f32_16x16x32_bf16 v[108:111], v[132:135], v[196:199], v[108:111]
	v_mfma_f32_16x16x32_bf16 v[104:107], v[140:143], v[196:199], v[104:107]
	v_mfma_f32_16x16x32_bf16 v[92:95], v[132:135], v[204:207], v[92:95]
	v_mfma_f32_16x16x32_bf16 v[88:91], v[140:143], v[204:207], v[88:91]
	v_mfma_f32_16x16x32_bf16 v[76:79], v[132:135], v[212:215], v[76:79]
	v_mfma_f32_16x16x32_bf16 v[72:75], v[140:143], v[212:215], v[72:75]
	v_mfma_f32_16x16x32_bf16 v[116:119], v[216:219], v[144:147], v[116:119]
	v_mfma_f32_16x16x32_bf16 v[112:115], v[224:227], v[144:147], v[112:115]
	v_mfma_f32_16x16x32_bf16 v[100:103], v[216:219], v[152:155], v[100:103]
	v_mfma_f32_16x16x32_bf16 v[96:99], v[224:227], v[152:155], v[96:99]
	v_mfma_f32_16x16x32_bf16 v[84:87], v[216:219], v[200:203], v[84:87]
	v_mfma_f32_16x16x32_bf16 v[80:83], v[224:227], v[200:203], v[80:83]
	v_mfma_f32_16x16x32_bf16 v[68:71], v[216:219], v[208:211], v[68:71]
	v_mfma_f32_16x16x32_bf16 v[64:67], v[224:227], v[208:211], v[64:67]
	v_mfma_f32_16x16x32_bf16 v[116:119], v[220:223], v[148:151], v[116:119]
	v_mfma_f32_16x16x32_bf16 v[112:115], v[228:231], v[148:151], v[112:115]
	v_mfma_f32_16x16x32_bf16 v[100:103], v[220:223], v[196:199], v[100:103]
	v_mfma_f32_16x16x32_bf16 v[96:99], v[228:231], v[196:199], v[96:99]
	v_mfma_f32_16x16x32_bf16 v[84:87], v[220:223], v[204:207], v[84:87]
	v_mfma_f32_16x16x32_bf16 v[80:83], v[228:231], v[204:207], v[80:83]
	v_mfma_f32_16x16x32_bf16 v[68:71], v[220:223], v[212:215], v[68:71]
	v_mfma_f32_16x16x32_bf16 v[64:67], v[228:231], v[212:215], v[64:67]
	s_setprio 0
	s_barrier
; #define PG8_STAGE(bufoff, gbase) do { _Pragma("unroll") for (int _i = 0; _i < 2; ++_i) \
;         __builtin_amdgcn_global_load_lds((const unsigned*)((const char*)(gbase) + voffA[_i]), (LAS unsigned*)(lds + (bufoff) + ldsw + _i * 8192), 16, 0, 0); } while (0)
; #define PG8_LDA(dst, b, h) do { _Pragma("unroll") for (int m = 0; m < 4; ++m) _Pragma("unroll") for (int k = 0; k < 2; ++k) dst[m][k] = *(const LAS bf16x8*)(lds + PG8_SA(b, h) + aoff + m * 2048 + k * 1024); } while (0)
; #define PG8_LDB(dst, b, h) do { _Pragma("unroll") for (int n = 0; n < 2; ++n) _Pragma("unroll") for (int k = 0; k < 2; ++k) dst[n][k] = *(const LAS bf16x8*)(lds + PG8_SB(b, h) + boff + n * 2048 + k * 1024); } while (0)
; #define PG8_MMA(ai, bj, At, Bt) do { __builtin_amdgcn_s_setprio(1); _Pragma("unroll") for (int m = 0; m < 4; ++m) _Pragma("unroll") for (int n = 0; n < 2; ++n) _Pragma("unroll") for (int k = 0; k < 2; ++k) \
;         acc[ai][bj][m][n] = __builtin_amdgcn_mfma_f32_16x16x32_bf16(Bt[n][k], At[m][k], acc[ai][bj][m][n], 0, 0, 0); __builtin_amdgcn_s_setprio(0); } while (0)
; #define PG8_WAIT_V(n) asm volatile("s_waitcnt vmcnt(" #n ")" ::: "memory")
; #define PG8_WAIT_L(n) asm volatile("s_waitcnt lgkmcnt(" #n ")" ::: "memory")
; #define PG8_BAR __builtin_amdgcn_s_barrier()
; #define PG8_SCHED __builtin_amdgcn_sched_barrier(0)
; template <class Epi>
; DI void gemm_phase(const int TID, const int BID, LAS unsigned char* lds, const Gemm g, const Epi& E) {
;     ...
;             PG8_LDB(B1, 1, 1); PG8_STAGE(PG8_SB(1, 0), b3);
;             PG8_BAR; PG8_WAIT_L(0); PG8_MMA(0, 1, At, B1); PG8_BAR;
;             PG8_LDA(At, 1, 1); PG8_STAGE(PG8_SA(1, 0), a3);
;             PG8_BAR; PG8_WAIT_L(0); PG8_MMA(1, 0, At, B0); PG8_BAR; PG8_SCHED;
;             PG8_STAGE(PG8_SB(1, 1), b3 + hstep);
;             PG8_WAIT_V(6); PG8_BAR; PG8_MMA(1, 1, At, B1); PG8_BAR;
;         }
	s_mov_b32 m0, s29
	v_lshl_add_u64 v[156:157], v[156:157], 0, s[92:93]
	global_load_lds_dwordx4 v[156:157], off
	v_lshl_add_u64 v[156:157], v[170:171], 0, s[92:93]
	s_mov_b32 m0, s30
	s_nop 0
	global_load_lds_dwordx4 v[156:157], off
	s_mov_b32 m0, s31
	v_lshl_add_u64 v[156:157], v[172:173], 0, s[92:93]
	ds_read_b128 v[144:147], v175 offset:49152
	ds_read_b128 v[148:151], v175 offset:50176
	ds_read_b128 v[152:155], v175 offset:51200
	ds_read_b128 v[196:199], v175 offset:52224
	ds_read_b128 v[200:203], v175 offset:53248
	ds_read_b128 v[204:207], v175 offset:54272
	ds_read_b128 v[208:211], v175 offset:55296
	ds_read_b128 v[212:215], v175 offset:56320
	global_load_lds_dwordx4 v[156:157], off
	v_lshl_add_u64 v[156:157], v[232:233], 0, s[92:93]
	s_mov_b32 m0, s33
	s_nop 0
	global_load_lds_dwordx4 v[156:157], off
	s_mov_b32 m0, s65
	v_lshl_add_u64 v[156:157], v[234:235], 0, s[92:93]
	global_load_lds_dwordx4 v[156:157], off
	v_lshl_add_u64 v[156:157], v[236:237], 0, s[92:93]
	s_mov_b32 m0, s66
	s_nop 0
	global_load_lds_dwordx4 v[156:157], off
	s_waitcnt vmcnt(8)
	s_waitcnt lgkmcnt(0)
	s_barrier
	s_setprio 1
	v_mfma_f32_16x16x32_bf16 v[60:63], v[128:131], v[144:147], v[60:63]
	v_mfma_f32_16x16x32_bf16 v[56:59], v[136:139], v[144:147], v[56:59]
	v_mfma_f32_16x16x32_bf16 v[44:47], v[128:131], v[152:155], v[44:47]
	v_mfma_f32_16x16x32_bf16 v[40:43], v[136:139], v[152:155], v[40:43]
	v_mfma_f32_16x16x32_bf16 v[28:31], v[128:131], v[200:203], v[28:31]
	v_mfma_f32_16x16x32_bf16 v[24:27], v[136:139], v[200:203], v[24:27]
	v_mfma_f32_16x16x32_bf16 v[12:15], v[128:131], v[208:211], v[12:15]
	v_mfma_f32_16x16x32_bf16 v[8:11], v[136:139], v[208:211], v[8:11]
	v_mfma_f32_16x16x32_bf16 v[60:63], v[132:135], v[148:151], v[60:63]
	v_mfma_f32_16x16x32_bf16 v[56:59], v[140:143], v[148:151], v[56:59]
	v_mfma_f32_16x16x32_bf16 v[44:47], v[132:135], v[196:199], v[44:47]
	v_mfma_f32_16x16x32_bf16 v[40:43], v[140:143], v[196:199], v[40:43]
	v_mfma_f32_16x16x32_bf16 v[28:31], v[132:135], v[204:207], v[28:31]
	v_mfma_f32_16x16x32_bf16 v[24:27], v[140:143], v[204:207], v[24:27]
	v_mfma_f32_16x16x32_bf16 v[12:15], v[132:135], v[212:215], v[12:15]
	v_mfma_f32_16x16x32_bf16 v[8:11], v[140:143], v[212:215], v[8:11]
	v_mfma_f32_16x16x32_bf16 v[52:55], v[216:219], v[144:147], v[52:55]
	v_mfma_f32_16x16x32_bf16 v[48:51], v[224:227], v[144:147], v[48:51]
	v_mfma_f32_16x16x32_bf16 v[36:39], v[216:219], v[152:155], v[36:39]
	v_mfma_f32_16x16x32_bf16 v[32:35], v[224:227], v[152:155], v[32:35]
	v_mfma_f32_16x16x32_bf16 v[20:23], v[216:219], v[200:203], v[20:23]
	v_mfma_f32_16x16x32_bf16 v[16:19], v[224:227], v[200:203], v[16:19]
	v_mfma_f32_16x16x32_bf16 v[4:7], v[216:219], v[208:211], v[4:7]
	v_mfma_f32_16x16x32_bf16 v[0:3], v[224:227], v[208:211], v[0:3]
	v_mfma_f32_16x16x32_bf16 v[52:55], v[220:223], v[148:151], v[52:55]
	v_mfma_f32_16x16x32_bf16 v[48:51], v[228:231], v[148:151], v[48:51]
	v_mfma_f32_16x16x32_bf16 v[36:39], v[220:223], v[196:199], v[36:39]
	v_mfma_f32_16x16x32_bf16 v[32:35], v[228:231], v[196:199], v[32:35]
	v_mfma_f32_16x16x32_bf16 v[20:23], v[220:223], v[204:207], v[20:23]
	v_mfma_f32_16x16x32_bf16 v[16:19], v[228:231], v[204:207], v[16:19]
	v_mfma_f32_16x16x32_bf16 v[4:7], v[220:223], v[212:215], v[4:7]
	v_mfma_f32_16x16x32_bf16 v[0:3], v[228:231], v[212:215], v[0:3]
	s_setprio 0
	s_add_u32 s4, s4, 0x100
	s_addc_u32 s5, s5, 0
	s_add_u32 vcc_lo, vcc_lo, 0x100
	s_addc_u32 vcc_hi, vcc_hi, 0
	s_cmp_ge_i32 s16, s67
	s_mov_b32 s60, s16
	s_barrier
	s_cbranch_scc0 .LBB0_491

; #define PG8_STAGE(bufoff, gbase) do { _Pragma("unroll") for (int _i = 0; _i < 2; ++_i) \
;         __builtin_amdgcn_global_load_lds((const unsigned*)((const char*)(gbase) + voffA[_i]), (LAS unsigned*)(lds + (bufoff) + ldsw + _i * 8192), 16, 0, 0); } while (0)
; #define PG8_LDA(dst, b, h) do { _Pragma("unroll") for (int m = 0; m < 4; ++m) _Pragma("unroll") for (int k = 0; k < 2; ++k) dst[m][k] = *(const LAS bf16x8*)(lds + PG8_SA(b, h) + aoff + m * 2048 + k * 1024); } while (0)
; #define PG8_LDB(dst, b, h) do { _Pragma("unroll") for (int n = 0; n < 2; ++n) _Pragma("unroll") for (int k = 0; k < 2; ++k) dst[n][k] = *(const LAS bf16x8*)(lds + PG8_SB(b, h) + boff + n * 2048 + k * 1024); } while (0)
; #define PG8_MMA(ai, bj, At, Bt) do { __builtin_amdgcn_s_setprio(1); _Pragma("unroll") for (int m = 0; m < 4; ++m) _Pragma("unroll") for (int n = 0; n < 2; ++n) _Pragma("unroll") for (int k = 0; k < 2; ++k) \
;         acc[ai][bj][m][n] = __builtin_amdgcn_mfma_f32_16x16x32_bf16(Bt[n][k], At[m][k], acc[ai][bj][m][n], 0, 0, 0); __builtin_amdgcn_s_setprio(0); } while (0)
; #define PG8_WAIT_L(n) asm volatile("s_waitcnt lgkmcnt(" #n ")" ::: "memory")
; #define PG8_BAR __builtin_amdgcn_s_barrier()
; #define PG8_SCHED __builtin_amdgcn_sched_barrier(0)
; template <class Epi>
; DI void gemm_phase(const int TID, const int BID, LAS unsigned char* lds, const Gemm g, const Epi& E) {
;     ...
;             const bool last = (t == nt - 2);
;             const char* a1 = cA + (size_t)(t + 1) * kstep;
;             const char* a2 = last ? nA : cA + (size_t)(t + 2) * kstep; const char* b2 = last ? nB : cB + (size_t)(t + 2) * kstep;
;             const char* a3 = a2 + kstep; const char* b3 = b2 + kstep;
;             PG8_LDB(B0, 0, 0); PG8_SCHED; PG8_LDA(At, 0, 0); PG8_STAGE(PG8_SA(1, 1), a1 + hstep);
;             PG8_WAIT_L(8); PG8_BAR; PG8_WAIT_L(0); PG8_MMA(0, 0, At, B0); PG8_BAR; PG8_SCHED;
;             PG8_LDB(B1, 0, 1); PG8_STAGE(PG8_SB(0, 0), b2);
;             PG8_BAR; PG8_WAIT_L(0); PG8_MMA(0, 1, At, B1); PG8_BAR;
;             PG8_LDA(At, 0, 1); PG8_STAGE(PG8_SA(0, 0), a2);
;             PG8_BAR; PG8_WAIT_L(0); PG8_MMA(1, 0, At, B0); PG8_BAR; PG8_SCHED;
;             PG8_STAGE(PG8_SB(0, 1), b2 + hstep);
.LBB0_568:
	v_add_u32_e32 v168, s65, v161
	ds_read_b128 v[156:159], v168
	ds_read_b128 v[176:179], v168 offset:1024
	ds_read_b128 v[180:183], v168 offset:2048
	ds_read_b128 v[184:187], v168 offset:3072
	s_add_i32 s31, s30, 2
	s_add_u32 s56, s4, 0x80
	s_addc_u32 s57, s5, 0
	s_cmp_eq_u32 s22, s30
	s_cselect_b32 s57, s53, s57
	s_cselect_b32 s56, s52, s56
	s_cselect_b32 s59, s55, s29
	s_cselect_b32 s58, s54, s28
	v_lshl_add_u64 v[170:171], s[4:5], 0, v[152:153]
	s_add_i32 m0, s62, 0xc000
	ds_read_b128 v[188:191], v175
	ds_read_b128 v[192:195], v175 offset:1024
	ds_read_b128 v[196:199], v175 offset:2048
	ds_read_b128 v[200:203], v175 offset:3072
	ds_read_b128 v[204:207], v175 offset:4096
	ds_read_b128 v[208:211], v175 offset:5120
	ds_read_b128 v[212:215], v175 offset:6144
	ds_read_b128 v[216:219], v175 offset:7168
	global_load_lds_dwordx4 v[170:171], off
	v_lshl_add_u64 v[170:171], s[4:5], 0, v[154:155]
	s_add_i32 m0, s62, 0xe000
	s_nop 0
	global_load_lds_dwordx4 v[170:171], off
	v_add_u32_e32 v168, s64, v161
	ds_read_b128 v[220:223], v168
	ds_read_b128 v[224:227], v168 offset:1024
	ds_read_b128 v[228:231], v168 offset:2048
	ds_read_b128 v[246:249], v168 offset:3072
	s_waitcnt vmcnt(8)
	s_waitcnt lgkmcnt(0)
	s_barrier
	s_setprio 1
	v_mfma_f32_16x16x32_bf16 v[124:127], v[156:159], v[188:191], v[124:127]
	v_mfma_f32_16x16x32_bf16 v[120:123], v[180:183], v[188:191], v[120:123]
	v_mfma_f32_16x16x32_bf16 v[116:119], v[156:159], v[196:199], v[116:119]
	v_mfma_f32_16x16x32_bf16 v[112:115], v[180:183], v[196:199], v[112:115]
	v_mfma_f32_16x16x32_bf16 v[108:111], v[156:159], v[204:207], v[108:111]
	v_mfma_f32_16x16x32_bf16 v[104:107], v[180:183], v[204:207], v[104:107]
	v_mfma_f32_16x16x32_bf16 v[100:103], v[156:159], v[212:215], v[100:103]
	v_mfma_f32_16x16x32_bf16 v[96:99], v[180:183], v[212:215], v[96:99]
	v_mfma_f32_16x16x32_bf16 v[124:127], v[176:179], v[192:195], v[124:127]
	v_mfma_f32_16x16x32_bf16 v[120:123], v[184:187], v[192:195], v[120:123]
	v_mfma_f32_16x16x32_bf16 v[116:119], v[176:179], v[200:203], v[116:119]
	v_mfma_f32_16x16x32_bf16 v[112:115], v[184:187], v[200:203], v[112:115]
	v_mfma_f32_16x16x32_bf16 v[108:111], v[176:179], v[208:211], v[108:111]
	v_mfma_f32_16x16x32_bf16 v[104:107], v[184:187], v[208:211], v[104:107]
	v_mfma_f32_16x16x32_bf16 v[100:103], v[176:179], v[216:219], v[100:103]
	v_mfma_f32_16x16x32_bf16 v[96:99], v[184:187], v[216:219], v[96:99]
	v_mfma_f32_16x16x32_bf16 v[56:59], v[220:223], v[188:191], v[56:59]
	v_mfma_f32_16x16x32_bf16 v[60:63], v[228:231], v[188:191], v[60:63]
	v_mfma_f32_16x16x32_bf16 v[52:55], v[220:223], v[196:199], v[52:55]
	v_mfma_f32_16x16x32_bf16 v[48:51], v[228:231], v[196:199], v[48:51]
	v_mfma_f32_16x16x32_bf16 v[44:47], v[220:223], v[204:207], v[44:47]
	v_mfma_f32_16x16x32_bf16 v[40:43], v[228:231], v[204:207], v[40:43]
	v_mfma_f32_16x16x32_bf16 v[36:39], v[220:223], v[212:215], v[36:39]
	v_mfma_f32_16x16x32_bf16 v[32:35], v[228:231], v[212:215], v[32:35]
	v_mfma_f32_16x16x32_bf16 v[56:59], v[224:227], v[192:195], v[56:59]
	v_mfma_f32_16x16x32_bf16 v[60:63], v[246:249], v[192:195], v[60:63]
	v_mfma_f32_16x16x32_bf16 v[52:55], v[224:227], v[200:203], v[52:55]
	v_mfma_f32_16x16x32_bf16 v[48:51], v[246:249], v[200:203], v[48:51]
	v_mfma_f32_16x16x32_bf16 v[44:47], v[224:227], v[208:211], v[44:47]
	v_mfma_f32_16x16x32_bf16 v[40:43], v[246:249], v[208:211], v[40:43]
	v_mfma_f32_16x16x32_bf16 v[36:39], v[224:227], v[216:219], v[36:39]
	v_mfma_f32_16x16x32_bf16 v[32:35], v[246:249], v[216:219], v[32:35]
	s_setprio 0
	s_barrier
	s_mov_b32 m0, s66
	v_lshl_add_u64 v[170:171], s[58:59], 0, v[128:129]
	global_load_lds_dwordx4 v[170:171], off
	v_lshl_add_u64 v[172:173], s[58:59], 0, v[130:131]
	s_mov_b32 m0, s67
	s_nop 0
	global_load_lds_dwordx4 v[172:173], off
	s_mov_b32 m0, s62
	v_lshl_add_u64 v[232:233], s[56:57], 0, v[128:129]
	ds_read_b128 v[188:191], v175 offset:16384
	ds_read_b128 v[192:195], v175 offset:17408
	ds_read_b128 v[196:199], v175 offset:18432
	ds_read_b128 v[200:203], v175 offset:19456
	ds_read_b128 v[204:207], v175 offset:20480
	ds_read_b128 v[208:211], v175 offset:21504
	ds_read_b128 v[212:215], v175 offset:22528
	ds_read_b128 v[216:219], v175 offset:23552
	global_load_lds_dwordx4 v[232:233], off
	v_lshl_add_u64 v[234:235], s[56:57], 0, v[130:131]
	s_mov_b32 m0, s63
	s_nop 0
	global_load_lds_dwordx4 v[234:235], off
	s_add_u32 s58, s58, s6
	s_addc_u32 s59, s59, s7
	s_mov_b32 m0, s10
	v_lshl_add_u64 v[236:237], s[58:59], 0, v[128:129]
	global_load_lds_dwordx4 v[236:237], off
	v_lshl_add_u64 v[238:239], s[58:59], 0, v[130:131]
	s_mov_b32 m0, s11
	s_nop 0
	global_load_lds_dwordx4 v[238:239], off
	s_waitcnt vmcnt(8)
	s_waitcnt lgkmcnt(0)
	s_barrier
; #define PG8_STAGE(bufoff, gbase) do { _Pragma("unroll") for (int _i = 0; _i < 2; ++_i) \
;         __builtin_amdgcn_global_load_lds((const unsigned*)((const char*)(gbase) + voffA[_i]), (LAS unsigned*)(lds + (bufoff) + ldsw + _i * 8192), 16, 0, 0); } while (0)
; #define PG8_LDA(dst, b, h) do { _Pragma("unroll") for (int m = 0; m < 4; ++m) _Pragma("unroll") for (int k = 0; k < 2; ++k) dst[m][k] = *(const LAS bf16x8*)(lds + PG8_SA(b, h) + aoff + m * 2048 + k * 1024); } while (0)
; #define PG8_LDB(dst, b, h) do { _Pragma("unroll") for (int n = 0; n < 2; ++n) _Pragma("unroll") for (int k = 0; k < 2; ++k) dst[n][k] = *(const LAS bf16x8*)(lds + PG8_SB(b, h) + boff + n * 2048 + k * 1024); } while (0)
; #define PG8_MMA(ai, bj, At, Bt) do { __builtin_amdgcn_s_setprio(1); _Pragma("unroll") for (int m = 0; m < 4; ++m) _Pragma("unroll") for (int n = 0; n < 2; ++n) _Pragma("unroll") for (int k = 0; k < 2; ++k) \
;         acc[ai][bj][m][n] = __builtin_amdgcn_mfma_f32_16x16x32_bf16(Bt[n][k], At[m][k], acc[ai][bj][m][n], 0, 0, 0); __builtin_amdgcn_s_setprio(0); } while (0)
; #define PG8_WAIT_V(n) asm volatile("s_waitcnt vmcnt(" #n ")" ::: "memory")
; #define PG8_WAIT_L(n) asm volatile("s_waitcnt lgkmcnt(" #n ")" ::: "memory")
; #define PG8_BAR __builtin_amdgcn_s_barrier()
; #define PG8_SCHED __builtin_amdgcn_sched_barrier(0)
; template <class Epi>
; DI void gemm_phase(const int TID, const int BID, LAS unsigned char* lds, const Gemm g, const Epi& E) {
;     ...
;             PG8_BAR; PG8_WAIT_L(0); PG8_MMA(0, 1, At, B1); PG8_BAR;
;             PG8_LDA(At, 0, 1); PG8_STAGE(PG8_SA(0, 0), a2);
;             PG8_BAR; PG8_WAIT_L(0); PG8_MMA(1, 0, At, B0); PG8_BAR; PG8_SCHED;
;             PG8_STAGE(PG8_SB(0, 1), b2 + hstep);
;             PG8_WAIT_V(6); PG8_BAR; PG8_MMA(1, 1, At, B1); PG8_BAR;
;             PG8_LDB(B0, 1, 0); PG8_SCHED; PG8_LDA(At, 1, 0); PG8_STAGE(PG8_SA(0, 1), a2 + hstep);
;             PG8_WAIT_L(8); PG8_BAR; PG8_WAIT_L(0); PG8_MMA(0, 0, At, B0); PG8_BAR; PG8_SCHED;
;             PG8_LDB(B1, 1, 1); PG8_STAGE(PG8_SB(1, 0), b3);
	s_setprio 1
	v_mfma_f32_16x16x32_bf16 v[92:95], v[156:159], v[188:191], v[92:95]
	v_mfma_f32_16x16x32_bf16 v[88:91], v[180:183], v[188:191], v[88:91]
	v_mfma_f32_16x16x32_bf16 v[84:87], v[156:159], v[196:199], v[84:87]
	v_mfma_f32_16x16x32_bf16 v[80:83], v[180:183], v[196:199], v[80:83]
	v_mfma_f32_16x16x32_bf16 v[76:79], v[156:159], v[204:207], v[76:79]
	v_mfma_f32_16x16x32_bf16 v[72:75], v[180:183], v[204:207], v[72:75]
	v_mfma_f32_16x16x32_bf16 v[68:71], v[156:159], v[212:215], v[68:71]
	v_mfma_f32_16x16x32_bf16 v[64:67], v[180:183], v[212:215], v[64:67]
	v_mfma_f32_16x16x32_bf16 v[92:95], v[176:179], v[192:195], v[92:95]
	v_mfma_f32_16x16x32_bf16 v[88:91], v[184:187], v[192:195], v[88:91]
	v_mfma_f32_16x16x32_bf16 v[84:87], v[176:179], v[200:203], v[84:87]
	v_mfma_f32_16x16x32_bf16 v[80:83], v[184:187], v[200:203], v[80:83]
	v_mfma_f32_16x16x32_bf16 v[76:79], v[176:179], v[208:211], v[76:79]
	v_mfma_f32_16x16x32_bf16 v[72:75], v[184:187], v[208:211], v[72:75]
	v_mfma_f32_16x16x32_bf16 v[68:71], v[176:179], v[216:219], v[68:71]
	v_mfma_f32_16x16x32_bf16 v[64:67], v[184:187], v[216:219], v[64:67]
	v_mfma_f32_16x16x32_bf16 v[28:31], v[220:223], v[188:191], v[28:31]
	v_mfma_f32_16x16x32_bf16 v[24:27], v[228:231], v[188:191], v[24:27]
	v_mfma_f32_16x16x32_bf16 v[20:23], v[220:223], v[196:199], v[20:23]
	v_mfma_f32_16x16x32_bf16 v[16:19], v[228:231], v[196:199], v[16:19]
	v_mfma_f32_16x16x32_bf16 v[12:15], v[220:223], v[204:207], v[12:15]
	v_mfma_f32_16x16x32_bf16 v[8:11], v[228:231], v[204:207], v[8:11]
	v_mfma_f32_16x16x32_bf16 v[4:7], v[220:223], v[212:215], v[4:7]
	v_mfma_f32_16x16x32_bf16 v[0:3], v[228:231], v[212:215], v[0:3]
	v_mfma_f32_16x16x32_bf16 v[28:31], v[224:227], v[192:195], v[28:31]
	v_mfma_f32_16x16x32_bf16 v[24:27], v[246:249], v[192:195], v[24:27]
	v_mfma_f32_16x16x32_bf16 v[20:23], v[224:227], v[200:203], v[20:23]
	v_mfma_f32_16x16x32_bf16 v[16:19], v[246:249], v[200:203], v[16:19]
	v_mfma_f32_16x16x32_bf16 v[12:15], v[224:227], v[208:211], v[12:15]
	v_mfma_f32_16x16x32_bf16 v[8:11], v[246:249], v[208:211], v[8:11]
	v_mfma_f32_16x16x32_bf16 v[4:7], v[224:227], v[216:219], v[4:7]
	v_mfma_f32_16x16x32_bf16 v[0:3], v[246:249], v[216:219], v[0:3]
	s_setprio 0
	s_barrier
	v_add_u32_e32 v168, s76, v161
	ds_read_b128 v[156:159], v168
	ds_read_b128 v[176:179], v168 offset:1024
	ds_read_b128 v[180:183], v168 offset:2048
	ds_read_b128 v[184:187], v168 offset:3072
	s_add_u32 s56, s56, s6
	s_addc_u32 s57, s57, s7
	s_mov_b32 m0, s33
	v_lshl_add_u64 v[220:221], s[56:57], 0, v[128:129]
	ds_read_b128 v[188:191], v175 offset:32768
	ds_read_b128 v[192:195], v175 offset:33792
	ds_read_b128 v[196:199], v175 offset:34816
	ds_read_b128 v[200:203], v175 offset:35840
	ds_read_b128 v[204:207], v175 offset:36864
	ds_read_b128 v[208:211], v175 offset:37888
	ds_read_b128 v[212:215], v175 offset:38912
	ds_read_b128 v[216:219], v175 offset:39936
	global_load_lds_dwordx4 v[220:221], off
	v_lshl_add_u64 v[220:221], s[56:57], 0, v[130:131]
	s_mov_b32 m0, s15
	s_nop 0
	global_load_lds_dwordx4 v[220:221], off
	v_add_u32_e32 v168, s9, v161
	ds_read_b128 v[220:223], v168
	ds_read_b128 v[224:227], v168 offset:1024
	ds_read_b128 v[228:231], v168 offset:2048
	ds_read_b128 v[246:249], v168 offset:3072
	s_waitcnt vmcnt(8)
	s_waitcnt lgkmcnt(0)
	s_barrier
	s_setprio 1
	v_mfma_f32_16x16x32_bf16 v[124:127], v[156:159], v[188:191], v[124:127]
	v_mfma_f32_16x16x32_bf16 v[120:123], v[180:183], v[188:191], v[120:123]
	v_mfma_f32_16x16x32_bf16 v[116:119], v[156:159], v[196:199], v[116:119]
	v_mfma_f32_16x16x32_bf16 v[112:115], v[180:183], v[196:199], v[112:115]
	v_mfma_f32_16x16x32_bf16 v[108:111], v[156:159], v[204:207], v[108:111]
	v_mfma_f32_16x16x32_bf16 v[104:107], v[180:183], v[204:207], v[104:107]
	v_mfma_f32_16x16x32_bf16 v[100:103], v[156:159], v[212:215], v[100:103]
	v_mfma_f32_16x16x32_bf16 v[96:99], v[180:183], v[212:215], v[96:99]
	v_mfma_f32_16x16x32_bf16 v[124:127], v[176:179], v[192:195], v[124:127]
	v_mfma_f32_16x16x32_bf16 v[120:123], v[184:187], v[192:195], v[120:123]
	v_mfma_f32_16x16x32_bf16 v[116:119], v[176:179], v[200:203], v[116:119]
	v_mfma_f32_16x16x32_bf16 v[112:115], v[184:187], v[200:203], v[112:115]
	v_mfma_f32_16x16x32_bf16 v[108:111], v[176:179], v[208:211], v[108:111]
	v_mfma_f32_16x16x32_bf16 v[104:107], v[184:187], v[208:211], v[104:107]
	v_mfma_f32_16x16x32_bf16 v[100:103], v[176:179], v[216:219], v[100:103]
	v_mfma_f32_16x16x32_bf16 v[96:99], v[184:187], v[216:219], v[96:99]
	v_mfma_f32_16x16x32_bf16 v[56:59], v[220:223], v[188:191], v[56:59]
	v_mfma_f32_16x16x32_bf16 v[60:63], v[228:231], v[188:191], v[60:63]
	v_mfma_f32_16x16x32_bf16 v[52:55], v[220:223], v[196:199], v[52:55]
	v_mfma_f32_16x16x32_bf16 v[48:51], v[228:231], v[196:199], v[48:51]
	v_mfma_f32_16x16x32_bf16 v[44:47], v[220:223], v[204:207], v[44:47]
	v_mfma_f32_16x16x32_bf16 v[40:43], v[228:231], v[204:207], v[40:43]
	v_mfma_f32_16x16x32_bf16 v[36:39], v[220:223], v[212:215], v[36:39]
	v_mfma_f32_16x16x32_bf16 v[32:35], v[228:231], v[212:215], v[32:35]
	v_mfma_f32_16x16x32_bf16 v[56:59], v[224:227], v[192:195], v[56:59]
	v_mfma_f32_16x16x32_bf16 v[60:63], v[246:249], v[192:195], v[60:63]
	v_mfma_f32_16x16x32_bf16 v[52:55], v[224:227], v[200:203], v[52:55]
	v_mfma_f32_16x16x32_bf16 v[48:51], v[246:249], v[200:203], v[48:51]
	v_mfma_f32_16x16x32_bf16 v[44:47], v[224:227], v[208:211], v[44:47]
	v_mfma_f32_16x16x32_bf16 v[40:43], v[246:249], v[208:211], v[40:43]
	v_mfma_f32_16x16x32_bf16 v[36:39], v[224:227], v[216:219], v[36:39]
	v_mfma_f32_16x16x32_bf16 v[32:35], v[246:249], v[216:219], v[32:35]
	s_setprio 0
	s_barrier
; #define PG8_STAGE(bufoff, gbase) do { _Pragma("unroll") for (int _i = 0; _i < 2; ++_i) \
;         __builtin_amdgcn_global_load_lds((const unsigned*)((const char*)(gbase) + voffA[_i]), (LAS unsigned*)(lds + (bufoff) + ldsw + _i * 8192), 16, 0, 0); } while (0)
; #define PG8_LDA(dst, b, h) do { _Pragma("unroll") for (int m = 0; m < 4; ++m) _Pragma("unroll") for (int k = 0; k < 2; ++k) dst[m][k] = *(const LAS bf16x8*)(lds + PG8_SA(b, h) + aoff + m * 2048 + k * 1024); } while (0)
; #define PG8_LDB(dst, b, h) do { _Pragma("unroll") for (int n = 0; n < 2; ++n) _Pragma("unroll") for (int k = 0; k < 2; ++k) dst[n][k] = *(const LAS bf16x8*)(lds + PG8_SB(b, h) + boff + n * 2048 + k * 1024); } while (0)
; #define PG8_MMA(ai, bj, At, Bt) do { __builtin_amdgcn_s_setprio(1); _Pragma("unroll") for (int m = 0; m < 4; ++m) _Pragma("unroll") for (int n = 0; n < 2; ++n) _Pragma("unroll") for (int k = 0; k < 2; ++k) \
;         acc[ai][bj][m][n] = __builtin_amdgcn_mfma_f32_16x16x32_bf16(Bt[n][k], At[m][k], acc[ai][bj][m][n], 0, 0, 0); __builtin_amdgcn_s_setprio(0); } while (0)
; #define PG8_WAIT_V(n) asm volatile("s_waitcnt vmcnt(" #n ")" ::: "memory")
; #define PG8_WAIT_L(n) asm volatile("s_waitcnt lgkmcnt(" #n ")" ::: "memory")
; #define PG8_BAR __builtin_amdgcn_s_barrier()
; #define PG8_SCHED __builtin_amdgcn_sched_barrier(0)
; template <class Epi>
; DI void gemm_phase(const int TID, const int BID, LAS unsigned char* lds, const Gemm g, const Epi& E) {
;     ...
;             PG8_LDB(B1, 1, 1); PG8_STAGE(PG8_SB(1, 0), b3);
;             PG8_BAR; PG8_WAIT_L(0); PG8_MMA(0, 1, At, B1); PG8_BAR;
;             PG8_LDA(At, 1, 1); PG8_STAGE(PG8_SA(1, 0), a3);
;             PG8_BAR; PG8_WAIT_L(0); PG8_MMA(1, 0, At, B0); PG8_BAR; PG8_SCHED;
;             PG8_STAGE(PG8_SB(1, 1), b3 + hstep);
;             PG8_WAIT_V(6); PG8_BAR; PG8_MMA(1, 1, At, B1); PG8_BAR;
;         }
	s_mov_b32 m0, s77
	v_lshl_add_u64 v[170:171], v[170:171], 0, s[92:93]
	global_load_lds_dwordx4 v[170:171], off
	v_lshl_add_u64 v[170:171], v[172:173], 0, s[92:93]
	s_mov_b32 m0, s80
	s_nop 0
	global_load_lds_dwordx4 v[170:171], off
	s_mov_b32 m0, s81
	v_lshl_add_u64 v[170:171], v[232:233], 0, s[92:93]
	ds_read_b128 v[188:191], v175 offset:49152
	ds_read_b128 v[192:195], v175 offset:50176
	ds_read_b128 v[196:199], v175 offset:51200
	ds_read_b128 v[200:203], v175 offset:52224
	ds_read_b128 v[204:207], v175 offset:53248
	ds_read_b128 v[208:211], v175 offset:54272
	ds_read_b128 v[212:215], v175 offset:55296
	ds_read_b128 v[216:219], v175 offset:56320
	global_load_lds_dwordx4 v[170:171], off
	v_lshl_add_u64 v[170:171], v[234:235], 0, s[92:93]
	s_mov_b32 m0, s8
	s_nop 0
	global_load_lds_dwordx4 v[170:171], off
	s_mov_b32 m0, s16
	v_lshl_add_u64 v[170:171], v[236:237], 0, s[92:93]
	global_load_lds_dwordx4 v[170:171], off
	v_lshl_add_u64 v[170:171], v[238:239], 0, s[92:93]
	s_mov_b32 m0, s17
	s_nop 0
	global_load_lds_dwordx4 v[170:171], off
	s_waitcnt vmcnt(8)
	s_waitcnt lgkmcnt(0)
	s_barrier
	s_setprio 1
	v_mfma_f32_16x16x32_bf16 v[92:95], v[156:159], v[188:191], v[92:95]
	v_mfma_f32_16x16x32_bf16 v[88:91], v[180:183], v[188:191], v[88:91]
	v_mfma_f32_16x16x32_bf16 v[84:87], v[156:159], v[196:199], v[84:87]
	v_mfma_f32_16x16x32_bf16 v[80:83], v[180:183], v[196:199], v[80:83]
	v_mfma_f32_16x16x32_bf16 v[76:79], v[156:159], v[204:207], v[76:79]
	v_mfma_f32_16x16x32_bf16 v[72:75], v[180:183], v[204:207], v[72:75]
	v_mfma_f32_16x16x32_bf16 v[68:71], v[156:159], v[212:215], v[68:71]
	v_mfma_f32_16x16x32_bf16 v[64:67], v[180:183], v[212:215], v[64:67]
	v_mfma_f32_16x16x32_bf16 v[92:95], v[176:179], v[192:195], v[92:95]
	v_mfma_f32_16x16x32_bf16 v[88:91], v[184:187], v[192:195], v[88:91]
	v_mfma_f32_16x16x32_bf16 v[84:87], v[176:179], v[200:203], v[84:87]
	v_mfma_f32_16x16x32_bf16 v[80:83], v[184:187], v[200:203], v[80:83]
	v_mfma_f32_16x16x32_bf16 v[76:79], v[176:179], v[208:211], v[76:79]
	v_mfma_f32_16x16x32_bf16 v[72:75], v[184:187], v[208:211], v[72:75]
	v_mfma_f32_16x16x32_bf16 v[68:71], v[176:179], v[216:219], v[68:71]
	v_mfma_f32_16x16x32_bf16 v[64:67], v[184:187], v[216:219], v[64:67]
	v_mfma_f32_16x16x32_bf16 v[28:31], v[220:223], v[188:191], v[28:31]
	v_mfma_f32_16x16x32_bf16 v[24:27], v[228:231], v[188:191], v[24:27]
	v_mfma_f32_16x16x32_bf16 v[20:23], v[220:223], v[196:199], v[20:23]
	v_mfma_f32_16x16x32_bf16 v[16:19], v[228:231], v[196:199], v[16:19]
	v_mfma_f32_16x16x32_bf16 v[12:15], v[220:223], v[204:207], v[12:15]
	v_mfma_f32_16x16x32_bf16 v[8:11], v[228:231], v[204:207], v[8:11]
	v_mfma_f32_16x16x32_bf16 v[4:7], v[220:223], v[212:215], v[4:7]
	v_mfma_f32_16x16x32_bf16 v[0:3], v[228:231], v[212:215], v[0:3]
	v_mfma_f32_16x16x32_bf16 v[28:31], v[224:227], v[192:195], v[28:31]
	v_mfma_f32_16x16x32_bf16 v[24:27], v[246:249], v[192:195], v[24:27]
	v_mfma_f32_16x16x32_bf16 v[20:23], v[224:227], v[200:203], v[20:23]
	v_mfma_f32_16x16x32_bf16 v[16:19], v[246:249], v[200:203], v[16:19]
	v_mfma_f32_16x16x32_bf16 v[12:15], v[224:227], v[208:211], v[12:15]
	v_mfma_f32_16x16x32_bf16 v[8:11], v[246:249], v[208:211], v[8:11]
	v_mfma_f32_16x16x32_bf16 v[4:7], v[224:227], v[216:219], v[4:7]
	v_mfma_f32_16x16x32_bf16 v[0:3], v[246:249], v[216:219], v[0:3]
	s_setprio 0
	s_add_u32 s4, s4, 0x100
	s_addc_u32 s5, s5, 0
	s_add_u32 s28, s28, 0x100
	s_addc_u32 s29, s29, 0
	s_cmp_ge_i32 s31, s21
	s_mov_b32 s30, s31
	s_barrier
	s_cbranch_scc0 .LBB0_568
	v_readlane_b32 s31, v255, 8

; #define PG8_STAGE(bufoff, gbase) do { _Pragma("unroll") for (int _i = 0; _i < 2; ++_i) \
;         __builtin_amdgcn_global_load_lds((const unsigned*)((const char*)(gbase) + voffA[_i]), (LAS unsigned*)(lds + (bufoff) + ldsw + _i * 8192), 16, 0, 0); } while (0)
; #define PG8_LDA(dst, b, h) do { _Pragma("unroll") for (int m = 0; m < 4; ++m) _Pragma("unroll") for (int k = 0; k < 2; ++k) dst[m][k] = *(const LAS bf16x8*)(lds + PG8_SA(b, h) + aoff + m * 2048 + k * 1024); } while (0)
; #define PG8_LDB(dst, b, h) do { _Pragma("unroll") for (int n = 0; n < 2; ++n) _Pragma("unroll") for (int k = 0; k < 2; ++k) dst[n][k] = *(const LAS bf16x8*)(lds + PG8_SB(b, h) + boff + n * 2048 + k * 1024); } while (0)
; #define PG8_MMA(ai, bj, At, Bt) do { __builtin_amdgcn_s_setprio(1); _Pragma("unroll") for (int m = 0; m < 4; ++m) _Pragma("unroll") for (int n = 0; n < 2; ++n) _Pragma("unroll") for (int k = 0; k < 2; ++k) \
;         acc[ai][bj][m][n] = __builtin_amdgcn_mfma_f32_16x16x32_bf16(Bt[n][k], At[m][k], acc[ai][bj][m][n], 0, 0, 0); __builtin_amdgcn_s_setprio(0); } while (0)
; #define PG8_WAIT_L(n) asm volatile("s_waitcnt lgkmcnt(" #n ")" ::: "memory")
; #define PG8_BAR __builtin_amdgcn_s_barrier()
; #define PG8_SCHED __builtin_amdgcn_sched_barrier(0)
; template <class Epi>
; DI void gemm_phase(const int TID, const int BID, LAS unsigned char* lds, const Gemm g, const Epi& E) {
;     ...
;             const bool last = (t == nt - 2);
;             const char* a1 = cA + (size_t)(t + 1) * kstep;
;             const char* a2 = last ? nA : cA + (size_t)(t + 2) * kstep; const char* b2 = last ? nB : cB + (size_t)(t + 2) * kstep;
;             const char* a3 = a2 + kstep; const char* b3 = b2 + kstep;
;             PG8_LDB(B0, 0, 0); PG8_SCHED; PG8_LDA(At, 0, 0); PG8_STAGE(PG8_SA(1, 1), a1 + hstep);
;             PG8_WAIT_L(8); PG8_BAR; PG8_WAIT_L(0); PG8_MMA(0, 0, At, B0); PG8_BAR; PG8_SCHED;
;             PG8_LDB(B1, 0, 1); PG8_STAGE(PG8_SB(0, 0), b2);
;             PG8_BAR; PG8_WAIT_L(0); PG8_MMA(0, 1, At, B1); PG8_BAR;
;             PG8_LDA(At, 0, 1); PG8_STAGE(PG8_SA(0, 0), a2);
;             PG8_BAR; PG8_WAIT_L(0); PG8_MMA(1, 0, At, B0); PG8_BAR; PG8_SCHED;
;             PG8_STAGE(PG8_SB(0, 1), b2 + hstep);
.LBB0_746:
	v_add_u32_e32 v76, s65, v175
	ds_read_b128 v[64:67], v76
	ds_read_b128 v[68:71], v76 offset:1024
	ds_read_b128 v[72:75], v76 offset:2048
	ds_read_b128 v[76:79], v76 offset:3072
	s_add_i32 s24, s23, 2
	s_add_u32 s4, s2, 0x80
	s_addc_u32 s5, s3, 0
	s_cmp_eq_u32 s0, s23
	s_cselect_b32 s5, s55, s5
	s_cselect_b32 s4, s54, s4
	s_cselect_b32 s59, s57, s20
	s_cselect_b32 s58, s56, s19
	v_lshl_add_u64 v[170:171], s[2:3], 0, v[176:177]
	s_add_i32 m0, s84, 0xc000
	ds_read_b128 v[188:191], v187
	ds_read_b128 v[192:195], v187 offset:1024
	ds_read_b128 v[196:199], v187 offset:2048
	ds_read_b128 v[200:203], v187 offset:3072
	ds_read_b128 v[204:207], v187 offset:4096
	ds_read_b128 v[208:211], v187 offset:5120
	ds_read_b128 v[212:215], v187 offset:6144
	ds_read_b128 v[216:219], v187 offset:7168
	global_load_lds_dwordx4 v[170:171], off
	v_lshl_add_u64 v[170:171], s[2:3], 0, v[178:179]
	s_add_i32 m0, s84, 0xe000
	s_nop 0
	global_load_lds_dwordx4 v[170:171], off
	v_add_u32_e32 v168, s63, v175
	ds_read_b128 v[220:223], v168
	ds_read_b128 v[224:227], v168 offset:1024
	ds_read_b128 v[228:231], v168 offset:2048
	ds_read_b128 v[246:249], v168 offset:3072
	s_waitcnt vmcnt(8)
	s_waitcnt lgkmcnt(0)
	s_barrier
	s_setprio 1
	v_mfma_f32_16x16x32_bf16 v[140:143], v[64:67], v[188:191], v[140:143]
	v_mfma_f32_16x16x32_bf16 v[136:139], v[72:75], v[188:191], v[136:139]
	v_mfma_f32_16x16x32_bf16 v[124:127], v[64:67], v[196:199], v[124:127]
	v_mfma_f32_16x16x32_bf16 v[120:123], v[72:75], v[196:199], v[120:123]
	v_mfma_f32_16x16x32_bf16 v[108:111], v[64:67], v[204:207], v[108:111]
	v_mfma_f32_16x16x32_bf16 v[104:107], v[72:75], v[204:207], v[104:107]
	v_mfma_f32_16x16x32_bf16 v[92:95], v[64:67], v[212:215], v[92:95]
	v_mfma_f32_16x16x32_bf16 v[88:91], v[72:75], v[212:215], v[88:91]
	v_mfma_f32_16x16x32_bf16 v[140:143], v[68:71], v[192:195], v[140:143]
	v_mfma_f32_16x16x32_bf16 v[136:139], v[76:79], v[192:195], v[136:139]
	v_mfma_f32_16x16x32_bf16 v[124:127], v[68:71], v[200:203], v[124:127]
	v_mfma_f32_16x16x32_bf16 v[120:123], v[76:79], v[200:203], v[120:123]
	v_mfma_f32_16x16x32_bf16 v[108:111], v[68:71], v[208:211], v[108:111]
	v_mfma_f32_16x16x32_bf16 v[104:107], v[76:79], v[208:211], v[104:107]
	v_mfma_f32_16x16x32_bf16 v[92:95], v[68:71], v[216:219], v[92:95]
	v_mfma_f32_16x16x32_bf16 v[88:91], v[76:79], v[216:219], v[88:91]
	v_mfma_f32_16x16x32_bf16 v[132:135], v[220:223], v[188:191], v[132:135]
	v_mfma_f32_16x16x32_bf16 v[128:131], v[228:231], v[188:191], v[128:131]
	v_mfma_f32_16x16x32_bf16 v[116:119], v[220:223], v[196:199], v[116:119]
	v_mfma_f32_16x16x32_bf16 v[112:115], v[228:231], v[196:199], v[112:115]
	v_mfma_f32_16x16x32_bf16 v[100:103], v[220:223], v[204:207], v[100:103]
	v_mfma_f32_16x16x32_bf16 v[96:99], v[228:231], v[204:207], v[96:99]
	v_mfma_f32_16x16x32_bf16 v[84:87], v[220:223], v[212:215], v[84:87]
	v_mfma_f32_16x16x32_bf16 v[80:83], v[228:231], v[212:215], v[80:83]
	v_mfma_f32_16x16x32_bf16 v[132:135], v[224:227], v[192:195], v[132:135]
	v_mfma_f32_16x16x32_bf16 v[128:131], v[246:249], v[192:195], v[128:131]
	v_mfma_f32_16x16x32_bf16 v[116:119], v[224:227], v[200:203], v[116:119]
	v_mfma_f32_16x16x32_bf16 v[112:115], v[246:249], v[200:203], v[112:115]
	v_mfma_f32_16x16x32_bf16 v[100:103], v[224:227], v[208:211], v[100:103]
	v_mfma_f32_16x16x32_bf16 v[96:99], v[246:249], v[208:211], v[96:99]
	v_mfma_f32_16x16x32_bf16 v[84:87], v[224:227], v[216:219], v[84:87]
	v_mfma_f32_16x16x32_bf16 v[80:83], v[246:249], v[216:219], v[80:83]
	s_setprio 0
	s_barrier
	s_mov_b32 m0, s66
	v_lshl_add_u64 v[170:171], s[58:59], 0, v[144:145]
	global_load_lds_dwordx4 v[170:171], off
	v_lshl_add_u64 v[172:173], s[58:59], 0, v[146:147]
	s_mov_b32 m0, s67
	s_nop 0
	global_load_lds_dwordx4 v[172:173], off
	s_mov_b32 m0, s84
	v_lshl_add_u64 v[232:233], s[4:5], 0, v[144:145]
	ds_read_b128 v[188:191], v187 offset:16384
	ds_read_b128 v[192:195], v187 offset:17408
	ds_read_b128 v[196:199], v187 offset:18432
	ds_read_b128 v[200:203], v187 offset:19456
	ds_read_b128 v[204:207], v187 offset:20480
	ds_read_b128 v[208:211], v187 offset:21504
	ds_read_b128 v[212:215], v187 offset:22528
	ds_read_b128 v[216:219], v187 offset:23552
	global_load_lds_dwordx4 v[232:233], off
	v_lshl_add_u64 v[234:235], s[4:5], 0, v[146:147]
	s_mov_b32 m0, s62
	s_nop 0
	global_load_lds_dwordx4 v[234:235], off
	s_add_u32 s26, s58, s6
	s_addc_u32 s27, s59, s7
	s_mov_b32 m0, s64
	v_lshl_add_u64 v[236:237], s[26:27], 0, v[144:145]
	global_load_lds_dwordx4 v[236:237], off
	v_lshl_add_u64 v[238:239], s[26:27], 0, v[146:147]
	s_mov_b32 m0, s10
	s_nop 0
	global_load_lds_dwordx4 v[238:239], off
	s_waitcnt vmcnt(8)
	s_waitcnt lgkmcnt(0)
	s_barrier
; #define PG8_STAGE(bufoff, gbase) do { _Pragma("unroll") for (int _i = 0; _i < 2; ++_i) \
;         __builtin_amdgcn_global_load_lds((const unsigned*)((const char*)(gbase) + voffA[_i]), (LAS unsigned*)(lds + (bufoff) + ldsw + _i * 8192), 16, 0, 0); } while (0)
; #define PG8_LDA(dst, b, h) do { _Pragma("unroll") for (int m = 0; m < 4; ++m) _Pragma("unroll") for (int k = 0; k < 2; ++k) dst[m][k] = *(const LAS bf16x8*)(lds + PG8_SA(b, h) + aoff + m * 2048 + k * 1024); } while (0)
; #define PG8_LDB(dst, b, h) do { _Pragma("unroll") for (int n = 0; n < 2; ++n) _Pragma("unroll") for (int k = 0; k < 2; ++k) dst[n][k] = *(const LAS bf16x8*)(lds + PG8_SB(b, h) + boff + n * 2048 + k * 1024); } while (0)
; #define PG8_MMA(ai, bj, At, Bt) do { __builtin_amdgcn_s_setprio(1); _Pragma("unroll") for (int m = 0; m < 4; ++m) _Pragma("unroll") for (int n = 0; n < 2; ++n) _Pragma("unroll") for (int k = 0; k < 2; ++k) \
;         acc[ai][bj][m][n] = __builtin_amdgcn_mfma_f32_16x16x32_bf16(Bt[n][k], At[m][k], acc[ai][bj][m][n], 0, 0, 0); __builtin_amdgcn_s_setprio(0); } while (0)
; #define PG8_WAIT_V(n) asm volatile("s_waitcnt vmcnt(" #n ")" ::: "memory")
; #define PG8_WAIT_L(n) asm volatile("s_waitcnt lgkmcnt(" #n ")" ::: "memory")
; #define PG8_BAR __builtin_amdgcn_s_barrier()
; #define PG8_SCHED __builtin_amdgcn_sched_barrier(0)
; template <class Epi>
; DI void gemm_phase(const int TID, const int BID, LAS unsigned char* lds, const Gemm g, const Epi& E) {
;     ...
;             PG8_BAR; PG8_WAIT_L(0); PG8_MMA(0, 1, At, B1); PG8_BAR;
;             PG8_LDA(At, 0, 1); PG8_STAGE(PG8_SA(0, 0), a2);
;             PG8_BAR; PG8_WAIT_L(0); PG8_MMA(1, 0, At, B0); PG8_BAR; PG8_SCHED;
;             PG8_STAGE(PG8_SB(0, 1), b2 + hstep);
;             PG8_WAIT_V(6); PG8_BAR; PG8_MMA(1, 1, At, B1); PG8_BAR;
;             PG8_LDB(B0, 1, 0); PG8_SCHED; PG8_LDA(At, 1, 0); PG8_STAGE(PG8_SA(0, 1), a2 + hstep);
;             PG8_WAIT_L(8); PG8_BAR; PG8_WAIT_L(0); PG8_MMA(0, 0, At, B0); PG8_BAR; PG8_SCHED;
;             PG8_LDB(B1, 1, 1); PG8_STAGE(PG8_SB(1, 0), b3);
	s_setprio 1
	v_mfma_f32_16x16x32_bf16 v[60:63], v[64:67], v[188:191], v[60:63]
	v_mfma_f32_16x16x32_bf16 v[56:59], v[72:75], v[188:191], v[56:59]
	v_mfma_f32_16x16x32_bf16 v[44:47], v[64:67], v[196:199], v[44:47]
	v_mfma_f32_16x16x32_bf16 v[40:43], v[72:75], v[196:199], v[40:43]
	v_mfma_f32_16x16x32_bf16 v[28:31], v[64:67], v[204:207], v[28:31]
	v_mfma_f32_16x16x32_bf16 v[24:27], v[72:75], v[204:207], v[24:27]
	v_mfma_f32_16x16x32_bf16 v[12:15], v[64:67], v[212:215], v[12:15]
	v_mfma_f32_16x16x32_bf16 v[8:11], v[72:75], v[212:215], v[8:11]
	v_mfma_f32_16x16x32_bf16 v[60:63], v[68:71], v[192:195], v[60:63]
	v_mfma_f32_16x16x32_bf16 v[56:59], v[76:79], v[192:195], v[56:59]
	v_mfma_f32_16x16x32_bf16 v[44:47], v[68:71], v[200:203], v[44:47]
	v_mfma_f32_16x16x32_bf16 v[40:43], v[76:79], v[200:203], v[40:43]
	v_mfma_f32_16x16x32_bf16 v[28:31], v[68:71], v[208:211], v[28:31]
	v_mfma_f32_16x16x32_bf16 v[24:27], v[76:79], v[208:211], v[24:27]
	v_mfma_f32_16x16x32_bf16 v[12:15], v[68:71], v[216:219], v[12:15]
	v_mfma_f32_16x16x32_bf16 v[8:11], v[76:79], v[216:219], v[8:11]
	v_mfma_f32_16x16x32_bf16 v[52:55], v[220:223], v[188:191], v[52:55]
	v_mfma_f32_16x16x32_bf16 v[48:51], v[228:231], v[188:191], v[48:51]
	v_mfma_f32_16x16x32_bf16 v[36:39], v[220:223], v[196:199], v[36:39]
	v_mfma_f32_16x16x32_bf16 v[32:35], v[228:231], v[196:199], v[32:35]
	v_mfma_f32_16x16x32_bf16 v[20:23], v[220:223], v[204:207], v[20:23]
	v_mfma_f32_16x16x32_bf16 v[16:19], v[228:231], v[204:207], v[16:19]
	v_mfma_f32_16x16x32_bf16 v[0:3], v[220:223], v[212:215], v[0:3]
	v_mfma_f32_16x16x32_bf16 v[4:7], v[228:231], v[212:215], v[4:7]
	v_mfma_f32_16x16x32_bf16 v[52:55], v[224:227], v[192:195], v[52:55]
	v_mfma_f32_16x16x32_bf16 v[48:51], v[246:249], v[192:195], v[48:51]
	v_mfma_f32_16x16x32_bf16 v[36:39], v[224:227], v[200:203], v[36:39]
	v_mfma_f32_16x16x32_bf16 v[32:35], v[246:249], v[200:203], v[32:35]
	v_mfma_f32_16x16x32_bf16 v[20:23], v[224:227], v[208:211], v[20:23]
	v_mfma_f32_16x16x32_bf16 v[16:19], v[246:249], v[208:211], v[16:19]
	v_mfma_f32_16x16x32_bf16 v[0:3], v[224:227], v[216:219], v[0:3]
	v_mfma_f32_16x16x32_bf16 v[4:7], v[246:249], v[216:219], v[4:7]
	s_setprio 0
	s_barrier
	v_add_u32_e32 v76, s13, v175
	ds_read_b128 v[64:67], v76
	ds_read_b128 v[68:71], v76 offset:1024
	ds_read_b128 v[72:75], v76 offset:2048
	ds_read_b128 v[76:79], v76 offset:3072
	s_add_u32 s4, s4, s6
	s_addc_u32 s5, s5, s7
	s_mov_b32 m0, s11
	v_lshl_add_u64 v[220:221], s[4:5], 0, v[144:145]
	ds_read_b128 v[188:191], v187 offset:32768
	ds_read_b128 v[192:195], v187 offset:33792
	ds_read_b128 v[196:199], v187 offset:34816
	ds_read_b128 v[200:203], v187 offset:35840
	ds_read_b128 v[204:207], v187 offset:36864
	ds_read_b128 v[208:211], v187 offset:37888
	ds_read_b128 v[212:215], v187 offset:38912
	ds_read_b128 v[216:219], v187 offset:39936
	global_load_lds_dwordx4 v[220:221], off
	v_lshl_add_u64 v[220:221], s[4:5], 0, v[146:147]
	s_mov_b32 m0, s12
	s_nop 0
	global_load_lds_dwordx4 v[220:221], off
	v_add_u32_e32 v168, s80, v175
	ds_read_b128 v[220:223], v168
	ds_read_b128 v[224:227], v168 offset:1024
	ds_read_b128 v[228:231], v168 offset:2048
	ds_read_b128 v[246:249], v168 offset:3072
	s_waitcnt vmcnt(8)
	s_waitcnt lgkmcnt(0)
	s_barrier
	s_setprio 1
	v_mfma_f32_16x16x32_bf16 v[140:143], v[64:67], v[188:191], v[140:143]
	v_mfma_f32_16x16x32_bf16 v[136:139], v[72:75], v[188:191], v[136:139]
	v_mfma_f32_16x16x32_bf16 v[124:127], v[64:67], v[196:199], v[124:127]
	v_mfma_f32_16x16x32_bf16 v[120:123], v[72:75], v[196:199], v[120:123]
	v_mfma_f32_16x16x32_bf16 v[108:111], v[64:67], v[204:207], v[108:111]
	v_mfma_f32_16x16x32_bf16 v[104:107], v[72:75], v[204:207], v[104:107]
	v_mfma_f32_16x16x32_bf16 v[92:95], v[64:67], v[212:215], v[92:95]
	v_mfma_f32_16x16x32_bf16 v[88:91], v[72:75], v[212:215], v[88:91]
	v_mfma_f32_16x16x32_bf16 v[140:143], v[68:71], v[192:195], v[140:143]
	v_mfma_f32_16x16x32_bf16 v[136:139], v[76:79], v[192:195], v[136:139]
	v_mfma_f32_16x16x32_bf16 v[124:127], v[68:71], v[200:203], v[124:127]
	v_mfma_f32_16x16x32_bf16 v[120:123], v[76:79], v[200:203], v[120:123]
	v_mfma_f32_16x16x32_bf16 v[108:111], v[68:71], v[208:211], v[108:111]
	v_mfma_f32_16x16x32_bf16 v[104:107], v[76:79], v[208:211], v[104:107]
	v_mfma_f32_16x16x32_bf16 v[92:95], v[68:71], v[216:219], v[92:95]
	v_mfma_f32_16x16x32_bf16 v[88:91], v[76:79], v[216:219], v[88:91]
	v_mfma_f32_16x16x32_bf16 v[132:135], v[220:223], v[188:191], v[132:135]
	v_mfma_f32_16x16x32_bf16 v[128:131], v[228:231], v[188:191], v[128:131]
	v_mfma_f32_16x16x32_bf16 v[116:119], v[220:223], v[196:199], v[116:119]
	v_mfma_f32_16x16x32_bf16 v[112:115], v[228:231], v[196:199], v[112:115]
	v_mfma_f32_16x16x32_bf16 v[100:103], v[220:223], v[204:207], v[100:103]
	v_mfma_f32_16x16x32_bf16 v[96:99], v[228:231], v[204:207], v[96:99]
	v_mfma_f32_16x16x32_bf16 v[84:87], v[220:223], v[212:215], v[84:87]
	v_mfma_f32_16x16x32_bf16 v[80:83], v[228:231], v[212:215], v[80:83]
	v_mfma_f32_16x16x32_bf16 v[132:135], v[224:227], v[192:195], v[132:135]
	v_mfma_f32_16x16x32_bf16 v[128:131], v[246:249], v[192:195], v[128:131]
	v_mfma_f32_16x16x32_bf16 v[116:119], v[224:227], v[200:203], v[116:119]
	v_mfma_f32_16x16x32_bf16 v[112:115], v[246:249], v[200:203], v[112:115]
	v_mfma_f32_16x16x32_bf16 v[100:103], v[224:227], v[208:211], v[100:103]
	v_mfma_f32_16x16x32_bf16 v[96:99], v[246:249], v[208:211], v[96:99]
	v_mfma_f32_16x16x32_bf16 v[84:87], v[224:227], v[216:219], v[84:87]
	v_mfma_f32_16x16x32_bf16 v[80:83], v[246:249], v[216:219], v[80:83]
	s_setprio 0
	s_barrier
; #define PG8_STAGE(bufoff, gbase) do { _Pragma("unroll") for (int _i = 0; _i < 2; ++_i) \
;         __builtin_amdgcn_global_load_lds((const unsigned*)((const char*)(gbase) + voffA[_i]), (LAS unsigned*)(lds + (bufoff) + ldsw + _i * 8192), 16, 0, 0); } while (0)
; #define PG8_LDA(dst, b, h) do { _Pragma("unroll") for (int m = 0; m < 4; ++m) _Pragma("unroll") for (int k = 0; k < 2; ++k) dst[m][k] = *(const LAS bf16x8*)(lds + PG8_SA(b, h) + aoff + m * 2048 + k * 1024); } while (0)
; #define PG8_LDB(dst, b, h) do { _Pragma("unroll") for (int n = 0; n < 2; ++n) _Pragma("unroll") for (int k = 0; k < 2; ++k) dst[n][k] = *(const LAS bf16x8*)(lds + PG8_SB(b, h) + boff + n * 2048 + k * 1024); } while (0)
; #define PG8_MMA(ai, bj, At, Bt) do { __builtin_amdgcn_s_setprio(1); _Pragma("unroll") for (int m = 0; m < 4; ++m) _Pragma("unroll") for (int n = 0; n < 2; ++n) _Pragma("unroll") for (int k = 0; k < 2; ++k) \
;         acc[ai][bj][m][n] = __builtin_amdgcn_mfma_f32_16x16x32_bf16(Bt[n][k], At[m][k], acc[ai][bj][m][n], 0, 0, 0); __builtin_amdgcn_s_setprio(0); } while (0)
; #define PG8_WAIT_V(n) asm volatile("s_waitcnt vmcnt(" #n ")" ::: "memory")
; #define PG8_WAIT_L(n) asm volatile("s_waitcnt lgkmcnt(" #n ")" ::: "memory")
; #define PG8_BAR __builtin_amdgcn_s_barrier()
; #define PG8_SCHED __builtin_amdgcn_sched_barrier(0)
; template <class Epi>
; DI void gemm_phase(const int TID, const int BID, LAS unsigned char* lds, const Gemm g, const Epi& E) {
;     ...
;             PG8_LDB(B1, 1, 1); PG8_STAGE(PG8_SB(1, 0), b3);
;             PG8_BAR; PG8_WAIT_L(0); PG8_MMA(0, 1, At, B1); PG8_BAR;
;             PG8_LDA(At, 1, 1); PG8_STAGE(PG8_SA(1, 0), a3);
;             PG8_BAR; PG8_WAIT_L(0); PG8_MMA(1, 0, At, B0); PG8_BAR; PG8_SCHED;
;             PG8_STAGE(PG8_SB(1, 1), b3 + hstep);
;             PG8_WAIT_V(6); PG8_BAR; PG8_MMA(1, 1, At, B1); PG8_BAR;
;         }
	s_mov_b32 m0, s76
	v_lshl_add_u64 v[170:171], v[170:171], 0, s[92:93]
	global_load_lds_dwordx4 v[170:171], off
	v_lshl_add_u64 v[170:171], v[172:173], 0, s[92:93]
	s_mov_b32 m0, s77
	s_nop 0
	global_load_lds_dwordx4 v[170:171], off
	s_mov_b32 m0, s33
	v_lshl_add_u64 v[170:171], v[232:233], 0, s[92:93]
	ds_read_b128 v[188:191], v187 offset:49152
	ds_read_b128 v[192:195], v187 offset:50176
	ds_read_b128 v[196:199], v187 offset:51200
	ds_read_b128 v[200:203], v187 offset:52224
	ds_read_b128 v[204:207], v187 offset:53248
	ds_read_b128 v[208:211], v187 offset:54272
	ds_read_b128 v[212:215], v187 offset:55296
	ds_read_b128 v[216:219], v187 offset:56320
	global_load_lds_dwordx4 v[170:171], off
	v_lshl_add_u64 v[170:171], v[234:235], 0, s[92:93]
	s_mov_b32 m0, s15
	s_nop 0
	global_load_lds_dwordx4 v[170:171], off
	s_mov_b32 m0, s81
	v_lshl_add_u64 v[170:171], v[236:237], 0, s[92:93]
	global_load_lds_dwordx4 v[170:171], off
	v_lshl_add_u64 v[170:171], v[238:239], 0, s[92:93]
	s_mov_b32 m0, s8
	s_nop 0
	global_load_lds_dwordx4 v[170:171], off
	s_waitcnt vmcnt(8)
	s_waitcnt lgkmcnt(0)
	s_barrier
	s_setprio 1
	v_mfma_f32_16x16x32_bf16 v[60:63], v[64:67], v[188:191], v[60:63]
	v_mfma_f32_16x16x32_bf16 v[56:59], v[72:75], v[188:191], v[56:59]
	v_mfma_f32_16x16x32_bf16 v[44:47], v[64:67], v[196:199], v[44:47]
	v_mfma_f32_16x16x32_bf16 v[40:43], v[72:75], v[196:199], v[40:43]
	v_mfma_f32_16x16x32_bf16 v[28:31], v[64:67], v[204:207], v[28:31]
	v_mfma_f32_16x16x32_bf16 v[24:27], v[72:75], v[204:207], v[24:27]
	v_mfma_f32_16x16x32_bf16 v[12:15], v[64:67], v[212:215], v[12:15]
	v_mfma_f32_16x16x32_bf16 v[8:11], v[72:75], v[212:215], v[8:11]
	v_mfma_f32_16x16x32_bf16 v[60:63], v[68:71], v[192:195], v[60:63]
	v_mfma_f32_16x16x32_bf16 v[56:59], v[76:79], v[192:195], v[56:59]
	v_mfma_f32_16x16x32_bf16 v[44:47], v[68:71], v[200:203], v[44:47]
	v_mfma_f32_16x16x32_bf16 v[40:43], v[76:79], v[200:203], v[40:43]
	v_mfma_f32_16x16x32_bf16 v[28:31], v[68:71], v[208:211], v[28:31]
	v_mfma_f32_16x16x32_bf16 v[24:27], v[76:79], v[208:211], v[24:27]
	v_mfma_f32_16x16x32_bf16 v[12:15], v[68:71], v[216:219], v[12:15]
	v_mfma_f32_16x16x32_bf16 v[8:11], v[76:79], v[216:219], v[8:11]
	v_mfma_f32_16x16x32_bf16 v[52:55], v[220:223], v[188:191], v[52:55]
	v_mfma_f32_16x16x32_bf16 v[48:51], v[228:231], v[188:191], v[48:51]
	v_mfma_f32_16x16x32_bf16 v[36:39], v[220:223], v[196:199], v[36:39]
	v_mfma_f32_16x16x32_bf16 v[32:35], v[228:231], v[196:199], v[32:35]
	v_mfma_f32_16x16x32_bf16 v[20:23], v[220:223], v[204:207], v[20:23]
	v_mfma_f32_16x16x32_bf16 v[16:19], v[228:231], v[204:207], v[16:19]
	v_mfma_f32_16x16x32_bf16 v[0:3], v[220:223], v[212:215], v[0:3]
	v_mfma_f32_16x16x32_bf16 v[4:7], v[228:231], v[212:215], v[4:7]
	v_mfma_f32_16x16x32_bf16 v[52:55], v[224:227], v[192:195], v[52:55]
	v_mfma_f32_16x16x32_bf16 v[48:51], v[246:249], v[192:195], v[48:51]
	v_mfma_f32_16x16x32_bf16 v[36:39], v[224:227], v[200:203], v[36:39]
	v_mfma_f32_16x16x32_bf16 v[32:35], v[246:249], v[200:203], v[32:35]
	v_mfma_f32_16x16x32_bf16 v[20:23], v[224:227], v[208:211], v[20:23]
	v_mfma_f32_16x16x32_bf16 v[16:19], v[246:249], v[208:211], v[16:19]
	v_mfma_f32_16x16x32_bf16 v[0:3], v[224:227], v[216:219], v[0:3]
	v_mfma_f32_16x16x32_bf16 v[4:7], v[246:249], v[216:219], v[4:7]
	s_setprio 0
	s_add_u32 s2, s2, 0x100
	s_addc_u32 s3, s3, 0
	s_add_u32 s19, s19, 0x100
	s_addc_u32 s20, s20, 0
	s_cmp_ge_i32 s24, s9
	s_mov_b32 s23, s24
	s_barrier
	s_cbranch_scc0 .LBB0_746
	v_readlane_b32 s26, v255, 16
	v_readlane_b32 s27, v255, 17
